# rsqrt rescale removal extended to in-place form (104 sites); padded two-op DPP steps
# baseline (speedup 1.0000x reference)
; DI void run_phase(const Params& p, int ph, unsigned char* smem, const int tid, const int rep) {
;     ...
;         { const float* g1 = PIN(12) + l * 192; const float* g2 = PIN(13) + l * 192; const float* g3 = PIN(17) + l * 128; const float* g4 = PIN(18) + l * 128;
;           float a1 = fmaxf(fmaxf(fabsf(g1[lane]), fabsf(g1[lane + 64])), fabsf(g1[lane + 128])), a2 = fmaxf(fmaxf(fabsf(g2[lane]), fabsf(g2[lane + 64])), fabsf(g2[lane + 128]));
;           float a3 = fmaxf(fabsf(g3[lane]), fabsf(g3[lane + 64])), a4 = fmaxf(fabsf(g4[lane]), fabsf(g4[lane + 64]));
;           for (int o = 32; o; o >>= 1) { a1 = fmaxf(a1, __shfl_xor(a1, o)); a2 = fmaxf(a2, __shfl_xor(a2, o)); a3 = fmaxf(a3, __shfl_xor(a3, o)); a4 = fmaxf(a4, __shfl_xor(a4, o)); }
;           if (tid == 0) { float* mp = (float*)(smem + LDS_BYTES - 48); mp[0] = a1 * a2 * 13.856406460551018f * LOG2E; mp[1] = a3 * a4 * 11.313708498984761f * LOG2E; } }
.LBB0_203:
	s_andn2_b64 vcc, exec, s[0:1]
	s_cbranch_vccnz .LBB0_325
	v_readlane_b32 s0, v255, 3
	s_mov_b32 s4, s0
	s_mul_i32 s14, s4, 0xc0
	v_readlane_b32 s1, v255, 4
	s_lshl_b32 s0, s0, 7
	s_ashr_i32 s15, s14, 31
	v_readlane_b32 s40, v254, 35
	s_ashr_i32 s1, s0, 31
	s_lshl_b64 s[14:15], s[14:15], 2
	v_readlane_b32 s48, v254, 43
	v_readlane_b32 s49, v254, 44
	s_add_u32 s24, s48, s14
	v_readlane_b32 s50, v254, 45
	s_addc_u32 s25, s49, s15
	v_readlane_b32 s41, v254, 36
	v_readlane_b32 s42, v254, 37
	v_readlane_b32 s43, v254, 38
	v_readlane_b32 s44, v254, 39
	v_readlane_b32 s45, v254, 40
	v_readlane_b32 s46, v254, 41
	v_readlane_b32 s47, v254, 42
	v_readlane_b32 s51, v254, 46
	v_readlane_b32 s52, v254, 47
	v_readlane_b32 s53, v254, 48
	v_readlane_b32 s54, v254, 49
	v_readlane_b32 s55, v254, 50
	s_add_u32 s14, s50, s14
	s_addc_u32 s15, s51, s15
	v_readlane_b32 s40, v254, 51
	s_lshl_b64 s[0:1], s[0:1], 2
	v_readlane_b32 s42, v254, 53
	v_readlane_b32 s43, v254, 54
	s_add_u32 s34, s42, s0
	v_readlane_b32 s44, v254, 55
	s_addc_u32 s35, s43, s1
	v_lshlrev_b32_e32 v0, 2, v194
	v_readlane_b32 s45, v254, 56
	global_load_dword v2, v0, s[24:25]
	global_load_dword v3, v0, s[24:25] offset:256
	global_load_dword v4, v0, s[24:25] offset:512
	global_load_dword v5, v0, s[14:15]
	global_load_dword v6, v0, s[14:15] offset:256
	global_load_dword v7, v0, s[14:15] offset:512
	global_load_dword v8, v0, s[34:35]
	global_load_dword v9, v0, s[34:35] offset:256
	s_add_u32 s14, s44, s0
	s_addc_u32 s15, s45, s1
	global_load_dword v10, v0, s[14:15] offset:256
	s_nop 0
	global_load_dword v0, v0, s[14:15]
	v_and_b32_e32 v11, 64, v218
	v_xor_b32_e32 v12, 32, v218
	v_add_u32_e32 v11, 64, v11
	v_cmp_lt_i32_e32 vcc, v12, v11
	v_xor_b32_e32 v13, 16, v218
	v_xor_b32_e32 v14, 8, v218
	v_cndmask_b32_e32 v12, v218, v12, vcc
	v_lshlrev_b32_e32 v191, 2, v12
	v_cmp_lt_i32_e32 vcc, v13, v11
	v_xor_b32_e32 v15, 4, v218
	v_xor_b32_e32 v16, 2, v218
	v_cndmask_b32_e32 v13, v218, v13, vcc
	v_lshlrev_b32_e32 v227, 2, v13
	v_cmp_lt_i32_e32 vcc, v14, v11
	v_xor_b32_e32 v17, 1, v218
	v_cmp_eq_u32_e64 s[38:39], 0, v225
	v_cndmask_b32_e32 v14, v218, v14, vcc
	v_lshlrev_b32_e32 v228, 2, v14
	v_cmp_lt_i32_e32 vcc, v15, v11
	v_readlane_b32 s41, v254, 52
	v_readlane_b32 s46, v254, 57
	v_cndmask_b32_e32 v15, v218, v15, vcc
	v_lshlrev_b32_e32 v229, 2, v15
	v_cmp_lt_i32_e32 vcc, v16, v11
	v_readlane_b32 s47, v254, 58
	v_readlane_b32 s48, v254, 59
	v_cndmask_b32_e32 v16, v218, v16, vcc
	v_lshlrev_b32_e32 v230, 2, v16
	v_cmp_lt_i32_e32 vcc, v17, v11
	v_readlane_b32 s49, v254, 60
	v_readlane_b32 s50, v254, 61
	v_cndmask_b32_e32 v11, v218, v17, vcc
	v_lshlrev_b32_e32 v231, 2, v11
	v_readlane_b32 s51, v254, 62
	v_readlane_b32 s52, v254, 63
	v_readlane_b32 s53, v255, 0
	v_readlane_b32 s54, v255, 1
	v_readlane_b32 s55, v255, 2
	s_waitcnt vmcnt(0)
	v_max3_f32 v2, |v2|, |v3|, |v4|
	v_mov_b32_e32 v3, v2
	s_nop 1
	v_permlane32_swap_b32_e32 v3, v2
	v_max3_f32 v4, |v5|, |v6|, |v7|
	ds_bpermute_b32 v5, v191, v4
	v_max_f32_e64 v6, |v9|, |v9|
	v_max_f32_e64 v7, |v8|, |v8|
	v_max_f32_e32 v6, v7, v6
	v_max_f32_e64 v7, |v10|, |v10|
	v_max_f32_e64 v0, |v0|, |v0|
	s_waitcnt lgkmcnt(1)
	v_max_f32_e32 v3, v3, v3
	v_mov_b32_e32 v8, v6
	s_nop 1
	v_permlane32_swap_b32_e32 v8, v6
	v_max_f32_e32 v0, v0, v7
	v_max_f32_e32 v2, v2, v3
	s_waitcnt lgkmcnt(1)
	v_max_f32_e32 v3, v5, v5
	v_mov_b32_e32 v5, v0
	s_nop 1
	v_permlane32_swap_b32_e32 v5, v0
	v_mov_b32_e32 v7, v2
	s_nop 1
	v_permlane16_swap_b32_e32 v7, v2
	s_waitcnt lgkmcnt(2)
	v_max_f32_e32 v8, v8, v8
	v_max_f32_e32 v6, v6, v8
	v_max_f32_e32 v3, v4, v3
	s_waitcnt lgkmcnt(1)
	v_max_f32_e32 v5, v5, v5
	s_waitcnt lgkmcnt(0)
	v_max_f32_e32 v7, v7, v7
	v_mov_b32_e32 v8, v6
	s_nop 1
	v_permlane16_swap_b32_e32 v8, v6
	v_max_f32_e32 v0, v0, v5
	v_mov_b32_e32 v4, v3
	s_nop 1
	v_permlane16_swap_b32_e32 v4, v3
	v_max_f32_e32 v2, v2, v7
	v_mov_b32_e32 v5, v0
	s_nop 1
	v_permlane16_swap_b32_e32 v5, v0
	s_nop 1
	v_mov_b32_dpp v7, v2 row_ror:8 row_mask:0xf bank_mask:0xf
	s_waitcnt lgkmcnt(3)
	v_max_f32_e32 v8, v8, v8
	s_waitcnt lgkmcnt(2)
	v_max_f32_e32 v4, v4, v4
	v_max_f32_e32 v6, v6, v8
	s_waitcnt lgkmcnt(1)
	v_max_f32_e32 v5, v5, v5
	v_max_f32_e32 v3, v3, v4
	s_waitcnt lgkmcnt(0)
	v_max_f32_e32 v7, v7, v7
	s_nop 1
	v_mov_b32_dpp v8, v6 row_ror:8 row_mask:0xf bank_mask:0xf
	v_max_f32_e32 v0, v0, v5
	s_nop 1
	v_mov_b32_dpp v4, v3 row_ror:8 row_mask:0xf bank_mask:0xf
	v_max_f32_e32 v2, v2, v7
	s_nop 1
	v_mov_b32_dpp v5, v0 row_ror:8 row_mask:0xf bank_mask:0xf
	s_nop 1
	v_mov_b32_dpp v7, v2 row_shl:4 row_mask:0xf bank_mask:0x5
	s_nop 1
	v_mov_b32_dpp v7, v2 row_shr:4 row_mask:0xf bank_mask:0xa
	s_waitcnt lgkmcnt(3)
	v_max_f32_e32 v8, v8, v8
	s_waitcnt lgkmcnt(2)
	v_max_f32_e32 v4, v4, v4
	v_max_f32_e32 v6, v6, v8
	s_waitcnt lgkmcnt(1)
	v_max_f32_e32 v5, v5, v5
	v_max_f32_e32 v3, v3, v4
	s_waitcnt lgkmcnt(0)
	v_max_f32_e32 v7, v7, v7
	s_nop 1
	v_mov_b32_dpp v8, v6 row_shl:4 row_mask:0xf bank_mask:0x5
	s_nop 1
	v_mov_b32_dpp v8, v6 row_shr:4 row_mask:0xf bank_mask:0xa
	v_max_f32_e32 v0, v0, v5
	s_nop 1
	v_mov_b32_dpp v4, v3 row_shl:4 row_mask:0xf bank_mask:0x5
	s_nop 1
	v_mov_b32_dpp v4, v3 row_shr:4 row_mask:0xf bank_mask:0xa
	v_max_f32_e32 v2, v2, v7
	s_nop 1
	v_mov_b32_dpp v5, v0 row_shl:4 row_mask:0xf bank_mask:0x5
	s_nop 1
	v_mov_b32_dpp v5, v0 row_shr:4 row_mask:0xf bank_mask:0xa
	s_nop 1
	v_mov_b32_dpp v7, v2 quad_perm:[2,3,0,1] row_mask:0xf bank_mask:0xf
	s_waitcnt lgkmcnt(3)
	v_max_f32_e32 v8, v8, v8
	s_waitcnt lgkmcnt(2)
	v_max_f32_e32 v4, v4, v4
	v_max_f32_e32 v6, v6, v8
	s_waitcnt lgkmcnt(1)
	v_max_f32_e32 v5, v5, v5
	v_max_f32_e32 v3, v3, v4
	s_waitcnt lgkmcnt(0)
	v_max_f32_e32 v7, v7, v7
	s_nop 1
	v_mov_b32_dpp v8, v6 quad_perm:[2,3,0,1] row_mask:0xf bank_mask:0xf
	v_max_f32_e32 v9, v0, v5
	s_nop 1
	v_mov_b32_dpp v4, v3 quad_perm:[2,3,0,1] row_mask:0xf bank_mask:0xf
	v_max_f32_e32 v0, v2, v7
	s_nop 1
	v_mov_b32_dpp v7, v9 quad_perm:[2,3,0,1] row_mask:0xf bank_mask:0xf
	s_waitcnt lgkmcnt(2)
	v_max_f32_e32 v5, v8, v8
	v_max_f32_e32 v5, v6, v5
	s_waitcnt lgkmcnt(1)
	v_max_f32_e32 v4, v4, v4
	v_max_f32_e32 v3, v3, v4
	s_waitcnt lgkmcnt(0)
	v_max_f32_e32 v6, v7, v7
	v_max_f32_e32 v7, v9, v6
	s_nop 1
	v_mov_b32_dpp v2, v0 quad_perm:[1,0,3,2] row_mask:0xf bank_mask:0xf
	v_mov_b32_dpp v4, v3 quad_perm:[1,0,3,2] row_mask:0xf bank_mask:0xf
	s_nop 1
	v_mov_b32_dpp v6, v5 quad_perm:[1,0,3,2] row_mask:0xf bank_mask:0xf
	v_mov_b32_dpp v8, v7 quad_perm:[1,0,3,2] row_mask:0xf bank_mask:0xf
	s_and_saveexec_b64 s[14:15], s[38:39]
	s_cbranch_execz .LBB0_206
; DI void run_phase(const Params& p, int ph, unsigned char* smem, const int tid, const int rep) {
;     ...
;           for (int o = 32; o; o >>= 1) { a1 = fmaxf(a1, __shfl_xor(a1, o)); a2 = fmaxf(a2, __shfl_xor(a2, o)); a3 = fmaxf(a3, __shfl_xor(a3, o)); a4 = fmaxf(a4, __shfl_xor(a4, o)); }
;           if (tid == 0) { float* mp = (float*)(smem + LDS_BYTES - 48); mp[0] = a1 * a2 * 13.856406460551018f * LOG2E; mp[1] = a3 * a4 * 11.313708498984761f * LOG2E; } }
;         if (tid == 0) s_item[1] = 0;
	s_waitcnt lgkmcnt(0)
	v_max_f32_e32 v8, v8, v8
	v_max_f32_e32 v7, v7, v7
	v_max_f32_e32 v6, v6, v6
	v_max_f32_e32 v5, v5, v5
	v_max_f32_e32 v4, v4, v4
	v_max_f32_e32 v3, v3, v3
	v_max_f32_e32 v2, v2, v2
	v_max_f32_e32 v0, v0, v0
	v_max_f32_e32 v7, v7, v8
	v_max_f32_e32 v5, v5, v6
	v_max_f32_e32 v6, v3, v4
	v_max_f32_e32 v4, v0, v2
	s_mov_b32 s24, 0x415db3d7
	v_pk_mul_f32 v[2:3], v[4:5], v[6:7]
	s_mov_b32 s25, 0x413504f3
	v_pk_mul_f32 v[2:3], v[2:3], s[24:25]
	s_mov_b32 s4, 0x3fb8aa3b
	v_pk_mul_f32 v[2:3], v[2:3], s[4:5] op_sel_hi:[1,0]
	v_readlane_b32 s4, v254, 4
	s_nop 1
	v_mov_b32_e32 v0, s4
	v_readlane_b32 s4, v254, 5
	ds_write_b64 v0, v[2:3]
	s_nop 0
	v_mov_b32_e32 v0, s4
	ds_write_b32 v0, v1

; DI float bf2f(bf16_t b) { return __uint_as_float(((unsigned)b) << 16); }
; DI void sg_item(int item, const bf16_t* proj, const bf16_t* sgw, const float* vng, const float* bs, bf16_t* obuf, unsigned char* smem, const int tid) {
;     ...
;     const int g = item & 3, n = (item >> 2) & 31, b = item >> 7;
;     const int t0 = b * SEQ + n * 128;
;     bf16_t* vT = (bf16_t*)smem;
;     const int tb = wv >> 1;
;     const bf16_t* W = sgw + (size_t)g * 16384;
;     bf16x8 wf[8];
; #pragma unroll
;     for (int ks = 0; ks < 8; ++ks) wf[ks] = *(const bf16x8*)(W + (32 * tb + r) * 128 + 16 * ks + 8 * h2);
;     float va[16][2];
; #pragma unroll
;     for (int e = 0; e < 16; ++e) { const bf16_t* vr = proj + (size_t)(t0 + wv * 16 + e) * PLD + 3008 + g * 128; va[e][0] = bf2f(vr[lane]); va[e][1] = bf2f(vr[lane + 64]); }
;     const float g0 = vng[g * 128 + lane], g1 = vng[g * 128 + lane + 64];
; DI void run_phase(const Params& p, int ph, unsigned char* smem, const int tid, const int rep) {
;     ...
;             const int v = *s_item;
;             if (v < 0) break;
;             const int xq = v >> 16, li = v & 0xffff;
;             int tq = tid; asm volatile("" : "+v"(tq));
;             if (li < 4) dn_scan_item(xq * 4 + li, da, smem, tq);
;             else if (li < 4 + 128) { const int idx = li - 4, qt = 15 - (idx >> 3), rr = xq * 8 + (idx & 7), type = rr & 1, bh = rr >> 1, b = bh >> 2, h = bh & 3;
;                 if (type == 0) attn_item<192, false>(mlaq + (size_t)b * SEQ * 768 + h * 192, 768, mlak + (size_t)b * SEQ * 768 + h * 192, 768, mlavt + (size_t)bh * 128 * SEQ, nullptr,
;                                                      obuf + (size_t)b * SEQ * 2048 + 512 + h * 128, 2048, qt, ((const float*)(smem + LDS_BYTES - 48))[0], smem, tq, rep);
;                 else attn_item<128, true>(proj + (size_t)b * SEQ * PLD + 3520 + h * 128, PLD, proj + (size_t)b * SEQ * PLD + 3520 + 512 + h * 128, PLD, foxvt + (size_t)bh * 128 * SEQ, foxcum + (size_t)bh * SEQ,
;                                           obuf + (size_t)b * SEQ * 2048 + 1536 + h * 128, 2048, qt, ((const float*)(smem + LDS_BYTES - 48))[1], smem, tq, rep); }
;             else sg_item(xq * 128 + (li - 132), proj, sgw, PIN(14) + l * 512, PIN(16) + l * 512, obuf, smem, tq);
.LBB0_222:
	s_or_b64 exec, exec, s[0:1]
	v_readlane_b32 s0, v254, 6
	s_waitcnt lgkmcnt(0)
	s_barrier
	v_mov_b32_e32 v0, s0
	ds_read_b32 v0, v0
	s_waitcnt lgkmcnt(0)
	v_cmp_gt_i32_e32 vcc, 0, v0
	v_readfirstlane_b32 s24, v0
	s_cbranch_vccnz .LBB0_265
	s_lshr_b32 s52, s24, 16
	s_and_b32 s54, s24, 0xffff
	v_mov_b32_e32 v196, v225
	s_cmp_gt_u32 s54, 3
	s_mov_b64 s[0:1], -1
	s_cbranch_scc0 .LBB0_304
	v_bfe_u32 v180, v196, 5, 1
	s_cmpk_gt_u32 s54, 0x83
	v_lshlrev_b32_e32 v198, 4, v180
	s_cbranch_scc0 .LBB0_244
	s_lshl_b32 s0, s52, 7
	s_add_i32 s14, s54, s0
	s_addk_i32 s14, 0xff7c
	s_and_b32 s4, s24, 3
	v_lshlrev_b32_e32 v0, 7, v196
	s_lshl_b32 s12, s14, 5
	v_ashrrev_i32_e32 v62, 7, v196
	s_lshl_b32 s0, s4, 15
	v_and_b32_e32 v0, 0xf80, v0
	s_add_u32 s0, s26, s0
	v_lshl_or_b32 v2, v62, 12, v0
	s_addc_u32 s1, s27, 0
	v_ashrrev_i32_e32 v3, 31, v2
	v_lshl_add_u64 v[2:3], v[2:3], 1, s[0:1]
	v_mov_b32_e32 v199, v1
	v_ashrrev_i32_e32 v5, 2, v196
	v_lshl_add_u64 v[2:3], v[2:3], 0, v[198:199]
	s_and_b32 s25, s12, 0xfffff80
	v_and_b32_e32 v96, -16, v5
	global_load_dwordx4 v[46:49], v[2:3], off
	global_load_dwordx4 v[42:45], v[2:3], off offset:32
	global_load_dwordx4 v[38:41], v[2:3], off offset:64
	global_load_dwordx4 v[34:37], v[2:3], off offset:96
	global_load_dwordx4 v[30:33], v[2:3], off offset:128
	global_load_dwordx4 v[26:29], v[2:3], off offset:160
	global_load_dwordx4 v[22:25], v[2:3], off offset:192
	global_load_dwordx4 v[18:21], v[2:3], off offset:224
	v_add_u32_e32 v4, s25, v96
	v_mov_b64_e32 v[2:3], s[30:31]
	v_and_b32_e32 v63, 63, v196
	s_lshl_b32 s34, s4, 7
	v_mad_i64_i32 v[6:7], s[0:1], v4, s3, v[2:3]
	s_lshl_b32 s4, s4, 8
	v_lshl_add_u64 v[6:7], v[6:7], 0, s[4:5]
	v_lshlrev_b32_e32 v0, 1, v63
	v_lshl_add_u64 v[12:13], v[6:7], 0, v[0:1]
	v_or_b32_e32 v6, 1, v4
	v_mad_i64_i32 v[6:7], s[0:1], v6, s3, v[2:3]
	v_lshl_add_u64 v[6:7], v[6:7], 0, s[4:5]
	v_lshl_add_u64 v[14:15], v[6:7], 0, v[0:1]
	v_or_b32_e32 v6, 2, v4
	v_mad_i64_i32 v[6:7], s[0:1], v6, s3, v[2:3]
	v_lshl_add_u64 v[6:7], v[6:7], 0, s[4:5]
	v_lshl_add_u64 v[16:17], v[6:7], 0, v[0:1]
	v_or_b32_e32 v6, 3, v4
	v_mad_i64_i32 v[6:7], s[0:1], v6, s3, v[2:3]
	v_lshl_add_u64 v[6:7], v[6:7], 0, s[4:5]
	v_lshl_add_u64 v[50:51], v[6:7], 0, v[0:1]
	v_or_b32_e32 v6, 4, v4
	v_mad_i64_i32 v[6:7], s[0:1], v6, s3, v[2:3]
	v_lshl_add_u64 v[6:7], v[6:7], 0, s[4:5]
	v_lshl_add_u64 v[66:67], v[6:7], 0, v[0:1]
	v_or_b32_e32 v6, 5, v4
	s_mov_b64 s[40:41], 0x1780
	v_mad_i64_i32 v[6:7], s[0:1], v6, s3, v[2:3]
	v_lshl_add_u64 v[56:57], v[12:13], 0, s[40:41]
	v_lshl_add_u64 v[6:7], v[6:7], 0, s[4:5]
	v_add_co_u32_e32 v12, vcc, s87, v12
	v_lshl_add_u64 v[70:71], v[6:7], 0, v[0:1]
	v_or_b32_e32 v6, 6, v4
	v_addc_co_u32_e32 v13, vcc, 0, v13, vcc
	v_lshl_add_u64 v[58:59], v[14:15], 0, s[40:41]
	v_mad_i64_i32 v[6:7], s[0:1], v6, s3, v[2:3]
	v_add_co_u32_e32 v14, vcc, s87, v14
	v_lshl_add_u64 v[6:7], v[6:7], 0, s[4:5]
	s_nop 0
	v_addc_co_u32_e32 v15, vcc, 0, v15, vcc
	v_lshl_add_u64 v[60:61], v[16:17], 0, s[40:41]
	v_lshl_add_u64 v[74:75], v[6:7], 0, v[0:1]
	v_or_b32_e32 v6, 7, v4
	v_add_co_u32_e32 v16, vcc, s87, v16
	v_mad_i64_i32 v[6:7], s[0:1], v6, s3, v[2:3]
	s_nop 0
	v_addc_co_u32_e32 v17, vcc, 0, v17, vcc
	v_lshl_add_u64 v[64:65], v[50:51], 0, s[40:41]
	v_lshl_add_u64 v[6:7], v[6:7], 0, s[4:5]
	v_or_b32_e32 v52, 11, v4
	v_add_co_u32_e32 v50, vcc, s87, v50
	v_lshl_add_u64 v[78:79], v[6:7], 0, v[0:1]
	v_or_b32_e32 v6, 8, v4
	v_or_b32_e32 v8, 9, v4
	v_or_b32_e32 v10, 10, v4
	v_mad_i64_i32 v[52:53], s[0:1], v52, s3, v[2:3]
	v_addc_co_u32_e32 v51, vcc, 0, v51, vcc
	global_load_ushort v97, v[12:13], off offset:1920
	global_load_ushort v98, v[14:15], off offset:1920
	global_load_ushort v99, v[16:17], off offset:1920
	global_load_ushort v100, v[50:51], off offset:1920
	v_or_b32_e32 v14, 12, v4
	v_or_b32_e32 v16, 13, v4
	v_or_b32_e32 v50, 14, v4
	v_or_b32_e32 v4, 15, v4
	v_mad_i64_i32 v[6:7], s[0:1], v6, s3, v[2:3]
	v_mad_i64_i32 v[8:9], s[0:1], v8, s3, v[2:3]
	v_mad_i64_i32 v[10:11], s[0:1], v10, s3, v[2:3]
	v_lshl_add_u64 v[12:13], v[52:53], 0, s[4:5]
	v_mad_i64_i32 v[14:15], s[0:1], v14, s3, v[2:3]
	v_mad_i64_i32 v[16:17], s[0:1], v16, s3, v[2:3]
	v_mad_i64_i32 v[50:51], s[0:1], v50, s3, v[2:3]
	v_mad_i64_i32 v[52:53], s[0:1], v4, s3, v[2:3]
	v_lshl_add_u64 v[6:7], v[6:7], 0, s[4:5]
	v_lshl_add_u64 v[8:9], v[8:9], 0, s[4:5]
	v_lshl_add_u64 v[10:11], v[10:11], 0, s[4:5]
	v_lshl_add_u64 v[14:15], v[14:15], 0, s[4:5]
	v_lshl_add_u64 v[16:17], v[16:17], 0, s[4:5]
	v_lshl_add_u64 v[50:51], v[50:51], 0, s[4:5]
	v_lshl_add_u64 v[52:53], v[52:53], 0, s[4:5]
	v_lshl_add_u64 v[82:83], v[6:7], 0, v[0:1]
	v_lshl_add_u64 v[84:85], v[8:9], 0, v[0:1]
	v_lshl_add_u64 v[86:87], v[10:11], 0, v[0:1]
	v_lshl_add_u64 v[88:89], v[12:13], 0, v[0:1]
	v_lshl_add_u64 v[90:91], v[14:15], 0, v[0:1]
	v_lshl_add_u64 v[92:93], v[16:17], 0, v[0:1]
	v_lshl_add_u64 v[94:95], v[50:51], 0, v[0:1]
	v_lshl_add_u64 v[54:55], v[52:53], 0, v[0:1]
	v_or_b32_e32 v0, s34, v63
	v_lshlrev_b32_e32 v0, 2, v0
	global_load_dword v4, v0, s[48:49]
	s_nop 0
	global_load_dword v0, v0, s[48:49] offset:256
	s_nop 0
	global_load_ushort v101, v[56:57], off offset:128
	global_load_ushort v102, v[58:59], off offset:128
	global_load_ushort v103, v[60:61], off offset:128
	global_load_ushort v104, v[64:65], off offset:128
	v_add_co_u32_e32 v56, vcc, s87, v66
	v_lshl_add_u64 v[68:69], v[66:67], 0, s[40:41]
	s_nop 0
	v_addc_co_u32_e32 v57, vcc, 0, v67, vcc
	v_add_co_u32_e32 v58, vcc, s87, v70
	v_lshl_add_u64 v[72:73], v[70:71], 0, s[40:41]
	s_nop 0
	v_addc_co_u32_e32 v59, vcc, 0, v71, vcc
	v_add_co_u32_e32 v60, vcc, s87, v74
	v_lshl_add_u64 v[76:77], v[74:75], 0, s[40:41]
	s_nop 0
	v_addc_co_u32_e32 v61, vcc, 0, v75, vcc
	v_add_co_u32_e32 v64, vcc, s87, v78
	v_lshl_add_u64 v[80:81], v[78:79], 0, s[40:41]
	s_nop 0
	v_addc_co_u32_e32 v65, vcc, 0, v79, vcc
	global_load_ushort v105, v[56:57], off offset:1920
	global_load_ushort v106, v[58:59], off offset:1920
	global_load_ushort v107, v[60:61], off offset:1920
	global_load_ushort v108, v[64:65], off offset:1920
	global_load_ushort v109, v[68:69], off offset:128
	global_load_ushort v110, v[72:73], off offset:128
	global_load_ushort v111, v[76:77], off offset:128
	global_load_ushort v112, v[80:81], off offset:128
	v_add_co_u32_e32 v56, vcc, s87, v82
	v_lshl_add_u64 v[6:7], v[82:83], 0, s[40:41]
	s_nop 0
	v_addc_co_u32_e32 v57, vcc, 0, v83, vcc
	v_add_co_u32_e32 v58, vcc, s87, v84
	v_lshl_add_u64 v[8:9], v[84:85], 0, s[40:41]
	s_nop 0
	v_addc_co_u32_e32 v59, vcc, 0, v85, vcc
	v_add_co_u32_e32 v60, vcc, s87, v86
	v_lshl_add_u64 v[10:11], v[86:87], 0, s[40:41]
	s_nop 0
	v_addc_co_u32_e32 v61, vcc, 0, v87, vcc
	v_add_co_u32_e32 v64, vcc, s87, v88
	v_lshl_add_u64 v[12:13], v[88:89], 0, s[40:41]
	s_waitcnt vmcnt(17)
; DI bf16_t f2bf(float f) { unsigned u = __float_as_uint(f); u += 0x7fffu + ((u >> 16) & 1u); return (bf16_t)(u >> 16); }
; DI float wave_sum(float v) { for (int o = 32; o; o >>= 1) v += __shfl_xor(v, o); return v; }
; DI float geluf_(float x) { const float u = 0.7978845608028654f * (x + 0.044715f * x * x * x); return x * __builtin_amdgcn_rcpf(1.f + __builtin_amdgcn_exp2f(-2.f * LOG2E * u)); }
; DI void sg_item(int item, const bf16_t* proj, const bf16_t* sgw, const float* vng, const float* bs, bf16_t* obuf, unsigned char* smem, const int tid) {
;     ...
; #pragma unroll
;     for (int e = 0; e < 16; ++e) { const int tt = wv * 16 + e;
;         const float a0 = geluf_(va[e][0]), a1 = geluf_(va[e][1]);
;         const float ss = wave_sum(a0 * a0 + a1 * a1); const float rs = rsqrtf(ss * (1.f / 128.f) + NEPS);
;         vT[lane * 136 + tt] = f2bf(a0 * rs * g0); vT[(lane + 64) * 136 + tt] = f2bf(a1 * rs * g1); }
	v_lshlrev_b32_e32 v70, 16, v97
	v_mul_f32_e32 v68, 0x3d372713, v70
	v_mul_f32_e32 v68, v68, v70
	v_fma_f32 v68, v68, v70, v70
	v_mul_f32_e32 v68, 0x3f4c422a, v68
	s_waitcnt vmcnt(16)
	v_lshlrev_b32_e32 v71, 16, v98
	v_mul_f32_e32 v68, 0xc038aa3b, v68
	v_exp_f32_e32 v72, v68
	v_mul_f32_e32 v68, 0x3d372713, v71
	v_mul_f32_e32 v68, v68, v71
	v_fma_f32 v68, v68, v71, v71
	v_mul_f32_e32 v68, 0x3f4c422a, v68
	v_mul_f32_e32 v68, 0xc038aa3b, v68
	s_waitcnt vmcnt(14)
	v_lshlrev_b32_e32 v69, 16, v100
	v_exp_f32_e32 v73, v68
	v_lshlrev_b32_e32 v68, 16, v99
	v_mul_f32_e32 v74, 0x3d372713, v68
	v_mul_f32_e32 v75, 0x3d372713, v69
	v_mul_f32_e32 v74, v74, v68
	v_mul_f32_e32 v75, v75, v69
	v_fma_f32 v74, v74, v68, v68
	v_fma_f32 v75, v75, v69, v69
	v_mul_f32_e32 v74, 0x3f4c422a, v74
	v_mul_f32_e32 v75, 0x3f4c422a, v75
	v_mul_f32_e32 v74, 0xc038aa3b, v74
	v_mul_f32_e32 v75, 0xc038aa3b, v75
	v_exp_f32_e32 v74, v74
	v_exp_f32_e32 v75, v75
	v_add_f32_e32 v72, 1.0, v72
	v_add_f32_e32 v73, 1.0, v73
	v_add_f32_e32 v74, 1.0, v74
	v_add_f32_e32 v75, 1.0, v75
	v_rcp_f32_e32 v74, v74
	v_rcp_f32_e32 v75, v75
	v_rcp_f32_e32 v72, v72
	v_rcp_f32_e32 v73, v73
	v_addc_co_u32_e32 v65, vcc, 0, v89, vcc
	s_waitcnt vmcnt(11)
	v_lshlrev_b32_e32 v76, 16, v101
	v_mul_f32_e32 v77, 0x3d372713, v76
	v_mul_f32_e32 v77, v77, v76
	v_fma_f32 v77, v77, v76, v76
	v_mul_f32_e32 v77, 0x3f4c422a, v77
	v_mul_f32_e32 v77, 0xc038aa3b, v77
	v_exp_f32_e32 v80, v77
	s_waitcnt vmcnt(10)
	v_lshlrev_b32_e32 v77, 16, v102
	v_mul_f32_e32 v81, 0x3d372713, v77
	s_waitcnt vmcnt(8)
	v_lshlrev_b32_e32 v79, 16, v104
	v_lshlrev_b32_e32 v78, 16, v103
	v_mul_f32_e32 v81, v81, v77
	v_fma_f32 v81, v81, v77, v77
	v_mul_f32_e32 v82, 0x3d372713, v78
	v_mul_f32_e32 v83, 0x3d372713, v79
	v_mul_f32_e32 v81, 0x3f4c422a, v81
	v_mul_f32_e32 v82, v82, v78
	v_mul_f32_e32 v83, v83, v79
	v_mul_f32_e32 v81, 0xc038aa3b, v81
	v_fma_f32 v82, v82, v78, v78
	v_fma_f32 v83, v83, v79, v79
	v_exp_f32_e32 v81, v81
	v_mul_f32_e32 v82, 0x3f4c422a, v82
	v_mul_f32_e32 v83, 0x3f4c422a, v83
	v_mul_f32_e32 v82, 0xc038aa3b, v82
	v_mul_f32_e32 v83, 0xc038aa3b, v83
	v_exp_f32_e32 v82, v82
	v_exp_f32_e32 v83, v83
	v_add_f32_e32 v80, 1.0, v80
	v_add_f32_e32 v81, 1.0, v81
	v_rcp_f32_e32 v80, v80
	v_rcp_f32_e32 v81, v81
	v_add_f32_e32 v82, 1.0, v82
	v_add_f32_e32 v83, 1.0, v83
	v_rcp_f32_e32 v82, v82
	v_rcp_f32_e32 v83, v83
	v_pk_mul_f32 v[68:69], v[74:75], v[68:69]
	v_pk_mul_f32 v[74:75], v[80:81], v[76:77]
	v_pk_mul_f32 v[70:71], v[72:73], v[70:71]
	v_pk_mul_f32 v[76:77], v[74:75], v[74:75]
	v_pk_mul_f32 v[72:73], v[82:83], v[78:79]
	v_pk_fma_f32 v[76:77], v[70:71], v[70:71], v[76:77]
	v_pk_mul_f32 v[78:79], v[72:73], v[72:73]
	v_mov_b32_e32 v80, v76
	v_mov_b32_e32 v81, v77
	s_nop 0
	v_permlane32_swap_b32_e32 v80, v76
	v_permlane32_swap_b32_e32 v81, v77
	v_pk_fma_f32 v[78:79], v[68:69], v[68:69], v[78:79]
	v_mov_b32_e32 v82, v78
	v_mov_b32_e32 v83, v79
	s_nop 0
	v_permlane32_swap_b32_e32 v82, v78
	v_permlane32_swap_b32_e32 v83, v79
	v_add_co_u32_e32 v66, vcc, s87, v90
	s_waitcnt lgkmcnt(2)
	v_pk_add_f32 v[76:77], v[76:77], v[80:81]
	v_mov_b32_e32 v80, v76
	v_mov_b32_e32 v81, v77
	s_nop 0
	v_permlane16_swap_b32_e32 v80, v76
	v_permlane16_swap_b32_e32 v81, v77
	s_waitcnt lgkmcnt(2)
	v_pk_add_f32 v[78:79], v[78:79], v[82:83]
	v_mov_b32_e32 v82, v78
	v_mov_b32_e32 v83, v79
	s_nop 0
	v_permlane16_swap_b32_e32 v82, v78
	v_permlane16_swap_b32_e32 v83, v79
	v_addc_co_u32_e32 v67, vcc, 0, v91, vcc
	s_waitcnt lgkmcnt(2)
	v_pk_add_f32 v[76:77], v[76:77], v[80:81]
	s_nop 1
	v_mov_b32_dpp v80, v76 row_ror:8 row_mask:0xf bank_mask:0xf
	v_mov_b32_dpp v81, v77 row_ror:8 row_mask:0xf bank_mask:0xf
	s_waitcnt lgkmcnt(2)
	v_pk_add_f32 v[78:79], v[78:79], v[82:83]
	s_nop 1
	v_mov_b32_dpp v82, v78 row_ror:8 row_mask:0xf bank_mask:0xf
	v_mov_b32_dpp v83, v79 row_ror:8 row_mask:0xf bank_mask:0xf
	v_add_co_u32_e32 v84, vcc, s87, v92
	s_waitcnt lgkmcnt(2)
	v_pk_add_f32 v[76:77], v[76:77], v[80:81]
	s_nop 1
	v_mov_b32_dpp v80, v76 row_shl:4 row_mask:0xf bank_mask:0x5
	s_nop 1
	v_mov_b32_dpp v80, v76 row_shr:4 row_mask:0xf bank_mask:0xa
	v_mov_b32_dpp v81, v77 row_shl:4 row_mask:0xf bank_mask:0x5
	s_nop 1
	v_mov_b32_dpp v81, v77 row_shr:4 row_mask:0xf bank_mask:0xa
	v_addc_co_u32_e32 v85, vcc, 0, v93, vcc
	s_waitcnt lgkmcnt(2)
	v_pk_add_f32 v[78:79], v[78:79], v[82:83]
	v_add_co_u32_e32 v86, vcc, s87, v94
	s_nop 1
	v_mov_b32_dpp v82, v78 row_shl:4 row_mask:0xf bank_mask:0x5
	s_nop 1
	v_mov_b32_dpp v82, v78 row_shr:4 row_mask:0xf bank_mask:0xa
	v_mov_b32_dpp v83, v79 row_shl:4 row_mask:0xf bank_mask:0x5
	s_nop 1
	v_mov_b32_dpp v83, v79 row_shr:4 row_mask:0xf bank_mask:0xa
	v_addc_co_u32_e32 v87, vcc, 0, v95, vcc
	v_add_co_u32_e32 v88, vcc, s87, v54
	v_lshl_add_u64 v[14:15], v[90:91], 0, s[40:41]
	v_lshl_add_u64 v[16:17], v[92:93], 0, s[40:41]
	v_lshl_add_u64 v[52:53], v[54:55], 0, s[40:41]
	v_addc_co_u32_e32 v89, vcc, 0, v55, vcc
	global_load_ushort v90, v[56:57], off offset:1920
	global_load_ushort v91, v[58:59], off offset:1920
	global_load_ushort v92, v[60:61], off offset:1920
	global_load_ushort v93, v[64:65], off offset:1920
	s_nop 0
	global_load_ushort v56, v[66:67], off offset:1920
	global_load_ushort v57, v[84:85], off offset:1920
	global_load_ushort v55, v[86:87], off offset:1920
	global_load_ushort v54, v[88:89], off offset:1920
	s_waitcnt lgkmcnt(2)
	v_pk_add_f32 v[58:59], v[76:77], v[80:81]
	s_nop 1
	v_mov_b32_dpp v60, v58 quad_perm:[2,3,0,1] row_mask:0xf bank_mask:0xf
	v_mov_b32_dpp v61, v59 quad_perm:[2,3,0,1] row_mask:0xf bank_mask:0xf
	s_waitcnt lgkmcnt(2)
; DI bf16_t f2bf(float f) { unsigned u = __float_as_uint(f); u += 0x7fffu + ((u >> 16) & 1u); return (bf16_t)(u >> 16); }
; DI float wave_sum(float v) { for (int o = 32; o; o >>= 1) v += __shfl_xor(v, o); return v; }
; DI float geluf_(float x) { const float u = 0.7978845608028654f * (x + 0.044715f * x * x * x); return x * __builtin_amdgcn_rcpf(1.f + __builtin_amdgcn_exp2f(-2.f * LOG2E * u)); }
; DI void sg_item(int item, const bf16_t* proj, const bf16_t* sgw, const float* vng, const float* bs, bf16_t* obuf, unsigned char* smem, const int tid) {
;     ...
; #pragma unroll
;     for (int e = 0; e < 16; ++e) { const int tt = wv * 16 + e;
;         const float a0 = geluf_(va[e][0]), a1 = geluf_(va[e][1]);
;         const float ss = wave_sum(a0 * a0 + a1 * a1); const float rs = rsqrtf(ss * (1.f / 128.f) + NEPS);
;         vT[lane * 136 + tt] = f2bf(a0 * rs * g0); vT[(lane + 64) * 136 + tt] = f2bf(a1 * rs * g1); }
	v_pk_add_f32 v[64:65], v[78:79], v[82:83]
	s_nop 1
	v_mov_b32_dpp v66, v64 quad_perm:[2,3,0,1] row_mask:0xf bank_mask:0xf
	v_mov_b32_dpp v67, v65 quad_perm:[2,3,0,1] row_mask:0xf bank_mask:0xf
	v_lshl_add_u64 v[50:51], v[94:95], 0, s[40:41]
	global_load_ushort v76, v[6:7], off offset:128
	global_load_ushort v77, v[8:9], off offset:128
	global_load_ushort v78, v[10:11], off offset:128
	global_load_ushort v79, v[12:13], off offset:128
	s_nop 0
	global_load_ushort v12, v[14:15], off offset:128
	global_load_ushort v13, v[16:17], off offset:128
	global_load_ushort v11, v[50:51], off offset:128
	global_load_ushort v10, v[52:53], off offset:128
	s_waitcnt lgkmcnt(2)
	v_pk_add_f32 v[6:7], v[58:59], v[60:61]
	s_nop 1
	v_mov_b32_dpp v8, v6 quad_perm:[1,0,3,2] row_mask:0xf bank_mask:0xf
	v_mov_b32_dpp v9, v7 quad_perm:[1,0,3,2] row_mask:0xf bank_mask:0xf
	s_waitcnt lgkmcnt(2)
	v_pk_add_f32 v[14:15], v[64:65], v[66:67]
	s_nop 1
	v_mov_b32_dpp v16, v14 quad_perm:[1,0,3,2] row_mask:0xf bank_mask:0xf
	v_mov_b32_dpp v17, v15 quad_perm:[1,0,3,2] row_mask:0xf bank_mask:0xf
	s_mov_b32 s56, 0x45800000
	s_waitcnt lgkmcnt(2)
	v_pk_add_f32 v[8:9], v[6:7], v[8:9]
	v_mov_b64_e32 v[6:7], s[72:73]
	v_pk_fma_f32 v[8:9], v[8:9], s[96:97], v[6:7] op_sel_hi:[1,0,0]
	s_waitcnt lgkmcnt(0)
	v_pk_add_f32 v[14:15], v[14:15], v[16:17]
	v_mul_f32_e32 v16, 0x4b800000, v8
	v_cmp_gt_f32_e32 vcc, s77, v8
	v_pk_fma_f32 v[14:15], v[14:15], s[96:97], v[6:7] op_sel_hi:[1,0,0]
	v_cmp_gt_f32_e64 s[0:1], s77, v9
	v_cndmask_b32_e32 v8, v8, v16, vcc
	v_rsq_f32_e32 v16, v8
	v_mul_f32_e32 v8, 0x4b800000, v9
	v_cndmask_b32_e64 v8, v9, v8, s[0:1]
	v_mul_f32_e32 v9, 0x4b800000, v14
	v_cmp_gt_f32_e64 s[40:41], s77, v14
	v_cmp_gt_f32_e64 s[42:43], s77, v15
	v_rsq_f32_e32 v17, v8
	v_cndmask_b32_e64 v9, v14, v9, s[40:41]
	v_rsq_f32_e32 v14, v9
	v_mul_f32_e32 v9, 0x4b800000, v15
	v_cndmask_b32_e64 v9, v15, v9, s[42:43]
	v_rsq_f32_e32 v15, v9
	v_pk_mul_f32 v[52:53], v[16:17], s[56:57] op_sel_hi:[1,0]
	v_mad_u32_u24 v8, v63, s10, 0
	v_cndmask_b32_e64 v17, v17, v53, s[0:1]
	v_pk_mul_f32 v[50:51], v[14:15], s[56:57] op_sel_hi:[1,0]
	v_cndmask_b32_e32 v16, v16, v52, vcc
	v_cndmask_b32_e64 v15, v15, v51, s[42:43]
	v_cndmask_b32_e64 v14, v14, v50, s[40:41]
	v_pk_mul_f32 v[52:53], v[70:71], v[16:17]
	v_pk_mul_f32 v[50:51], v[68:69], v[14:15]
	v_pk_mul_f32 v[52:53], v[4:5], v[52:53] op_sel_hi:[0,1]
	v_pk_mul_f32 v[50:51], v[4:5], v[50:51] op_sel_hi:[0,1]
	v_bfe_u32 v61, v52, 16, 1
	v_bfe_u32 v59, v50, 16, 1
	v_add3_u32 v63, v52, v61, s11
	s_waitcnt vmcnt(23)
	v_lshlrev_b32_e32 v52, 16, v105
	v_add3_u32 v81, v50, v59, s11
	v_mul_f32_e32 v50, 0x3d372713, v52
	v_mul_f32_e32 v50, v50, v52
	v_fma_f32 v50, v50, v52, v52
	v_bfe_u32 v60, v53, 16, 1
	v_mul_f32_e32 v50, 0x3f4c422a, v50
	v_bfe_u32 v58, v51, 16, 1
	v_add3_u32 v80, v53, v60, s11
	s_waitcnt vmcnt(22)
	v_lshlrev_b32_e32 v53, 16, v106
	v_mul_f32_e32 v50, 0xc038aa3b, v50
	s_waitcnt vmcnt(19)
	v_lshlrev_b32_e32 v64, 16, v109
	v_add3_u32 v82, v51, v58, s11
	v_exp_f32_e32 v58, v50
	v_mul_f32_e32 v50, 0x3d372713, v53
	v_mul_f32_e32 v65, 0x3d372713, v64
	v_mul_f32_e32 v50, v50, v53
	v_mul_f32_e32 v65, v65, v64
	v_fma_f32 v50, v50, v53, v53
	v_fma_f32 v65, v65, v64, v64
	v_mul_f32_e32 v50, 0x3f4c422a, v50
	v_mul_f32_e32 v65, 0x3f4c422a, v65
	v_mul_f32_e32 v50, 0xc038aa3b, v50
	v_mul_f32_e32 v65, 0xc038aa3b, v65
	v_lshlrev_b32_e32 v51, 16, v108
	v_exp_f32_e32 v59, v50
	v_lshlrev_b32_e32 v50, 16, v107
	v_exp_f32_e32 v68, v65
	s_waitcnt vmcnt(18)
	v_lshlrev_b32_e32 v65, 16, v110
	v_mul_f32_e32 v60, 0x3d372713, v50
	v_mul_f32_e32 v61, 0x3d372713, v51
	v_mul_f32_e32 v69, 0x3d372713, v65
	v_mul_f32_e32 v60, v60, v50
	v_mul_f32_e32 v61, v61, v51
	s_waitcnt vmcnt(16)
	v_lshlrev_b32_e32 v67, 16, v112
	v_lshlrev_b32_e32 v66, 16, v111
	v_mul_f32_e32 v69, v69, v65
	v_fma_f32 v60, v60, v50, v50
	v_fma_f32 v61, v61, v51, v51
	v_fma_f32 v69, v69, v65, v65
	v_mul_f32_e32 v70, 0x3d372713, v66
	v_mul_f32_e32 v71, 0x3d372713, v67
	v_mul_f32_e32 v60, 0x3f4c422a, v60
	v_mul_f32_e32 v61, 0x3f4c422a, v61
	v_mul_f32_e32 v69, 0x3f4c422a, v69
	v_mul_f32_e32 v70, v70, v66
	v_mul_f32_e32 v71, v71, v67
	v_mul_f32_e32 v60, 0xc038aa3b, v60
	v_mul_f32_e32 v61, 0xc038aa3b, v61
	v_mul_f32_e32 v69, 0xc038aa3b, v69
	v_fma_f32 v70, v70, v66, v66
	v_fma_f32 v71, v71, v67, v67
	v_exp_f32_e32 v60, v60
	v_exp_f32_e32 v61, v61
	v_exp_f32_e32 v69, v69
	v_mul_f32_e32 v70, 0x3f4c422a, v70
	v_mul_f32_e32 v71, 0x3f4c422a, v71
	v_mul_f32_e32 v70, 0xc038aa3b, v70
	v_mul_f32_e32 v71, 0xc038aa3b, v71
	v_exp_f32_e32 v70, v70
	v_exp_f32_e32 v71, v71
	v_add_f32_e32 v60, 1.0, v60
	v_add_f32_e32 v61, 1.0, v61
	v_add_f32_e32 v68, 1.0, v68
	v_add_f32_e32 v69, 1.0, v69
	v_add_f32_e32 v58, 1.0, v58
	v_add_f32_e32 v59, 1.0, v59
	v_rcp_f32_e32 v60, v60
	v_rcp_f32_e32 v61, v61
	v_rcp_f32_e32 v68, v68
	v_rcp_f32_e32 v69, v69
	v_rcp_f32_e32 v58, v58
	v_rcp_f32_e32 v59, v59
	v_add_f32_e32 v70, 1.0, v70
	v_add_f32_e32 v71, 1.0, v71
	v_rcp_f32_e32 v70, v70
	v_rcp_f32_e32 v71, v71
	v_pk_mul_f32 v[50:51], v[60:61], v[50:51]
	v_pk_mul_f32 v[60:61], v[68:69], v[64:65]
	v_pk_mul_f32 v[52:53], v[58:59], v[52:53]
	v_pk_mul_f32 v[64:65], v[60:61], v[60:61]
	v_pk_mul_f32 v[58:59], v[70:71], v[66:67]
	v_pk_fma_f32 v[64:65], v[52:53], v[52:53], v[64:65]
	v_pk_mul_f32 v[66:67], v[58:59], v[58:59]
	v_mov_b32_e32 v68, v64
	v_mov_b32_e32 v69, v65
	s_nop 0
	v_permlane32_swap_b32_e32 v68, v64
	v_permlane32_swap_b32_e32 v69, v65
	v_pk_fma_f32 v[66:67], v[50:51], v[50:51], v[66:67]
	v_mov_b32_e32 v70, v66
	v_mov_b32_e32 v71, v67
	s_nop 0
	v_permlane32_swap_b32_e32 v70, v66
	v_permlane32_swap_b32_e32 v71, v67
	v_pk_mul_f32 v[16:17], v[74:75], v[16:17]
	s_waitcnt lgkmcnt(2)
; DI bf16_t f2bf(float f) { unsigned u = __float_as_uint(f); u += 0x7fffu + ((u >> 16) & 1u); return (bf16_t)(u >> 16); }
; DI float wave_sum(float v) { for (int o = 32; o; o >>= 1) v += __shfl_xor(v, o); return v; }
; DI float geluf_(float x) { const float u = 0.7978845608028654f * (x + 0.044715f * x * x * x); return x * __builtin_amdgcn_rcpf(1.f + __builtin_amdgcn_exp2f(-2.f * LOG2E * u)); }
; DI void sg_item(int item, const bf16_t* proj, const bf16_t* sgw, const float* vng, const float* bs, bf16_t* obuf, unsigned char* smem, const int tid) {
;     ...
; #pragma unroll
;     for (int e = 0; e < 16; ++e) { const int tt = wv * 16 + e;
;         const float a0 = geluf_(va[e][0]), a1 = geluf_(va[e][1]);
;         const float ss = wave_sum(a0 * a0 + a1 * a1); const float rs = rsqrtf(ss * (1.f / 128.f) + NEPS);
;         vT[lane * 136 + tt] = f2bf(a0 * rs * g0); vT[(lane + 64) * 136 + tt] = f2bf(a1 * rs * g1); }
	v_pk_add_f32 v[64:65], v[64:65], v[68:69]
	v_mov_b32_e32 v68, v64
	v_mov_b32_e32 v69, v65
	s_nop 0
	v_permlane16_swap_b32_e32 v68, v64
	v_permlane16_swap_b32_e32 v69, v65
	s_waitcnt lgkmcnt(2)
	v_pk_add_f32 v[66:67], v[66:67], v[70:71]
	v_mov_b32_e32 v70, v66
	v_mov_b32_e32 v71, v67
	s_nop 0
	v_permlane16_swap_b32_e32 v70, v66
	v_permlane16_swap_b32_e32 v71, v67
	v_pk_mul_f32 v[16:17], v[0:1], v[16:17] op_sel_hi:[0,1]
	s_waitcnt lgkmcnt(2)
	v_pk_add_f32 v[64:65], v[64:65], v[68:69]
	s_nop 1
	v_mov_b32_dpp v68, v64 row_ror:8 row_mask:0xf bank_mask:0xf
	v_mov_b32_dpp v69, v65 row_ror:8 row_mask:0xf bank_mask:0xf
	s_waitcnt lgkmcnt(2)
	v_pk_add_f32 v[66:67], v[66:67], v[70:71]
	s_nop 1
	v_mov_b32_dpp v70, v66 row_ror:8 row_mask:0xf bank_mask:0xf
	v_mov_b32_dpp v71, v67 row_ror:8 row_mask:0xf bank_mask:0xf
	v_bfe_u32 v74, v17, 16, 1
	s_waitcnt lgkmcnt(2)
	v_pk_add_f32 v[64:65], v[64:65], v[68:69]
	s_nop 1
	v_mov_b32_dpp v68, v64 row_shl:4 row_mask:0xf bank_mask:0x5
	s_nop 1
	v_mov_b32_dpp v68, v64 row_shr:4 row_mask:0xf bank_mask:0xa
	v_mov_b32_dpp v69, v65 row_shl:4 row_mask:0xf bank_mask:0x5
	s_nop 1
	v_mov_b32_dpp v69, v65 row_shr:4 row_mask:0xf bank_mask:0xa
	s_waitcnt lgkmcnt(2)
	v_pk_add_f32 v[66:67], v[66:67], v[70:71]
	s_nop 1
	v_mov_b32_dpp v70, v66 row_shl:4 row_mask:0xf bank_mask:0x5
	s_nop 1
	v_mov_b32_dpp v70, v66 row_shr:4 row_mask:0xf bank_mask:0xa
	v_mov_b32_dpp v71, v67 row_shl:4 row_mask:0xf bank_mask:0x5
	s_nop 1
	v_mov_b32_dpp v71, v67 row_shr:4 row_mask:0xf bank_mask:0xa
	v_bfe_u32 v75, v16, 16, 1
	s_waitcnt lgkmcnt(2)
	v_pk_add_f32 v[64:65], v[64:65], v[68:69]
	s_nop 1
	v_mov_b32_dpp v68, v64 quad_perm:[2,3,0,1] row_mask:0xf bank_mask:0xf
	v_mov_b32_dpp v69, v65 quad_perm:[2,3,0,1] row_mask:0xf bank_mask:0xf
	s_waitcnt lgkmcnt(2)
	v_pk_add_f32 v[66:67], v[66:67], v[70:71]
	s_nop 1
	v_mov_b32_dpp v70, v66 quad_perm:[2,3,0,1] row_mask:0xf bank_mask:0xf
	v_mov_b32_dpp v71, v67 quad_perm:[2,3,0,1] row_mask:0xf bank_mask:0xf
	v_add3_u32 v75, v16, v75, s11
	s_waitcnt lgkmcnt(2)
	v_pk_add_f32 v[64:65], v[64:65], v[68:69]
	s_nop 1
	v_mov_b32_dpp v68, v64 quad_perm:[1,0,3,2] row_mask:0xf bank_mask:0xf
	v_mov_b32_dpp v69, v65 quad_perm:[1,0,3,2] row_mask:0xf bank_mask:0xf
	s_waitcnt lgkmcnt(2)
	v_pk_add_f32 v[66:67], v[66:67], v[70:71]
	s_nop 1
	v_mov_b32_dpp v70, v66 quad_perm:[1,0,3,2] row_mask:0xf bank_mask:0xf
	v_mov_b32_dpp v71, v67 quad_perm:[1,0,3,2] row_mask:0xf bank_mask:0xf
	v_add3_u32 v74, v17, v74, s11
	s_waitcnt lgkmcnt(2)
	v_pk_add_f32 v[16:17], v[64:65], v[68:69]
	v_pk_mul_f32 v[14:15], v[72:73], v[14:15]
	v_pk_fma_f32 v[16:17], v[16:17], s[96:97], v[6:7] op_sel_hi:[1,0,0]
	s_waitcnt lgkmcnt(0)
	v_pk_add_f32 v[64:65], v[66:67], v[70:71]
	v_mul_f32_e32 v66, 0x4b800000, v16
	v_cmp_gt_f32_e32 vcc, s77, v16
	v_pk_fma_f32 v[64:65], v[64:65], s[96:97], v[6:7] op_sel_hi:[1,0,0]
	v_cmp_gt_f32_e64 s[0:1], s77, v17
	v_cndmask_b32_e32 v16, v16, v66, vcc
	v_mul_f32_e32 v66, 0x4b800000, v17
	v_cndmask_b32_e64 v17, v17, v66, s[0:1]
	v_mul_f32_e32 v66, 0x4b800000, v64
	v_cmp_gt_f32_e64 s[40:41], s77, v64
	v_rsq_f32_e32 v16, v16
	v_cmp_gt_f32_e64 s[42:43], s77, v65
	v_cndmask_b32_e64 v64, v64, v66, s[40:41]
	v_mul_f32_e32 v66, 0x4b800000, v65
	v_rsq_f32_e32 v17, v17
	v_cndmask_b32_e64 v65, v65, v66, s[42:43]
	v_rsq_f32_e32 v64, v64
	v_rsq_f32_e32 v65, v65
	v_pk_mul_f32 v[14:15], v[0:1], v[14:15] op_sel_hi:[0,1]
	v_pk_mul_f32 v[66:67], v[16:17], s[56:57] op_sel_hi:[1,0]
	v_bfe_u32 v72, v15, 16, 1
	v_bfe_u32 v73, v14, 16, 1
	v_cndmask_b32_e64 v67, v17, v67, s[0:1]
	v_cndmask_b32_e32 v66, v16, v66, vcc
	v_add3_u32 v73, v14, v73, s11
	v_add3_u32 v72, v15, v72, s11
	v_pk_mul_f32 v[14:15], v[64:65], s[56:57] op_sel_hi:[1,0]
	v_pk_mul_f32 v[16:17], v[52:53], v[66:67]
	v_cndmask_b32_e64 v65, v65, v15, s[42:43]
	v_cndmask_b32_e64 v64, v64, v14, s[40:41]
	v_pk_mul_f32 v[16:17], v[4:5], v[16:17] op_sel_hi:[0,1]
	v_pk_mul_f32 v[14:15], v[50:51], v[64:65]
	v_bfe_u32 v52, v17, 16, 1
	v_bfe_u32 v53, v16, 16, 1
	v_pk_mul_f32 v[14:15], v[4:5], v[14:15] op_sel_hi:[0,1]
	v_add3_u32 v16, v16, v53, s11
	v_add3_u32 v52, v17, v52, s11
	s_mov_b32 s12, 0x7060302
	v_bfe_u32 v50, v15, 16, 1
	v_perm_b32 v16, v52, v16, s12
	s_waitcnt vmcnt(15)
	v_lshlrev_b32_e32 v52, 16, v90
	v_add3_u32 v15, v15, v50, s11
	v_mul_f32_e32 v50, 0x3d372713, v52
	v_bfe_u32 v51, v14, 16, 1
	v_mul_f32_e32 v50, v50, v52
	v_add3_u32 v14, v14, v51, s11
	v_fma_f32 v50, v50, v52, v52
	v_lshl_add_u32 v9, v96, 1, v8
	v_perm_b32 v17, v15, v14, s12
	v_perm_b32 v15, v82, v81, s12
	v_perm_b32 v14, v80, v63, s12
	v_mul_f32_e32 v50, 0x3f4c422a, v50
	s_barrier
; DI bf16_t f2bf(float f) { unsigned u = __float_as_uint(f); u += 0x7fffu + ((u >> 16) & 1u); return (bf16_t)(u >> 16); }
; DI float wave_sum(float v) { for (int o = 32; o; o >>= 1) v += __shfl_xor(v, o); return v; }
; DI float geluf_(float x) { const float u = 0.7978845608028654f * (x + 0.044715f * x * x * x); return x * __builtin_amdgcn_rcpf(1.f + __builtin_amdgcn_exp2f(-2.f * LOG2E * u)); }
; DI void sg_item(int item, const bf16_t* proj, const bf16_t* sgw, const float* vng, const float* bs, bf16_t* obuf, unsigned char* smem, const int tid) {
;     ...
; #pragma unroll
;     for (int e = 0; e < 16; ++e) { const int tt = wv * 16 + e;
;         const float a0 = geluf_(va[e][0]), a1 = geluf_(va[e][1]);
;         const float ss = wave_sum(a0 * a0 + a1 * a1); const float rs = rsqrtf(ss * (1.f / 128.f) + NEPS);
;         vT[lane * 136 + tt] = f2bf(a0 * rs * g0); vT[(lane + 64) * 136 + tt] = f2bf(a1 * rs * g1); }
	ds_write_b128 v9, v[14:17]
	v_pk_mul_f32 v[14:15], v[58:59], v[64:65]
	s_waitcnt vmcnt(14)
	v_lshlrev_b32_e32 v53, 16, v91
	v_mul_f32_e32 v50, 0xc038aa3b, v50
	s_waitcnt vmcnt(7)
	v_lshlrev_b32_e32 v64, 16, v76
	v_exp_f32_e32 v58, v50
	v_mul_f32_e32 v50, 0x3d372713, v53
	v_mul_f32_e32 v65, 0x3d372713, v64
	v_mul_f32_e32 v50, v50, v53
	v_mul_f32_e32 v65, v65, v64
	v_fma_f32 v50, v50, v53, v53
	v_fma_f32 v65, v65, v64, v64
	v_mul_f32_e32 v50, 0x3f4c422a, v50
	v_mul_f32_e32 v65, 0x3f4c422a, v65
	v_mul_f32_e32 v50, 0xc038aa3b, v50
	v_mul_f32_e32 v65, 0xc038aa3b, v65
	v_lshlrev_b32_e32 v51, 16, v93
	v_exp_f32_e32 v59, v50
	v_lshlrev_b32_e32 v50, 16, v92
	v_exp_f32_e32 v68, v65
	s_waitcnt vmcnt(6)
	v_lshlrev_b32_e32 v65, 16, v77
	v_pk_mul_f32 v[16:17], v[60:61], v[66:67]
	v_mul_f32_e32 v60, 0x3d372713, v50
	v_mul_f32_e32 v61, 0x3d372713, v51
	v_mul_f32_e32 v69, 0x3d372713, v65
	v_mul_f32_e32 v60, v60, v50
	v_mul_f32_e32 v61, v61, v51
	v_mul_f32_e32 v69, v69, v65
	v_fma_f32 v60, v60, v50, v50
	v_fma_f32 v61, v61, v51, v51
	v_fma_f32 v69, v69, v65, v65
	v_mul_f32_e32 v60, 0x3f4c422a, v60
	v_mul_f32_e32 v61, 0x3f4c422a, v61
	s_waitcnt vmcnt(4)
	v_lshlrev_b32_e32 v67, 16, v79
	v_lshlrev_b32_e32 v66, 16, v78
	v_mul_f32_e32 v69, 0x3f4c422a, v69
	v_mul_f32_e32 v60, 0xc038aa3b, v60
	v_mul_f32_e32 v61, 0xc038aa3b, v61
	v_mul_f32_e32 v69, 0xc038aa3b, v69
	v_mul_f32_e32 v70, 0x3d372713, v66
	v_mul_f32_e32 v71, 0x3d372713, v67
	v_exp_f32_e32 v60, v60
	v_exp_f32_e32 v61, v61
	v_exp_f32_e32 v69, v69
	v_mul_f32_e32 v70, v70, v66
	v_mul_f32_e32 v71, v71, v67
	v_fma_f32 v70, v70, v66, v66
	v_fma_f32 v71, v71, v67, v67
	v_mul_f32_e32 v70, 0x3f4c422a, v70
	v_mul_f32_e32 v71, 0x3f4c422a, v71
	v_mul_f32_e32 v70, 0xc038aa3b, v70
	v_mul_f32_e32 v71, 0xc038aa3b, v71
	v_add_f32_e32 v60, 1.0, v60
	v_add_f32_e32 v61, 1.0, v61
	v_add_f32_e32 v68, 1.0, v68
	v_exp_f32_e32 v70, v70
	v_exp_f32_e32 v71, v71
	v_add_f32_e32 v69, 1.0, v69
	v_add_f32_e32 v58, 1.0, v58
	v_add_f32_e32 v59, 1.0, v59
	v_rcp_f32_e32 v60, v60
	v_rcp_f32_e32 v61, v61
	v_rcp_f32_e32 v68, v68
	v_rcp_f32_e32 v69, v69
	v_rcp_f32_e32 v58, v58
	v_rcp_f32_e32 v59, v59
	v_add_f32_e32 v70, 1.0, v70
	v_add_f32_e32 v71, 1.0, v71
	v_rcp_f32_e32 v70, v70
	v_rcp_f32_e32 v71, v71
	v_pk_mul_f32 v[50:51], v[60:61], v[50:51]
	v_pk_mul_f32 v[60:61], v[68:69], v[64:65]
	v_pk_mul_f32 v[52:53], v[58:59], v[52:53]
	v_pk_mul_f32 v[64:65], v[60:61], v[60:61]
	v_pk_mul_f32 v[58:59], v[70:71], v[66:67]
	v_pk_fma_f32 v[64:65], v[52:53], v[52:53], v[64:65]
	v_mov_b32_e32 v68, v64
	v_mov_b32_e32 v69, v65
	s_nop 0
	v_permlane32_swap_b32_e32 v68, v64
	v_permlane32_swap_b32_e32 v69, v65
	v_pk_mul_f32 v[66:67], v[58:59], v[58:59]
	v_pk_mul_f32 v[16:17], v[0:1], v[16:17] op_sel_hi:[0,1]
	v_pk_fma_f32 v[66:67], v[50:51], v[50:51], v[66:67]
	v_mov_b32_e32 v70, v66
	v_mov_b32_e32 v71, v67
	s_nop 0
	v_permlane32_swap_b32_e32 v70, v66
	v_permlane32_swap_b32_e32 v71, v67
	s_waitcnt lgkmcnt(2)
	v_pk_add_f32 v[64:65], v[64:65], v[68:69]
	v_mov_b32_e32 v68, v64
	v_mov_b32_e32 v69, v65
	s_nop 0
	v_permlane16_swap_b32_e32 v68, v64
	v_permlane16_swap_b32_e32 v69, v65
	v_bfe_u32 v81, v17, 16, 1
	s_waitcnt lgkmcnt(2)
	v_pk_add_f32 v[66:67], v[66:67], v[70:71]
	v_mov_b32_e32 v70, v66
	v_mov_b32_e32 v71, v67
	s_nop 0
	v_permlane16_swap_b32_e32 v70, v66
	v_permlane16_swap_b32_e32 v71, v67
	s_waitcnt lgkmcnt(2)
	v_pk_add_f32 v[64:65], v[64:65], v[68:69]
	s_nop 1
	v_mov_b32_dpp v68, v64 row_ror:8 row_mask:0xf bank_mask:0xf
	v_mov_b32_dpp v69, v65 row_ror:8 row_mask:0xf bank_mask:0xf
	v_bfe_u32 v76, v16, 16, 1
	s_waitcnt lgkmcnt(2)
	v_pk_add_f32 v[66:67], v[66:67], v[70:71]
	s_nop 1
	v_mov_b32_dpp v70, v66 row_ror:8 row_mask:0xf bank_mask:0xf
	v_mov_b32_dpp v71, v67 row_ror:8 row_mask:0xf bank_mask:0xf
	v_add3_u32 v76, v16, v76, s11
	v_add3_u32 v77, v17, v81, s11
	s_waitcnt lgkmcnt(2)
	v_pk_add_f32 v[16:17], v[64:65], v[68:69]
	s_nop 1
	v_mov_b32_dpp v64, v16 row_shl:4 row_mask:0xf bank_mask:0x5
	s_nop 1
	v_mov_b32_dpp v64, v16 row_shr:4 row_mask:0xf bank_mask:0xa
	v_mov_b32_dpp v65, v17 row_shl:4 row_mask:0xf bank_mask:0x5
	s_nop 1
	v_mov_b32_dpp v65, v17 row_shr:4 row_mask:0xf bank_mask:0xa
	s_waitcnt lgkmcnt(2)
	v_pk_add_f32 v[66:67], v[66:67], v[70:71]
	s_nop 1
	v_mov_b32_dpp v68, v66 row_shl:4 row_mask:0xf bank_mask:0x5
	s_nop 1
	v_mov_b32_dpp v68, v66 row_shr:4 row_mask:0xf bank_mask:0xa
	v_mov_b32_dpp v69, v67 row_shl:4 row_mask:0xf bank_mask:0x5
	s_nop 1
	v_mov_b32_dpp v69, v67 row_shr:4 row_mask:0xf bank_mask:0xa
	v_pk_mul_f32 v[14:15], v[0:1], v[14:15] op_sel_hi:[0,1]
	s_waitcnt lgkmcnt(2)
	v_pk_add_f32 v[16:17], v[16:17], v[64:65]
	s_nop 1
	v_mov_b32_dpp v64, v16 quad_perm:[2,3,0,1] row_mask:0xf bank_mask:0xf
	v_mov_b32_dpp v65, v17 quad_perm:[2,3,0,1] row_mask:0xf bank_mask:0xf
	s_waitcnt lgkmcnt(2)
	v_pk_add_f32 v[66:67], v[66:67], v[68:69]
	s_nop 1
	v_mov_b32_dpp v68, v66 quad_perm:[2,3,0,1] row_mask:0xf bank_mask:0xf
	v_mov_b32_dpp v69, v67 quad_perm:[2,3,0,1] row_mask:0xf bank_mask:0xf
	v_bfe_u32 v63, v15, 16, 1
	s_waitcnt lgkmcnt(2)
	v_pk_add_f32 v[64:65], v[16:17], v[64:65]
	s_nop 1
	v_mov_b32_dpp v70, v64 quad_perm:[1,0,3,2] row_mask:0xf bank_mask:0xf
	v_mov_b32_dpp v71, v65 quad_perm:[1,0,3,2] row_mask:0xf bank_mask:0xf
	s_waitcnt lgkmcnt(2)
	v_pk_add_f32 v[66:67], v[66:67], v[68:69]
	s_nop 1
	v_mov_b32_dpp v68, v66 quad_perm:[1,0,3,2] row_mask:0xf bank_mask:0xf
	v_mov_b32_dpp v69, v67 quad_perm:[1,0,3,2] row_mask:0xf bank_mask:0xf
	v_bfe_u32 v80, v14, 16, 1
	s_waitcnt lgkmcnt(2)
	v_pk_add_f32 v[64:65], v[64:65], v[70:71]
	v_add3_u32 v14, v14, v80, s11
	v_add3_u32 v15, v15, v63, s11
	v_pk_fma_f32 v[64:65], v[64:65], s[96:97], v[6:7] op_sel_hi:[1,0,0]
	v_perm_b32 v17, v15, v14, s12
	v_mul_f32_e32 v14, 0x4b800000, v64
	v_cmp_gt_f32_e64 s[0:1], s77, v64
	s_waitcnt lgkmcnt(0)
; DI bf16_t f2bf(float f) { unsigned u = __float_as_uint(f); u += 0x7fffu + ((u >> 16) & 1u); return (bf16_t)(u >> 16); }
; DI float wave_sum(float v) { for (int o = 32; o; o >>= 1) v += __shfl_xor(v, o); return v; }
; DI float geluf_(float x) { const float u = 0.7978845608028654f * (x + 0.044715f * x * x * x); return x * __builtin_amdgcn_rcpf(1.f + __builtin_amdgcn_exp2f(-2.f * LOG2E * u)); }
; DI void sg_item(int item, const bf16_t* proj, const bf16_t* sgw, const float* vng, const float* bs, bf16_t* obuf, unsigned char* smem, const int tid) {
;     ...
; #pragma unroll
;     for (int e = 0; e < 16; ++e) { const int tt = wv * 16 + e;
;         const float a0 = geluf_(va[e][0]), a1 = geluf_(va[e][1]);
;         const float ss = wave_sum(a0 * a0 + a1 * a1); const float rs = rsqrtf(ss * (1.f / 128.f) + NEPS);
;         vT[lane * 136 + tt] = f2bf(a0 * rs * g0); vT[(lane + 64) * 136 + tt] = f2bf(a1 * rs * g1); }
	v_pk_add_f32 v[66:67], v[66:67], v[68:69]
	v_cmp_gt_f32_e64 s[40:41], s77, v65
	v_cndmask_b32_e64 v14, v64, v14, s[0:1]
	v_rsq_f32_e32 v64, v14
	v_mul_f32_e32 v14, 0x4b800000, v65
	v_pk_fma_f32 v[66:67], v[66:67], s[96:97], v[6:7] op_sel_hi:[1,0,0]
	v_cndmask_b32_e64 v14, v65, v14, s[40:41]
	v_mul_f32_e32 v63, 0x4b800000, v66
	v_cmp_gt_f32_e32 vcc, s77, v66
	v_rsq_f32_e32 v65, v14
	v_cmp_gt_f32_e64 s[42:43], s77, v67
	v_cndmask_b32_e32 v63, v66, v63, vcc
	v_rsq_f32_e32 v66, v63
	v_mul_f32_e32 v63, 0x4b800000, v67
	v_perm_b32 v16, v77, v76, s12
	v_perm_b32 v15, v72, v73, s12
	v_cndmask_b32_e64 v63, v67, v63, s[42:43]
	v_perm_b32 v14, v74, v75, s12
	v_lshlrev_b32_e32 v56, 16, v56
	v_rsq_f32_e32 v67, v63
	ds_write_b128 v9, v[14:17] offset:17408
	v_pk_mul_f32 v[16:17], v[64:65], s[56:57] op_sel_hi:[1,0]
	v_mul_f32_e32 v63, 0x3d372713, v56
	v_cndmask_b32_e64 v17, v65, v17, s[40:41]
	v_mul_f32_e32 v63, v63, v56
	v_mov_b32_e32 v65, v56
	v_lshlrev_b32_e32 v57, 16, v57
	v_fmac_f32_e32 v65, v63, v65
	v_mul_f32_e32 v63, 0x3f4c422a, v65
	v_mul_f32_e32 v65, 0x3d372713, v57
	v_mul_f32_e32 v65, v65, v57
	v_mov_b32_e32 v68, v57
	v_fmac_f32_e32 v68, v65, v68
	v_mul_f32_e32 v63, 0xc038aa3b, v63
	v_mul_f32_e32 v65, 0x3f4c422a, v68
	v_exp_f32_e32 v63, v63
	v_mul_f32_e32 v65, 0xc038aa3b, v65
	v_exp_f32_e32 v65, v65
	s_waitcnt vmcnt(3)
	v_lshlrev_b32_e32 v12, 16, v12
	v_add_f32_e32 v63, 1.0, v63
	v_cndmask_b32_e64 v16, v64, v16, s[0:1]
	v_rcp_f32_e32 v64, v63
	v_add_f32_e32 v63, 1.0, v65
	v_mul_f32_e32 v65, 0x3d372713, v12
	v_mul_f32_e32 v65, v65, v12
	v_mov_b32_e32 v68, v12
	v_fmac_f32_e32 v68, v65, v68
	v_mul_f32_e32 v65, 0x3f4c422a, v68
	s_waitcnt vmcnt(2)
	v_lshlrev_b32_e32 v13, 16, v13
	v_mul_f32_e32 v65, 0xc038aa3b, v65
	v_exp_f32_e32 v68, v65
	v_mul_f32_e32 v65, 0x3d372713, v13
	v_mul_f32_e32 v65, v65, v13
	v_mov_b32_e32 v69, v13
	v_fmac_f32_e32 v69, v65, v69
	v_mul_f32_e32 v65, 0x3f4c422a, v69
	v_mul_f32_e32 v65, 0xc038aa3b, v65
	v_exp_f32_e32 v69, v65
	v_rcp_f32_e32 v65, v63
	v_add_f32_e32 v63, 1.0, v68
	v_rcp_f32_e32 v68, v63
	v_add_f32_e32 v63, 1.0, v69
	v_rcp_f32_e32 v69, v63
	v_pk_mul_f32 v[56:57], v[64:65], v[56:57]
	v_pk_mul_f32 v[14:15], v[66:67], s[56:57] op_sel_hi:[1,0]
	v_pk_mul_f32 v[52:53], v[52:53], v[16:17]
	v_pk_mul_f32 v[64:65], v[68:69], v[12:13]
	v_cndmask_b32_e64 v15, v67, v15, s[42:43]
	v_pk_mul_f32 v[12:13], v[64:65], v[64:65]
	v_cndmask_b32_e32 v14, v66, v14, vcc
	v_pk_fma_f32 v[12:13], v[56:57], v[56:57], v[12:13]
	v_mov_b32_e32 v66, v12
	v_mov_b32_e32 v67, v13
	s_nop 0
	v_permlane32_swap_b32_e32 v66, v12
	v_permlane32_swap_b32_e32 v67, v13
	v_pk_mul_f32 v[50:51], v[50:51], v[14:15]
	v_pk_mul_f32 v[52:53], v[4:5], v[52:53] op_sel_hi:[0,1]
	v_pk_mul_f32 v[50:51], v[4:5], v[50:51] op_sel_hi:[0,1]
	v_bfe_u32 v63, v51, 16, 1
	s_waitcnt lgkmcnt(0)
	v_pk_add_f32 v[12:13], v[12:13], v[66:67]
	v_mov_b32_e32 v66, v12
	v_mov_b32_e32 v67, v13
	s_nop 0
	v_permlane16_swap_b32_e32 v66, v12
	v_permlane16_swap_b32_e32 v67, v13
	v_bfe_u32 v68, v50, 16, 1
	v_add3_u32 v68, v50, v68, s11
	v_add3_u32 v63, v51, v63, s11
	v_pk_mul_f32 v[14:15], v[58:59], v[14:15]
	s_waitcnt lgkmcnt(0)
	v_pk_add_f32 v[12:13], v[12:13], v[66:67]
	s_nop 1
	v_mov_b32_dpp v66, v12 row_ror:8 row_mask:0xf bank_mask:0xf
	v_mov_b32_dpp v67, v13 row_ror:8 row_mask:0xf bank_mask:0xf
	v_bfe_u32 v69, v53, 16, 1
	v_pk_mul_f32 v[14:15], v[0:1], v[14:15] op_sel_hi:[0,1]
	v_bfe_u32 v70, v52, 16, 1
	v_add3_u32 v69, v53, v69, s11
	s_waitcnt lgkmcnt(0)
	v_pk_add_f32 v[12:13], v[12:13], v[66:67]
	s_nop 1
	v_mov_b32_dpp v50, v12 row_shl:4 row_mask:0xf bank_mask:0x5
	s_nop 1
	v_mov_b32_dpp v50, v12 row_shr:4 row_mask:0xf bank_mask:0xa
	v_mov_b32_dpp v51, v13 row_shl:4 row_mask:0xf bank_mask:0x5
	s_nop 1
	v_mov_b32_dpp v51, v13 row_shr:4 row_mask:0xf bank_mask:0xa
	v_pk_mul_f32 v[16:17], v[60:61], v[16:17]
	v_bfe_u32 v53, v14, 16, 1
	v_add3_u32 v70, v52, v70, s11
	v_pk_mul_f32 v[16:17], v[0:1], v[16:17] op_sel_hi:[0,1]
	s_waitcnt lgkmcnt(0)
	v_pk_add_f32 v[12:13], v[12:13], v[50:51]
	s_nop 1
	v_mov_b32_dpp v50, v12 quad_perm:[2,3,0,1] row_mask:0xf bank_mask:0xf
	v_mov_b32_dpp v51, v13 quad_perm:[2,3,0,1] row_mask:0xf bank_mask:0xf
	v_bfe_u32 v52, v15, 16, 1
	v_add3_u32 v60, v14, v53, s11
	v_lshlrev_b32_e32 v14, 16, v55
	v_bfe_u32 v58, v17, 16, 1
	s_waitcnt lgkmcnt(0)
	v_pk_add_f32 v[12:13], v[12:13], v[50:51]
	s_nop 1
	v_mov_b32_dpp v50, v12 quad_perm:[1,0,3,2] row_mask:0xf bank_mask:0xf
	v_mov_b32_dpp v51, v13 quad_perm:[1,0,3,2] row_mask:0xf bank_mask:0xf
	v_add3_u32 v61, v15, v52, s11
	s_waitcnt vmcnt(1)
	v_lshlrev_b32_e32 v15, 16, v11
	v_mul_f32_e32 v11, 0x3d372713, v14
	v_add3_u32 v58, v17, v58, s11
	v_mul_f32_e32 v11, v11, v14
	v_mov_b32_e32 v17, v14
	v_fmac_f32_e32 v17, v11, v17
	v_mul_f32_e32 v11, 0x3f4c422a, v17
	v_mul_f32_e32 v17, 0x3d372713, v15
	s_waitcnt lgkmcnt(0)
	v_pk_add_f32 v[12:13], v[12:13], v[50:51]
	v_mul_f32_e32 v17, v17, v15
	v_mov_b32_e32 v50, v15
	v_fmac_f32_e32 v50, v17, v50
	v_mul_f32_e32 v11, 0xc038aa3b, v11
	v_mul_f32_e32 v17, 0x3f4c422a, v50
	v_exp_f32_e32 v11, v11
	v_mul_f32_e32 v17, 0xc038aa3b, v17
	v_exp_f32_e32 v17, v17
	v_bfe_u32 v59, v16, 16, 1
	v_pk_fma_f32 v[12:13], v[12:13], s[96:97], v[6:7] op_sel_hi:[1,0,0]
	v_lshlrev_b32_e32 v50, 16, v54
	v_add3_u32 v59, v16, v59, s11
	v_mul_f32_e32 v16, 0x4b800000, v12
	v_cmp_gt_f32_e32 vcc, s77, v12
	v_add_f32_e32 v11, 1.0, v11
	s_waitcnt vmcnt(0)
; DI float bf2f(bf16_t b) { return __uint_as_float(((unsigned)b) << 16); }
; DI bf16_t f2bf(float f) { unsigned u = __float_as_uint(f); u += 0x7fffu + ((u >> 16) & 1u); return (bf16_t)(u >> 16); }
; DI float wave_sum(float v) { for (int o = 32; o; o >>= 1) v += __shfl_xor(v, o); return v; }
; DI float geluf_(float x) { const float u = 0.7978845608028654f * (x + 0.044715f * x * x * x); return x * __builtin_amdgcn_rcpf(1.f + __builtin_amdgcn_exp2f(-2.f * LOG2E * u)); }
; DI int crow(int i, int h) { return (i & 3) + 8 * (i >> 2) + 4 * h; }
; DI void sg_item(int item, const bf16_t* proj, const bf16_t* sgw, const float* vng, const float* bs, bf16_t* obuf, unsigned char* smem, const int tid) {
;     ...
; #pragma unroll
;     for (int e = 0; e < 16; ++e) { const int tt = wv * 16 + e;
;         const float a0 = geluf_(va[e][0]), a1 = geluf_(va[e][1]);
;         const float ss = wave_sum(a0 * a0 + a1 * a1); const float rs = rsqrtf(ss * (1.f / 128.f) + NEPS);
;         vT[lane * 136 + tt] = f2bf(a0 * rs * g0); vT[(lane + 64) * 136 + tt] = f2bf(a1 * rs * g1); }
;     __syncthreads();
; #pragma unroll
;     for (int ci = 0; ci < 2; ++ci) { const int cb = 2 * (wv & 1) + ci; const int c = 32 * cb + r;
;         float uv[16];
; #pragma unroll
;         for (int i = 0; i < 16; ++i) uv[i] = bf2f(proj[(size_t)(t0 + 32 * tb + crow(i, h2)) * PLD + 2496 + g * 128 + c]);
	v_lshlrev_b32_e32 v51, 16, v10
	v_mul_f32_e32 v10, 0x3d372713, v50
	v_cndmask_b32_e32 v12, v12, v16, vcc
	v_rcp_f32_e32 v16, v11
	v_add_f32_e32 v11, 1.0, v17
	v_mul_f32_e32 v10, v10, v50
	v_mov_b32_e32 v17, v50
	v_fmac_f32_e32 v17, v10, v17
	v_mul_f32_e32 v10, 0x3f4c422a, v17
	v_mul_f32_e32 v17, 0x3d372713, v51
	v_mul_f32_e32 v17, v17, v51
	v_mov_b32_e32 v52, v51
	v_fmac_f32_e32 v52, v17, v52
	v_mul_f32_e32 v17, 0x3f4c422a, v52
	v_mul_f32_e32 v10, 0xc038aa3b, v10
	v_mul_f32_e32 v17, 0xc038aa3b, v17
	v_exp_f32_e32 v10, v10
	v_exp_f32_e32 v52, v17
	v_rcp_f32_e32 v17, v11
	v_cmp_gt_f32_e64 s[0:1], s77, v13
	v_add_f32_e32 v10, 1.0, v10
	v_add_f32_e32 v11, 1.0, v52
	v_rcp_f32_e32 v10, v10
	v_rcp_f32_e32 v11, v11
	v_pk_mul_f32 v[14:15], v[16:17], v[14:15]
	v_rsq_f32_e32 v12, v12
	v_pk_mul_f32 v[16:17], v[14:15], v[14:15]
	v_pk_mul_f32 v[50:51], v[10:11], v[50:51]
	v_mov_b32_e32 v53, v16
	v_pk_mul_f32 v[10:11], v[50:51], v[50:51]
	v_and_b32_e32 v126, 0x5f, v196
	v_mov_b32_e32 v52, v10
	v_mov_b32_e32 v16, v11
	v_pk_add_f32 v[10:11], v[52:53], v[16:17]
	v_mov_b32_e32 v17, v11
	v_mov_b32_e32 v16, v10
	s_nop 0
	v_permlane32_swap_b32_e32 v17, v11
	v_permlane32_swap_b32_e32 v16, v10
	v_mul_f32_e32 v52, 0x4b800000, v13
	v_cndmask_b32_e64 v13, v13, v52, s[0:1]
	v_rsq_f32_e32 v13, v13
	v_add_u32_e32 v127, 0, v198
	s_waitcnt lgkmcnt(0)
	v_pk_add_f32 v[10:11], v[10:11], v[16:17]
	v_mov_b32_e32 v17, v11
	v_mov_b32_e32 v16, v10
	s_nop 0
	v_permlane16_swap_b32_e32 v17, v11
	v_permlane16_swap_b32_e32 v16, v10
	v_pk_mul_f32 v[52:53], v[12:13], s[56:57] op_sel_hi:[1,0]
	s_waitcnt lgkmcnt(0)
	v_pk_add_f32 v[10:11], v[10:11], v[16:17]
	s_nop 1
	v_mov_b32_dpp v17, v11 row_ror:8 row_mask:0xf bank_mask:0xf
	v_mov_b32_dpp v16, v10 row_ror:8 row_mask:0xf bank_mask:0xf
	v_cndmask_b32_e64 v53, v13, v53, s[0:1]
	v_cndmask_b32_e32 v52, v12, v52, vcc
	v_pk_mul_f32 v[12:13], v[56:57], v[52:53]
	s_and_b32 s0, s14, 0x7ffffc
	v_pk_mul_f32 v[12:13], v[4:5], v[12:13] op_sel_hi:[0,1]
	v_and_b32_sdwa v54, v12, v241 dst_sel:DWORD dst_unused:UNUSED_PAD src0_sel:WORD_1 src1_sel:DWORD
	s_waitcnt lgkmcnt(0)
	v_pk_add_f32 v[16:17], v[10:11], v[16:17]
	v_add3_u32 v12, v12, v54, s11
	s_nop 1
	v_mov_b32_dpp v55, v17 row_shl:4 row_mask:0xf bank_mask:0x5
	s_nop 1
	v_mov_b32_dpp v55, v17 row_shr:4 row_mask:0xf bank_mask:0xa
	v_mov_b32_dpp v54, v16 row_shl:4 row_mask:0xf bank_mask:0x5
	s_nop 1
	v_mov_b32_dpp v54, v16 row_shr:4 row_mask:0xf bank_mask:0xa
	v_and_b32_sdwa v56, v13, v241 dst_sel:DWORD dst_unused:UNUSED_PAD src0_sel:WORD_1 src1_sel:DWORD
	v_add3_u32 v10, v13, v56, s11
	v_perm_b32 v12, v10, v12, s12
	v_perm_b32 v11, v63, v68, s12
	s_waitcnt lgkmcnt(0)
	v_pk_add_f32 v[16:17], v[16:17], v[54:55]
	s_nop 1
	v_mov_b32_dpp v55, v17 quad_perm:[2,3,0,1] row_mask:0xf bank_mask:0xf
	v_mov_b32_dpp v54, v16 quad_perm:[2,3,0,1] row_mask:0xf bank_mask:0xf
	v_perm_b32 v10, v69, v70, s12
	ds_write_b96 v9, v[10:12] offset:16
	v_pk_mul_f32 v[10:11], v[64:65], v[52:53]
	v_lshl_or_b32 v5, v5, 1, 30
	s_waitcnt lgkmcnt(1)
	v_pk_add_f32 v[16:17], v[16:17], v[54:55]
	s_nop 1
	v_mov_b32_dpp v53, v17 quad_perm:[1,0,3,2] row_mask:0xf bank_mask:0xf
	v_mov_b32_dpp v52, v16 quad_perm:[1,0,3,2] row_mask:0xf bank_mask:0xf
	v_pk_mul_f32 v[10:11], v[0:1], v[10:11] op_sel_hi:[0,1]
	v_and_b32_sdwa v12, v11, v241 dst_sel:DWORD dst_unused:UNUSED_PAD src0_sel:WORD_1 src1_sel:DWORD
	v_and_b32_sdwa v13, v10, v241 dst_sel:DWORD dst_unused:UNUSED_PAD src0_sel:WORD_1 src1_sel:DWORD
	v_add3_u32 v10, v10, v13, s11
	v_add3_u32 v11, v11, v12, s11
	v_perm_b32 v12, v11, v10, s12
	s_waitcnt lgkmcnt(0)
	v_pk_add_f32 v[10:11], v[16:17], v[52:53]
	v_add_u32_e32 v5, v8, v5
	v_pk_fma_f32 v[6:7], v[10:11], s[96:97], v[6:7] op_sel_hi:[1,0,0]
	v_perm_b32 v11, v61, v60, s12
	v_cmp_gt_f32_e32 vcc, s77, v7
	s_nop 1
	v_rsq_f32_e32 v7, v7
	v_perm_b32 v10, v58, v59, s12
	ds_write_b96 v9, v[10:12] offset:17424
	v_mul_f32_e32 v10, v14, v7
	v_mul_f32_e32 v10, v4, v10
	v_bfe_u32 v11, v10, 16, 1
	v_add3_u32 v10, v10, v11, s11
	ds_write_b16_d16_hi v9, v10 offset:28
	v_cmp_gt_f32_e32 vcc, s77, v6
	v_mul_f32_e32 v7, v15, v7
	v_mul_f32_e32 v7, v0, v7
	v_rsq_f32_e32 v6, v6
	v_bfe_u32 v10, v7, 16, 1
	v_add3_u32 v7, v7, v10, s11
	ds_write_b16_d16_hi v9, v7 offset:17436
	v_mul_f32_e32 v7, v50, v6
	v_mul_f32_e32 v4, v4, v7
	v_bfe_u32 v7, v4, 16, 1
	v_add3_u32 v4, v4, v7, s11
	ds_write_b16_d16_hi v5, v4
	v_mul_f32_e32 v4, v51, v6
	v_mul_f32_e32 v0, v0, v4
	v_bfe_u32 v4, v0, 16, 1
	v_add3_u32 v0, v0, v4, s11
	ds_write_b16_d16_hi v5, v0 offset:17408
	v_add_u32_e32 v0, s0, v62
	v_lshlrev_b32_e32 v50, 2, v180
	v_lshl_or_b32 v51, v0, 5, v50
	v_mad_i64_i32 v[4:5], s[0:1], v51, s3, v[2:3]
	v_lshl_add_u64 v[4:5], v[4:5], 0, s[4:5]
	v_lshlrev_b32_e32 v0, 1, v126
	v_or_b32_e32 v6, 1, v51
	v_lshl_add_u64 v[52:53], v[4:5], 0, v[0:1]
	v_mad_i64_i32 v[6:7], s[0:1], v6, s3, v[2:3]
	v_add_co_u32_e32 v4, vcc, s87, v52
	v_lshl_add_u64 v[6:7], v[6:7], 0, s[4:5]
	v_or_b32_e32 v8, 2, v51
	v_addc_co_u32_e32 v5, vcc, 0, v53, vcc
	v_lshl_add_u64 v[54:55], v[6:7], 0, v[0:1]
	v_mad_i64_i32 v[8:9], s[0:1], v8, s3, v[2:3]
	v_add_co_u32_e32 v6, vcc, s87, v54
	v_lshl_add_u64 v[8:9], v[8:9], 0, s[4:5]
	v_or_b32_e32 v10, 3, v51
	v_addc_co_u32_e32 v7, vcc, 0, v55, vcc
	v_lshl_add_u64 v[56:57], v[8:9], 0, v[0:1]
	v_mad_i64_i32 v[10:11], s[0:1], v10, s3, v[2:3]
	v_add_co_u32_e32 v8, vcc, s87, v56
	v_lshl_add_u64 v[10:11], v[10:11], 0, s[4:5]
	v_or_b32_e32 v12, 8, v51
	v_addc_co_u32_e32 v9, vcc, 0, v57, vcc
	v_lshl_add_u64 v[58:59], v[10:11], 0, v[0:1]
	v_mad_i64_i32 v[12:13], s[0:1], v12, s3, v[2:3]
	v_add_co_u32_e32 v10, vcc, s87, v58
	v_lshl_add_u64 v[12:13], v[12:13], 0, s[4:5]
	v_or_b32_e32 v14, 9, v51
	v_addc_co_u32_e32 v11, vcc, 0, v59, vcc
	v_lshl_add_u64 v[60:61], v[12:13], 0, v[0:1]
	v_mad_i64_i32 v[14:15], s[0:1], v14, s3, v[2:3]
	v_add_co_u32_e32 v12, vcc, s87, v60
	v_lshl_add_u64 v[14:15], v[14:15], 0, s[4:5]
	v_or_b32_e32 v16, 10, v51
	v_addc_co_u32_e32 v13, vcc, 0, v61, vcc
	v_lshl_add_u64 v[66:67], v[14:15], 0, v[0:1]
	v_mad_i64_i32 v[16:17], s[0:1], v16, s3, v[2:3]
	v_add_co_u32_e32 v14, vcc, s87, v66
	v_lshl_add_u64 v[16:17], v[16:17], 0, s[4:5]
	v_or_b32_e32 v63, 11, v51
	v_addc_co_u32_e32 v15, vcc, 0, v67, vcc
	v_lshl_add_u64 v[68:69], v[16:17], 0, v[0:1]
	v_mad_i64_i32 v[64:65], s[0:1], v63, s3, v[2:3]
	v_add_co_u32_e32 v16, vcc, s87, v68
	v_lshl_add_u64 v[64:65], v[64:65], 0, s[4:5]
	s_nop 0
	v_addc_co_u32_e32 v17, vcc, 0, v69, vcc
	v_lshl_add_u64 v[74:75], v[64:65], 0, v[0:1]
	v_add_co_u32_e32 v64, vcc, s87, v74
	s_waitcnt lgkmcnt(0)
	s_barrier
; DI float bf2f(bf16_t b) { return __uint_as_float(((unsigned)b) << 16); }
; DI int crow(int i, int h) { return (i & 3) + 8 * (i >> 2) + 4 * h; }
; #define MFMA32(a, b, c) __builtin_amdgcn_mfma_f32_32x32x16_bf16((a), (b), (c), 0, 0, 0)
; DI void sg_item(int item, const bf16_t* proj, const bf16_t* sgw, const float* vng, const float* bs, bf16_t* obuf, unsigned char* smem, const int tid) {
;     ...
;     for (int ci = 0; ci < 2; ++ci) { const int cb = 2 * (wv & 1) + ci; const int c = 32 * cb + r;
;         float uv[16];
; #pragma unroll
;         for (int i = 0; i < 16; ++i) uv[i] = bf2f(proj[(size_t)(t0 + 32 * tb + crow(i, h2)) * PLD + 2496 + g * 128 + c]);
;         f32x16 acc; for (int i = 0; i < 16; ++i) acc[i] = 0.f;
; #pragma unroll
;         for (int ks = 0; ks < 8; ++ks) if (ks < 2 * (tb + 1)) acc = MFMA32(wf[ks], *(const bf16x8*)(vT + (32 * cb + r) * 136 + 16 * ks + 8 * h2), acc);
	v_addc_co_u32_e32 v65, vcc, 0, v75, vcc
	global_load_ushort v94, v[4:5], off offset:896
	global_load_ushort v95, v[6:7], off offset:896
	global_load_ushort v96, v[8:9], off offset:896
	global_load_ushort v97, v[10:11], off offset:896
	global_load_ushort v124, v[12:13], off offset:896
	global_load_ushort v125, v[14:15], off offset:896
	global_load_ushort v128, v[16:17], off offset:896
	global_load_ushort v129, v[64:65], off offset:896
	v_or_b32_e32 v4, 16, v51
	v_mad_i64_i32 v[4:5], s[0:1], v4, s3, v[2:3]
	v_lshl_add_u64 v[4:5], v[4:5], 0, s[4:5]
	v_or_b32_e32 v6, 17, v51
	v_lshl_add_u64 v[76:77], v[4:5], 0, v[0:1]
	v_mad_i64_i32 v[6:7], s[0:1], v6, s3, v[2:3]
	v_add_co_u32_e32 v4, vcc, s87, v76
	v_lshl_add_u64 v[6:7], v[6:7], 0, s[4:5]
	v_or_b32_e32 v8, 18, v51
	v_addc_co_u32_e32 v5, vcc, 0, v77, vcc
	v_lshl_add_u64 v[80:81], v[6:7], 0, v[0:1]
	v_mad_i64_i32 v[8:9], s[0:1], v8, s3, v[2:3]
	v_add_co_u32_e32 v6, vcc, s87, v80
	v_lshl_add_u64 v[8:9], v[8:9], 0, s[4:5]
	v_or_b32_e32 v10, 19, v51
	v_addc_co_u32_e32 v7, vcc, 0, v81, vcc
	v_lshl_add_u64 v[82:83], v[8:9], 0, v[0:1]
	v_mad_i64_i32 v[10:11], s[0:1], v10, s3, v[2:3]
	v_add_co_u32_e32 v8, vcc, s87, v82
	v_lshl_add_u64 v[10:11], v[10:11], 0, s[4:5]
	v_or_b32_e32 v12, 24, v51
	v_addc_co_u32_e32 v9, vcc, 0, v83, vcc
	v_lshl_add_u64 v[84:85], v[10:11], 0, v[0:1]
	v_mad_i64_i32 v[12:13], s[0:1], v12, s3, v[2:3]
	v_add_co_u32_e32 v10, vcc, s87, v84
	v_lshl_add_u64 v[12:13], v[12:13], 0, s[4:5]
	v_or_b32_e32 v14, 25, v51
	v_addc_co_u32_e32 v11, vcc, 0, v85, vcc
	v_lshl_add_u64 v[86:87], v[12:13], 0, v[0:1]
	v_mad_i64_i32 v[14:15], s[0:1], v14, s3, v[2:3]
	v_add_co_u32_e32 v12, vcc, s87, v86
	v_lshl_add_u64 v[14:15], v[14:15], 0, s[4:5]
	v_or_b32_e32 v16, 26, v51
	v_addc_co_u32_e32 v13, vcc, 0, v87, vcc
	v_lshl_add_u64 v[88:89], v[14:15], 0, v[0:1]
	v_mad_i64_i32 v[16:17], s[0:1], v16, s3, v[2:3]
	v_add_co_u32_e32 v14, vcc, s87, v88
	v_lshl_add_u64 v[16:17], v[16:17], 0, s[4:5]
	v_or_b32_e32 v51, 27, v51
	v_addc_co_u32_e32 v15, vcc, 0, v89, vcc
	v_lshl_add_u64 v[90:91], v[16:17], 0, v[0:1]
	v_mad_i64_i32 v[2:3], s[0:1], v51, s3, v[2:3]
	v_add_co_u32_e32 v16, vcc, s87, v90
	v_lshl_add_u64 v[2:3], v[2:3], 0, s[4:5]
	s_nop 0
	v_addc_co_u32_e32 v17, vcc, 0, v91, vcc
	v_lshl_add_u64 v[92:93], v[2:3], 0, v[0:1]
	v_add_co_u32_e32 v2, vcc, 0x1000, v92
	v_mul_u32_u24_e32 v51, 0x110, v126
	s_nop 0
	v_addc_co_u32_e32 v3, vcc, 0, v93, vcc
	global_load_ushort v130, v[4:5], off offset:896
	global_load_ushort v131, v[6:7], off offset:896
	global_load_ushort v132, v[8:9], off offset:896
	global_load_ushort v133, v[10:11], off offset:896
	global_load_ushort v134, v[12:13], off offset:896
	global_load_ushort v135, v[14:15], off offset:896
	global_load_ushort v136, v[16:17], off offset:896
	global_load_ushort v137, v[2:3], off offset:896
	v_cmp_lt_i32_e32 vcc, -1, v62
	v_mov_b32_e32 v2, v1
	v_mov_b32_e32 v3, v1
	v_mov_b32_e32 v4, v1
	v_mov_b32_e32 v5, v1
	v_mov_b32_e32 v6, v1
	v_mov_b32_e32 v7, v1
	v_mov_b32_e32 v8, v1
	v_mov_b32_e32 v9, v1
	v_mov_b32_e32 v10, v1
	v_mov_b32_e32 v11, v1
	v_mov_b32_e32 v12, v1
	v_mov_b32_e32 v13, v1
	v_mov_b32_e32 v14, v1
	v_mov_b32_e32 v15, v1
	v_mov_b32_e32 v16, v1
	v_mov_b32_e32 v17, v1
	v_add_u32_e32 v51, v127, v51
	s_and_saveexec_b64 s[0:1], vcc
	s_cbranch_execnz .LBB0_266
	s_or_b64 exec, exec, s[0:1]
	s_and_saveexec_b64 s[0:1], vcc
	s_cbranch_execnz .LBB0_267

.LBB0_316:
	s_andn2_b64 vcc, exec, s[0:1]
	s_cbranch_vccnz .LBB0_313
	s_lshl_b64 s[0:1], s[4:5], 6
	v_lshl_add_u64 v[38:39], v[8:9], 0, s[0:1]
	v_mov_b64_e32 v[40:41], s[30:31]
	v_mad_u64_u32 v[40:41], s[0:1], v38, s3, v[40:41]
	v_mad_u32_u24 v41, v39, s3, v41
	s_lshl_b32 s0, s34, 1
	s_mov_b32 s1, s5
	v_lshlrev_b64 v[44:45], 12, v[38:39]
	v_lshl_add_u64 v[38:39], v[40:41], 0, s[0:1]
	v_lshlrev_b32_e32 v0, 1, v6
	v_lshl_add_u64 v[100:101], v[38:39], 0, v[0:1]
	v_lshl_add_u64 v[70:71], v[4:5], 0, v[44:45]
	global_load_dword v102, v[100:101], off offset:3072
	global_load_dword v99, v[70:71], off
	v_or_b32_e32 v38, 0x1000, v44
	v_mov_b32_e32 v39, v45
	v_lshl_add_u64 v[68:69], v[4:5], 0, v[38:39]
	global_load_dword v107, v[68:69], off
	s_movk_i32 s0, 0x3000
	v_add_co_u32_e32 v38, vcc, s0, v100
	s_movk_i32 s0, 0x5000
	s_nop 0
	v_addc_co_u32_e32 v39, vcc, 0, v101, vcc
	global_load_dword v109, v[38:39], off offset:896
	v_or_b32_e32 v38, 0x2000, v44
	v_mov_b32_e32 v39, v45
	v_lshl_add_u64 v[66:67], v[4:5], 0, v[38:39]
	v_add_co_u32_e32 v38, vcc, s0, v100
	global_load_dword v97, v[66:67], off
	s_nop 0
	v_addc_co_u32_e32 v39, vcc, 0, v101, vcc
	global_load_dword v98, v[38:39], off offset:2816
	v_or_b32_e32 v38, 0x3000, v44
	v_mov_b32_e32 v39, v45
	s_mov_b32 s0, 0x8000
	v_lshl_add_u64 v[64:65], v[4:5], 0, v[38:39]
	v_add_co_u32_e32 v38, vcc, s0, v100
	global_load_dword v95, v[64:65], off
	s_nop 0
	v_addc_co_u32_e32 v39, vcc, 0, v101, vcc
	global_load_dword v96, v[38:39], off offset:640
	v_or_b32_e32 v38, 0x4000, v44
	v_mov_b32_e32 v39, v45
	s_mov_b32 s0, 0xa000
	v_lshl_add_u64 v[62:63], v[4:5], 0, v[38:39]
	v_add_co_u32_e32 v38, vcc, s0, v100
	global_load_dword v93, v[62:63], off
	s_nop 0
	v_addc_co_u32_e32 v39, vcc, 0, v101, vcc
	global_load_dword v94, v[38:39], off offset:2560
	v_or_b32_e32 v38, 0x5000, v44
	v_mov_b32_e32 v39, v45
	s_mov_b32 s0, 0xd000
	v_lshl_add_u64 v[60:61], v[4:5], 0, v[38:39]
	v_add_co_u32_e32 v38, vcc, s0, v100
	s_mov_b32 s0, 0xf000
	s_nop 0
	v_addc_co_u32_e32 v39, vcc, 0, v101, vcc
	global_load_dword v92, v[38:39], off offset:384
	v_or_b32_e32 v38, 0x6000, v44
	v_mov_b32_e32 v39, v45
	v_lshl_add_u64 v[58:59], v[4:5], 0, v[38:39]
	v_add_co_u32_e32 v38, vcc, s0, v100
	s_mov_b32 s0, 0x12000
	s_nop 0
	v_addc_co_u32_e32 v39, vcc, 0, v101, vcc
	global_load_dword v90, v[38:39], off offset:2304
	v_or_b32_e32 v38, 0x7000, v44
	v_mov_b32_e32 v39, v45
	v_lshl_add_u64 v[56:57], v[4:5], 0, v[38:39]
	v_add_co_u32_e32 v38, vcc, s0, v100
	s_mov_b32 s0, 0x14000
	s_nop 0
	v_addc_co_u32_e32 v39, vcc, 0, v101, vcc
	global_load_dword v88, v[38:39], off offset:128
	v_or_b32_e32 v38, 0x8000, v44
	v_mov_b32_e32 v39, v45
	v_lshl_add_u64 v[54:55], v[4:5], 0, v[38:39]
	v_add_co_u32_e32 v38, vcc, s0, v100
	s_mov_b32 s0, 0x16000
	s_nop 0
	v_addc_co_u32_e32 v39, vcc, 0, v101, vcc
	global_load_dword v86, v[38:39], off offset:2048
	v_or_b32_e32 v38, 0x9000, v44
	v_mov_b32_e32 v39, v45
	v_lshl_add_u64 v[52:53], v[4:5], 0, v[38:39]
	v_add_co_u32_e32 v38, vcc, s0, v100
	s_mov_b32 s0, 0x19000
	s_nop 0
	v_addc_co_u32_e32 v39, vcc, 0, v101, vcc
	global_load_dword v84, v[38:39], off offset:3968
	v_or_b32_e32 v38, 0xa000, v44
	v_mov_b32_e32 v39, v45
	v_lshl_add_u64 v[50:51], v[4:5], 0, v[38:39]
	v_add_co_u32_e32 v38, vcc, s0, v100
	s_mov_b32 s0, 0x1b000
	s_nop 0
	v_addc_co_u32_e32 v39, vcc, 0, v101, vcc
	global_load_dword v82, v[38:39], off offset:1792
	v_or_b32_e32 v38, 0xb000, v44
	v_mov_b32_e32 v39, v45
	v_lshl_add_u64 v[48:49], v[4:5], 0, v[38:39]
	v_add_co_u32_e32 v38, vcc, s0, v100
	s_mov_b32 s0, 0x1e000
	s_nop 0
	v_addc_co_u32_e32 v39, vcc, 0, v101, vcc
	global_load_dword v80, v[38:39], off offset:3712
	v_or_b32_e32 v38, 0xc000, v44
	v_mov_b32_e32 v39, v45
	v_lshl_add_u64 v[46:47], v[4:5], 0, v[38:39]
	v_add_co_u32_e32 v38, vcc, s0, v100
	s_mov_b32 s0, 0x20000
	s_nop 0
	v_addc_co_u32_e32 v39, vcc, 0, v101, vcc
	global_load_dword v78, v[38:39], off offset:1536
	v_or_b32_e32 v38, 0xd000, v44
	v_mov_b32_e32 v39, v45
	v_lshl_add_u64 v[42:43], v[4:5], 0, v[38:39]
	v_add_co_u32_e32 v38, vcc, s0, v100
	s_mov_b32 s0, 0x23000
	s_nop 0
	v_addc_co_u32_e32 v39, vcc, 0, v101, vcc
	global_load_dword v76, v[38:39], off offset:3456
	v_or_b32_e32 v38, 0xe000, v44
	v_mov_b32_e32 v39, v45
	v_lshl_add_u64 v[40:41], v[4:5], 0, v[38:39]
	v_add_co_u32_e32 v38, vcc, s0, v100
	v_or_b32_e32 v44, 0xf000, v44
	s_nop 0
	v_addc_co_u32_e32 v39, vcc, 0, v101, vcc
	s_mov_b32 s0, 0x25000
	global_load_dword v74, v[38:39], off offset:1280
	v_lshl_add_u64 v[38:39], v[4:5], 0, v[44:45]
	v_add_co_u32_e32 v44, vcc, s0, v100
	s_waitcnt vmcnt(18)
	v_lshlrev_b32_e32 v100, 16, v99
	v_addc_co_u32_e32 v45, vcc, 0, v101, vcc
	global_load_dword v72, v[44:45], off offset:3200
	v_lshlrev_b32_e32 v44, 16, v102
	v_and_b32_e32 v101, 0xffff0000, v99
	v_mul_f32_e32 v99, 0xbfb8aa3b, v44
	v_exp_f32_e32 v99, v99
	v_and_b32_e32 v45, 0xffff0000, v102
	s_waitcnt vmcnt(18)
	v_lshlrev_b32_e32 v106, 16, v107
	v_and_b32_e32 v107, 0xffff0000, v107
	v_add_f32_e32 v99, 1.0, v99
	v_rcp_f32_e32 v104, v99
	v_mul_f32_e32 v99, 0xbfb8aa3b, v45
	v_exp_f32_e32 v99, v99
	v_pk_mul_f32 v[102:103], v[100:101], v[100:101]
	s_waitcnt vmcnt(17)
	v_lshlrev_b32_e32 v108, 16, v109
	v_mov_b32_e32 v111, v102
	v_add_f32_e32 v99, 1.0, v99
	v_rcp_f32_e32 v105, v99
	v_and_b32_e32 v109, 0xffff0000, v109
	global_load_dword v91, v[60:61], off
	global_load_dword v89, v[58:59], off
	global_load_dword v87, v[56:57], off
	global_load_dword v85, v[54:55], off
	global_load_dword v83, v[52:53], off
	global_load_dword v81, v[50:51], off
	global_load_dword v79, v[48:49], off
	global_load_dword v77, v[46:47], off
	v_pk_mul_f32 v[104:105], v[104:105], v[44:45]
	v_pk_mul_f32 v[44:45], v[106:107], v[106:107]
	global_load_dword v75, v[42:43], off
	global_load_dword v73, v[40:41], off
	global_load_dword v0, v[38:39], off
	v_mov_b32_e32 v110, v44
	v_mov_b32_e32 v102, v45
	v_pk_add_f32 v[44:45], v[110:111], v[102:103]
	v_mov_b32_e32 v103, v45
	v_mov_b32_e32 v102, v44
	s_nop 0
	v_permlane32_swap_b32_e32 v103, v45
	v_permlane32_swap_b32_e32 v102, v44
	s_waitcnt lgkmcnt(0)
	v_pk_add_f32 v[44:45], v[44:45], v[102:103]
	v_mov_b32_e32 v103, v45
	v_mov_b32_e32 v102, v44
	s_nop 0
	v_permlane16_swap_b32_e32 v103, v45
	v_permlane16_swap_b32_e32 v102, v44
	s_waitcnt lgkmcnt(0)
	v_pk_add_f32 v[44:45], v[44:45], v[102:103]
	s_nop 1
	v_add_f32_dpp v45, v45, v45 row_ror:8 row_mask:0xf bank_mask:0xf
	v_add_f32_dpp v44, v44, v44 row_ror:8 row_mask:0xf bank_mask:0xf
	s_waitcnt lgkmcnt(0)
	s_nop 1
	v_add_f32_dpp v45, v45, v45 row_ror:4 row_mask:0xf bank_mask:0xf
	v_add_f32_dpp v44, v44, v44 row_ror:4 row_mask:0xf bank_mask:0xf
	s_waitcnt lgkmcnt(0)
	s_nop 1
	v_add_f32_dpp v45, v45, v45 quad_perm:[2,3,0,1] row_mask:0xf bank_mask:0xf
	v_add_f32_dpp v44, v44, v44 quad_perm:[2,3,0,1] row_mask:0xf bank_mask:0xf
	s_waitcnt lgkmcnt(0)
	s_nop 1
	v_add_f32_dpp v103, v45, v45 quad_perm:[1,0,3,2] row_mask:0xf bank_mask:0xf
	v_add_f32_dpp v102, v44, v44 quad_perm:[1,0,3,2] row_mask:0xf bank_mask:0xf
	s_waitcnt lgkmcnt(0)
	v_mov_b64_e32 v[44:45], s[72:73]
	v_pk_fma_f32 v[102:103], v[102:103], s[96:97], v[44:45] op_sel_hi:[1,0,0]
	s_nop 0
	v_cmp_gt_f32_e64 s[0:1], s77, v103
	v_cmp_gt_f32_e32 vcc, s77, v102
	s_nop 0
	v_rsq_f32_e32 v99, v103
	s_nop 0
	v_mov_b32_e32 v110, v99
	v_pk_mul_f32 v[100:101], v[110:111], v[100:101] op_sel_hi:[0,1]
	v_pk_mul_f32 v[100:101], v[2:3], v[100:101]
	s_waitcnt vmcnt(24)
	v_and_b32_e32 v103, 0xffff0000, v96
	v_pk_mul_f32 v[100:101], v[104:105], v[100:101]
	s_nop 0
	v_cvt_pk_bf16_f32 v99, v100, v101
	global_store_dword v[70:71], v99, off
	v_rsq_f32_e32 v70, v102
	v_mul_f32_e32 v99, 0xbfb8aa3b, v109
	v_exp_f32_e32 v99, v99
	v_lshlrev_b32_e32 v102, 16, v96
	v_mul_f32_e32 v71, 0xbfb8aa3b, v108
	v_exp_f32_e32 v71, v71
	v_add_f32_e32 v99, 1.0, v99
	v_rcp_f32_e32 v101, v99
	v_add_f32_e32 v71, 1.0, v71
	v_rcp_f32_e32 v100, v71
	v_pk_mul_f32 v[70:71], v[70:71], v[106:107] op_sel_hi:[0,1]
	v_pk_mul_f32 v[70:71], v[2:3], v[70:71]
	v_pk_mul_f32 v[100:101], v[100:101], v[108:109]
	s_nop 0
	v_pk_mul_f32 v[70:71], v[100:101], v[70:71]
	s_nop 0
	v_cvt_pk_bf16_f32 v70, v70, v71
	global_store_dword v[68:69], v70, off
	v_lshlrev_b32_e32 v70, 16, v98
	v_lshlrev_b32_e32 v68, 16, v97
	v_and_b32_e32 v69, 0xffff0000, v97
	v_mul_f32_e32 v97, 0xbfb8aa3b, v70
	v_exp_f32_e32 v97, v97
	v_and_b32_e32 v71, 0xffff0000, v98
	v_pk_mul_f32 v[98:99], v[68:69], v[68:69]
	v_add_f32_e32 v97, 1.0, v97
	v_rcp_f32_e32 v100, v97
	v_mul_f32_e32 v97, 0xbfb8aa3b, v71
	v_exp_f32_e32 v97, v97
	v_mov_b32_e32 v105, v98
	v_add_f32_e32 v97, 1.0, v97
	v_rcp_f32_e32 v101, v97
	s_nop 0
	v_pk_mul_f32 v[70:71], v[100:101], v[70:71]
	v_lshlrev_b32_e32 v100, 16, v95
	v_and_b32_e32 v101, 0xffff0000, v95
	v_pk_mul_f32 v[96:97], v[100:101], v[100:101]
	s_nop 0
	v_mov_b32_e32 v104, v96
	v_mov_b32_e32 v98, v97
	v_pk_add_f32 v[96:97], v[104:105], v[98:99]
	v_mov_b32_e32 v99, v97
	v_mov_b32_e32 v98, v96
	s_nop 0
	v_permlane32_swap_b32_e32 v99, v97
	v_permlane32_swap_b32_e32 v98, v96
	s_waitcnt lgkmcnt(0)
	v_pk_add_f32 v[96:97], v[96:97], v[98:99]
	v_mov_b32_e32 v99, v97
	v_mov_b32_e32 v98, v96
	s_nop 0
	v_permlane16_swap_b32_e32 v99, v97
	v_permlane16_swap_b32_e32 v98, v96
	s_waitcnt lgkmcnt(0)
	v_pk_add_f32 v[96:97], v[96:97], v[98:99]
	s_nop 1
	v_add_f32_dpp v97, v97, v97 row_ror:8 row_mask:0xf bank_mask:0xf
	v_add_f32_dpp v96, v96, v96 row_ror:8 row_mask:0xf bank_mask:0xf
	s_waitcnt lgkmcnt(0)
	s_nop 1
	v_add_f32_dpp v97, v97, v97 row_ror:4 row_mask:0xf bank_mask:0xf
	v_add_f32_dpp v96, v96, v96 row_ror:4 row_mask:0xf bank_mask:0xf
	s_waitcnt lgkmcnt(0)
	s_nop 1
	v_add_f32_dpp v97, v97, v97 quad_perm:[2,3,0,1] row_mask:0xf bank_mask:0xf
	v_add_f32_dpp v96, v96, v96 quad_perm:[2,3,0,1] row_mask:0xf bank_mask:0xf
	s_waitcnt lgkmcnt(0)
	s_nop 1
	v_add_f32_dpp v97, v97, v97 quad_perm:[1,0,3,2] row_mask:0xf bank_mask:0xf
	v_add_f32_dpp v96, v96, v96 quad_perm:[1,0,3,2] row_mask:0xf bank_mask:0xf
	s_waitcnt lgkmcnt(0)
	s_nop 0
	v_pk_fma_f32 v[96:97], v[96:97], s[96:97], v[44:45] op_sel_hi:[1,0,0]
	s_nop 0
	v_cmp_gt_f32_e64 s[0:1], s77, v97
	v_cmp_gt_f32_e32 vcc, s77, v96
	s_nop 0
	v_rsq_f32_e32 v95, v97
	s_nop 0
	v_mov_b32_e32 v98, v95
	v_pk_mul_f32 v[68:69], v[98:99], v[68:69] op_sel_hi:[0,1]
	v_pk_mul_f32 v[68:69], v[2:3], v[68:69]
	s_waitcnt vmcnt(23)
	v_and_b32_e32 v95, 0xffff0000, v92
	v_pk_mul_f32 v[68:69], v[70:71], v[68:69]
	s_nop 0
	v_cvt_pk_bf16_f32 v68, v68, v69
	global_store_dword v[66:67], v68, off
	v_rsq_f32_e32 v66, v96
	v_mul_f32_e32 v69, 0xbfb8aa3b, v103
	v_exp_f32_e32 v69, v69
	v_mul_f32_e32 v67, 0xbfb8aa3b, v102
	v_exp_f32_e32 v67, v67
	v_add_f32_e32 v69, 1.0, v69
	v_rcp_f32_e32 v69, v69
	v_add_f32_e32 v67, 1.0, v67
	v_rcp_f32_e32 v68, v67
	v_pk_mul_f32 v[66:67], v[66:67], v[100:101] op_sel_hi:[0,1]
	v_pk_mul_f32 v[66:67], v[2:3], v[66:67]
	v_pk_mul_f32 v[68:69], v[68:69], v[102:103]
	s_nop 0
	v_pk_mul_f32 v[66:67], v[68:69], v[66:67]
	s_nop 0
	v_cvt_pk_bf16_f32 v66, v66, v67
	global_store_dword v[64:65], v66, off
	v_lshlrev_b32_e32 v66, 16, v94
	v_and_b32_e32 v67, 0xffff0000, v94
	v_mul_f32_e32 v70, 0xbfb8aa3b, v66
	v_mul_f32_e32 v71, 0xbfb8aa3b, v67
	v_exp_f32_e32 v70, v70
	v_exp_f32_e32 v71, v71
	v_lshlrev_b32_e32 v64, 16, v93
	v_and_b32_e32 v65, 0xffff0000, v93
	v_add_f32_e32 v70, 1.0, v70
	v_add_f32_e32 v71, 1.0, v71
	v_rcp_f32_e32 v70, v70
	v_rcp_f32_e32 v71, v71
	v_pk_mul_f32 v[68:69], v[64:65], v[64:65]
	v_lshlrev_b32_e32 v94, 16, v92
	v_mov_b32_e32 v97, v68
	v_pk_mul_f32 v[66:67], v[70:71], v[66:67]
	s_waitcnt vmcnt(14)
	v_lshlrev_b32_e32 v70, 16, v91
	v_and_b32_e32 v71, 0xffff0000, v91
	v_pk_mul_f32 v[92:93], v[70:71], v[70:71]
	s_nop 0
	v_mov_b32_e32 v96, v92
	v_mov_b32_e32 v68, v93
	v_pk_add_f32 v[68:69], v[96:97], v[68:69]
	v_mov_b32_e32 v93, v69
	v_mov_b32_e32 v92, v68
	s_nop 0
	v_permlane32_swap_b32_e32 v93, v69
	v_permlane32_swap_b32_e32 v92, v68
	s_waitcnt lgkmcnt(0)
	v_pk_add_f32 v[68:69], v[68:69], v[92:93]
	v_mov_b32_e32 v93, v69
	v_mov_b32_e32 v92, v68
	s_nop 0
	v_permlane16_swap_b32_e32 v93, v69
	v_permlane16_swap_b32_e32 v92, v68
	s_waitcnt lgkmcnt(0)
	v_pk_add_f32 v[68:69], v[68:69], v[92:93]
	s_nop 1
	v_add_f32_dpp v69, v69, v69 row_ror:8 row_mask:0xf bank_mask:0xf
	v_add_f32_dpp v68, v68, v68 row_ror:8 row_mask:0xf bank_mask:0xf
	s_waitcnt lgkmcnt(0)
	s_nop 1
	v_add_f32_dpp v69, v69, v69 row_ror:4 row_mask:0xf bank_mask:0xf
	v_add_f32_dpp v68, v68, v68 row_ror:4 row_mask:0xf bank_mask:0xf
	s_waitcnt lgkmcnt(0)
	s_nop 1
	v_add_f32_dpp v69, v69, v69 quad_perm:[2,3,0,1] row_mask:0xf bank_mask:0xf
	v_add_f32_dpp v68, v68, v68 quad_perm:[2,3,0,1] row_mask:0xf bank_mask:0xf
	s_waitcnt lgkmcnt(0)
	s_nop 1
	v_add_f32_dpp v69, v69, v69 quad_perm:[1,0,3,2] row_mask:0xf bank_mask:0xf
	v_add_f32_dpp v68, v68, v68 quad_perm:[1,0,3,2] row_mask:0xf bank_mask:0xf
	s_waitcnt lgkmcnt(0)
	s_nop 0
	v_pk_fma_f32 v[68:69], v[68:69], s[96:97], v[44:45] op_sel_hi:[1,0,0]
	s_nop 0
	v_cmp_gt_f32_e64 s[0:1], s77, v69
	v_cmp_gt_f32_e32 vcc, s77, v68
	s_nop 0
	v_rsq_f32_e32 v69, v69
	s_nop 0
	v_mov_b32_e32 v92, v69
	v_pk_mul_f32 v[64:65], v[92:93], v[64:65] op_sel_hi:[0,1]
	v_pk_mul_f32 v[64:65], v[2:3], v[64:65]
	v_and_b32_e32 v69, 0xffff0000, v88
	v_pk_mul_f32 v[64:65], v[66:67], v[64:65]
	s_nop 0
	v_cvt_pk_bf16_f32 v64, v64, v65
	global_store_dword v[62:63], v64, off
	v_rsq_f32_e32 v62, v68
	v_mul_f32_e32 v65, 0xbfb8aa3b, v95
	v_exp_f32_e32 v65, v65
	v_lshlrev_b32_e32 v68, 16, v88
	v_mul_f32_e32 v63, 0xbfb8aa3b, v94
	v_exp_f32_e32 v63, v63
	v_add_f32_e32 v65, 1.0, v65
	v_rcp_f32_e32 v65, v65
	v_add_f32_e32 v63, 1.0, v63
	v_rcp_f32_e32 v64, v63
	v_pk_mul_f32 v[62:63], v[62:63], v[70:71] op_sel_hi:[0,1]
	v_pk_mul_f32 v[62:63], v[2:3], v[62:63]
	v_pk_mul_f32 v[64:65], v[64:65], v[94:95]
	s_nop 0
	v_pk_mul_f32 v[62:63], v[64:65], v[62:63]
	s_nop 0
	v_cvt_pk_bf16_f32 v62, v62, v63
	global_store_dword v[60:61], v62, off
	v_lshlrev_b32_e32 v62, 16, v90
	v_and_b32_e32 v63, 0xffff0000, v90
	v_mul_f32_e32 v66, 0xbfb8aa3b, v62
	v_mul_f32_e32 v67, 0xbfb8aa3b, v63
	v_exp_f32_e32 v66, v66
	v_exp_f32_e32 v67, v67
	s_waitcnt vmcnt(15)
	v_lshlrev_b32_e32 v60, 16, v89
	v_and_b32_e32 v61, 0xffff0000, v89
	v_add_f32_e32 v66, 1.0, v66
	v_add_f32_e32 v67, 1.0, v67
	v_rcp_f32_e32 v66, v66
	v_rcp_f32_e32 v67, v67
	v_pk_mul_f32 v[64:65], v[60:61], v[60:61]
	v_pk_mul_f32 v[62:63], v[66:67], v[62:63]
	s_waitcnt vmcnt(14)
	v_lshlrev_b32_e32 v66, 16, v87
	v_and_b32_e32 v67, 0xffff0000, v87
	v_pk_mul_f32 v[70:71], v[66:67], v[66:67]
	v_mov_b32_e32 v89, v64
	v_mov_b32_e32 v88, v70
	v_mov_b32_e32 v64, v71
	v_pk_add_f32 v[64:65], v[88:89], v[64:65]
	v_mov_b32_e32 v71, v65
	v_mov_b32_e32 v70, v64
	s_nop 0
	v_permlane32_swap_b32_e32 v71, v65
	v_permlane32_swap_b32_e32 v70, v64
	s_waitcnt lgkmcnt(0)
	v_pk_add_f32 v[64:65], v[64:65], v[70:71]
	v_mov_b32_e32 v71, v65
	v_mov_b32_e32 v70, v64
	s_nop 0
	v_permlane16_swap_b32_e32 v71, v65
	v_permlane16_swap_b32_e32 v70, v64
	s_waitcnt lgkmcnt(0)
	v_pk_add_f32 v[64:65], v[64:65], v[70:71]
	s_nop 1
	v_add_f32_dpp v65, v65, v65 row_ror:8 row_mask:0xf bank_mask:0xf
	v_add_f32_dpp v64, v64, v64 row_ror:8 row_mask:0xf bank_mask:0xf
	s_waitcnt lgkmcnt(0)
	s_nop 1
	v_add_f32_dpp v65, v65, v65 row_ror:4 row_mask:0xf bank_mask:0xf
	v_add_f32_dpp v64, v64, v64 row_ror:4 row_mask:0xf bank_mask:0xf
	s_waitcnt lgkmcnt(0)
	s_nop 1
	v_add_f32_dpp v65, v65, v65 quad_perm:[2,3,0,1] row_mask:0xf bank_mask:0xf
	v_add_f32_dpp v64, v64, v64 quad_perm:[2,3,0,1] row_mask:0xf bank_mask:0xf
	s_waitcnt lgkmcnt(0)
	s_nop 1
	v_add_f32_dpp v65, v65, v65 quad_perm:[1,0,3,2] row_mask:0xf bank_mask:0xf
	v_add_f32_dpp v64, v64, v64 quad_perm:[1,0,3,2] row_mask:0xf bank_mask:0xf
	s_waitcnt lgkmcnt(0)
	s_nop 0
	v_pk_fma_f32 v[64:65], v[64:65], s[96:97], v[44:45] op_sel_hi:[1,0,0]
	s_nop 0
	v_cmp_gt_f32_e64 s[0:1], s77, v65
	v_cmp_gt_f32_e32 vcc, s77, v64
	s_nop 0
	v_rsq_f32_e32 v65, v65
	s_nop 0
	v_mov_b32_e32 v70, v65
	v_pk_mul_f32 v[60:61], v[70:71], v[60:61] op_sel_hi:[0,1]
	v_pk_mul_f32 v[60:61], v[2:3], v[60:61]
	v_and_b32_e32 v65, 0xffff0000, v84
	v_pk_mul_f32 v[60:61], v[62:63], v[60:61]
	s_nop 0
	v_cvt_pk_bf16_f32 v60, v60, v61
	global_store_dword v[58:59], v60, off
	v_rsq_f32_e32 v58, v64
	v_mul_f32_e32 v61, 0xbfb8aa3b, v69
	v_exp_f32_e32 v61, v61
	v_lshlrev_b32_e32 v64, 16, v84
	v_mul_f32_e32 v59, 0xbfb8aa3b, v68
	v_exp_f32_e32 v59, v59
	v_add_f32_e32 v61, 1.0, v61
	v_rcp_f32_e32 v61, v61
	v_add_f32_e32 v59, 1.0, v59
	v_rcp_f32_e32 v60, v59
	v_pk_mul_f32 v[58:59], v[58:59], v[66:67] op_sel_hi:[0,1]
	v_pk_mul_f32 v[58:59], v[2:3], v[58:59]
	v_pk_mul_f32 v[60:61], v[60:61], v[68:69]
	s_nop 0
	v_pk_mul_f32 v[58:59], v[60:61], v[58:59]
	s_nop 0
	v_cvt_pk_bf16_f32 v58, v58, v59
	global_store_dword v[56:57], v58, off
	v_lshlrev_b32_e32 v58, 16, v86
	v_and_b32_e32 v59, 0xffff0000, v86
	v_mul_f32_e32 v62, 0xbfb8aa3b, v58
	v_mul_f32_e32 v63, 0xbfb8aa3b, v59
	v_exp_f32_e32 v62, v62
	v_exp_f32_e32 v63, v63
	s_waitcnt vmcnt(15)
	v_lshlrev_b32_e32 v56, 16, v85
	v_and_b32_e32 v57, 0xffff0000, v85
	v_add_f32_e32 v62, 1.0, v62
	v_add_f32_e32 v63, 1.0, v63
	v_rcp_f32_e32 v62, v62
	v_rcp_f32_e32 v63, v63
	v_pk_mul_f32 v[60:61], v[56:57], v[56:57]
	v_pk_mul_f32 v[58:59], v[62:63], v[58:59]
	s_waitcnt vmcnt(14)
	v_lshlrev_b32_e32 v62, 16, v83
	v_and_b32_e32 v63, 0xffff0000, v83
	v_pk_mul_f32 v[66:67], v[62:63], v[62:63]
	v_mov_b32_e32 v69, v60
	v_mov_b32_e32 v68, v66
	v_mov_b32_e32 v60, v67
	v_pk_add_f32 v[60:61], v[68:69], v[60:61]
	v_mov_b32_e32 v67, v61
	v_mov_b32_e32 v66, v60
	s_nop 0
	v_permlane32_swap_b32_e32 v67, v61
	v_permlane32_swap_b32_e32 v66, v60
	s_waitcnt lgkmcnt(0)
	v_pk_add_f32 v[60:61], v[60:61], v[66:67]
	v_mov_b32_e32 v67, v61
	v_mov_b32_e32 v66, v60
	s_nop 0
	v_permlane16_swap_b32_e32 v67, v61
	v_permlane16_swap_b32_e32 v66, v60
	s_waitcnt lgkmcnt(0)
	v_pk_add_f32 v[60:61], v[60:61], v[66:67]
	s_nop 1
	v_add_f32_dpp v61, v61, v61 row_ror:8 row_mask:0xf bank_mask:0xf
	v_add_f32_dpp v60, v60, v60 row_ror:8 row_mask:0xf bank_mask:0xf
	s_waitcnt lgkmcnt(0)
	s_nop 1
	v_add_f32_dpp v61, v61, v61 row_ror:4 row_mask:0xf bank_mask:0xf
	v_add_f32_dpp v60, v60, v60 row_ror:4 row_mask:0xf bank_mask:0xf
	s_waitcnt lgkmcnt(0)
	s_nop 1
	v_add_f32_dpp v61, v61, v61 quad_perm:[2,3,0,1] row_mask:0xf bank_mask:0xf
	v_add_f32_dpp v60, v60, v60 quad_perm:[2,3,0,1] row_mask:0xf bank_mask:0xf
	s_waitcnt lgkmcnt(0)
	s_nop 1
	v_add_f32_dpp v61, v61, v61 quad_perm:[1,0,3,2] row_mask:0xf bank_mask:0xf
	v_add_f32_dpp v60, v60, v60 quad_perm:[1,0,3,2] row_mask:0xf bank_mask:0xf
	s_waitcnt lgkmcnt(0)
	s_nop 0
	v_pk_fma_f32 v[60:61], v[60:61], s[96:97], v[44:45] op_sel_hi:[1,0,0]
	s_nop 0
	v_cmp_gt_f32_e64 s[0:1], s77, v61
	v_cmp_gt_f32_e32 vcc, s77, v60
	s_nop 0
	v_rsq_f32_e32 v61, v61
	s_nop 0
	v_mov_b32_e32 v66, v61
	v_pk_mul_f32 v[56:57], v[66:67], v[56:57] op_sel_hi:[0,1]
	v_pk_mul_f32 v[56:57], v[2:3], v[56:57]
	v_and_b32_e32 v61, 0xffff0000, v80
	v_pk_mul_f32 v[56:57], v[58:59], v[56:57]
	s_nop 0
	v_cvt_pk_bf16_f32 v56, v56, v57
	global_store_dword v[54:55], v56, off
	v_rsq_f32_e32 v54, v60
	v_mul_f32_e32 v57, 0xbfb8aa3b, v65
	v_exp_f32_e32 v57, v57
	v_lshlrev_b32_e32 v60, 16, v80
	v_mul_f32_e32 v55, 0xbfb8aa3b, v64
	v_exp_f32_e32 v55, v55
	v_add_f32_e32 v57, 1.0, v57
	v_rcp_f32_e32 v57, v57
	v_add_f32_e32 v55, 1.0, v55
	v_rcp_f32_e32 v56, v55
	v_pk_mul_f32 v[54:55], v[54:55], v[62:63] op_sel_hi:[0,1]
	v_pk_mul_f32 v[54:55], v[2:3], v[54:55]
	v_pk_mul_f32 v[56:57], v[56:57], v[64:65]
	s_nop 0
	v_pk_mul_f32 v[54:55], v[56:57], v[54:55]
	s_nop 0
	v_cvt_pk_bf16_f32 v54, v54, v55
	global_store_dword v[52:53], v54, off
	v_lshlrev_b32_e32 v54, 16, v82
	v_and_b32_e32 v55, 0xffff0000, v82
	v_mul_f32_e32 v58, 0xbfb8aa3b, v54
	v_mul_f32_e32 v59, 0xbfb8aa3b, v55
	v_exp_f32_e32 v58, v58
	v_exp_f32_e32 v59, v59
	s_waitcnt vmcnt(15)
	v_lshlrev_b32_e32 v52, 16, v81
	v_and_b32_e32 v53, 0xffff0000, v81
	v_add_f32_e32 v58, 1.0, v58
	v_add_f32_e32 v59, 1.0, v59
	v_rcp_f32_e32 v58, v58
	v_rcp_f32_e32 v59, v59
	v_pk_mul_f32 v[56:57], v[52:53], v[52:53]
	v_pk_mul_f32 v[54:55], v[58:59], v[54:55]
	s_waitcnt vmcnt(14)
	v_lshlrev_b32_e32 v58, 16, v79
	v_and_b32_e32 v59, 0xffff0000, v79
	v_pk_mul_f32 v[62:63], v[58:59], v[58:59]
	v_mov_b32_e32 v65, v56
	v_mov_b32_e32 v64, v62
	v_mov_b32_e32 v56, v63
	v_pk_add_f32 v[56:57], v[64:65], v[56:57]
	v_mov_b32_e32 v63, v57
	v_mov_b32_e32 v62, v56
	s_nop 0
	v_permlane32_swap_b32_e32 v63, v57
	v_permlane32_swap_b32_e32 v62, v56
	s_waitcnt lgkmcnt(0)
	v_pk_add_f32 v[56:57], v[56:57], v[62:63]
	v_mov_b32_e32 v63, v57
	v_mov_b32_e32 v62, v56
	s_nop 0
	v_permlane16_swap_b32_e32 v63, v57
	v_permlane16_swap_b32_e32 v62, v56
	s_waitcnt lgkmcnt(0)
	v_pk_add_f32 v[56:57], v[56:57], v[62:63]
	s_nop 1
	v_add_f32_dpp v57, v57, v57 row_ror:8 row_mask:0xf bank_mask:0xf
	v_add_f32_dpp v56, v56, v56 row_ror:8 row_mask:0xf bank_mask:0xf
	s_waitcnt lgkmcnt(0)
	s_nop 1
	v_add_f32_dpp v57, v57, v57 row_ror:4 row_mask:0xf bank_mask:0xf
	v_add_f32_dpp v56, v56, v56 row_ror:4 row_mask:0xf bank_mask:0xf
	s_waitcnt lgkmcnt(0)
	s_nop 1
	v_add_f32_dpp v57, v57, v57 quad_perm:[2,3,0,1] row_mask:0xf bank_mask:0xf
	v_add_f32_dpp v56, v56, v56 quad_perm:[2,3,0,1] row_mask:0xf bank_mask:0xf
	s_waitcnt lgkmcnt(0)
	s_nop 1
	v_add_f32_dpp v57, v57, v57 quad_perm:[1,0,3,2] row_mask:0xf bank_mask:0xf
	v_add_f32_dpp v56, v56, v56 quad_perm:[1,0,3,2] row_mask:0xf bank_mask:0xf
	s_waitcnt lgkmcnt(0)
	s_nop 0
	v_pk_fma_f32 v[56:57], v[56:57], s[96:97], v[44:45] op_sel_hi:[1,0,0]
	s_nop 0
	v_cmp_gt_f32_e64 s[0:1], s77, v57
	v_cmp_gt_f32_e32 vcc, s77, v56
	s_nop 0
	v_rsq_f32_e32 v57, v57
	s_nop 0
	v_mov_b32_e32 v62, v57
	v_pk_mul_f32 v[52:53], v[62:63], v[52:53] op_sel_hi:[0,1]
	v_pk_mul_f32 v[52:53], v[2:3], v[52:53]
	v_and_b32_e32 v57, 0xffff0000, v76
	v_pk_mul_f32 v[52:53], v[54:55], v[52:53]
	s_nop 0
	v_cvt_pk_bf16_f32 v52, v52, v53
	global_store_dword v[50:51], v52, off
	v_rsq_f32_e32 v50, v56
	v_mul_f32_e32 v53, 0xbfb8aa3b, v61
	v_exp_f32_e32 v53, v53
	v_lshlrev_b32_e32 v56, 16, v76
	v_mul_f32_e32 v51, 0xbfb8aa3b, v60
	v_exp_f32_e32 v51, v51
	v_add_f32_e32 v53, 1.0, v53
	v_rcp_f32_e32 v53, v53
	v_add_f32_e32 v51, 1.0, v51
	v_rcp_f32_e32 v52, v51
	v_pk_mul_f32 v[50:51], v[50:51], v[58:59] op_sel_hi:[0,1]
	v_pk_mul_f32 v[50:51], v[2:3], v[50:51]
	v_pk_mul_f32 v[52:53], v[52:53], v[60:61]
	s_nop 0
	v_pk_mul_f32 v[50:51], v[52:53], v[50:51]
	s_nop 0
	v_cvt_pk_bf16_f32 v50, v50, v51
	global_store_dword v[48:49], v50, off
	v_lshlrev_b32_e32 v50, 16, v78
	v_and_b32_e32 v51, 0xffff0000, v78
	v_mul_f32_e32 v54, 0xbfb8aa3b, v50
	v_mul_f32_e32 v55, 0xbfb8aa3b, v51
	v_exp_f32_e32 v54, v54
	v_exp_f32_e32 v55, v55
	s_waitcnt vmcnt(15)
	v_lshlrev_b32_e32 v48, 16, v77
	v_and_b32_e32 v49, 0xffff0000, v77
	v_add_f32_e32 v54, 1.0, v54
	v_add_f32_e32 v55, 1.0, v55
	v_rcp_f32_e32 v54, v54
	v_rcp_f32_e32 v55, v55
	v_pk_mul_f32 v[52:53], v[48:49], v[48:49]
	v_pk_mul_f32 v[50:51], v[54:55], v[50:51]
	s_waitcnt vmcnt(14)
	v_lshlrev_b32_e32 v54, 16, v75
	v_and_b32_e32 v55, 0xffff0000, v75
	v_pk_mul_f32 v[58:59], v[54:55], v[54:55]
	v_mov_b32_e32 v61, v52
	v_mov_b32_e32 v60, v58
	v_mov_b32_e32 v52, v59
	v_pk_add_f32 v[52:53], v[60:61], v[52:53]
	v_mov_b32_e32 v59, v53
	v_mov_b32_e32 v58, v52
	s_nop 0
	v_permlane32_swap_b32_e32 v59, v53
	v_permlane32_swap_b32_e32 v58, v52
	s_waitcnt lgkmcnt(0)
	v_pk_add_f32 v[52:53], v[52:53], v[58:59]
	v_mov_b32_e32 v59, v53
	v_mov_b32_e32 v58, v52
	s_nop 0
	v_permlane16_swap_b32_e32 v59, v53
	v_permlane16_swap_b32_e32 v58, v52
	s_waitcnt lgkmcnt(0)
	v_pk_add_f32 v[52:53], v[52:53], v[58:59]
	s_nop 1
	v_add_f32_dpp v53, v53, v53 row_ror:8 row_mask:0xf bank_mask:0xf
	v_add_f32_dpp v52, v52, v52 row_ror:8 row_mask:0xf bank_mask:0xf
	s_waitcnt lgkmcnt(0)
	s_nop 1
	v_add_f32_dpp v53, v53, v53 row_ror:4 row_mask:0xf bank_mask:0xf
	v_add_f32_dpp v52, v52, v52 row_ror:4 row_mask:0xf bank_mask:0xf
	s_waitcnt lgkmcnt(0)
	s_nop 1
	v_add_f32_dpp v53, v53, v53 quad_perm:[2,3,0,1] row_mask:0xf bank_mask:0xf
	v_add_f32_dpp v52, v52, v52 quad_perm:[2,3,0,1] row_mask:0xf bank_mask:0xf
	s_waitcnt lgkmcnt(0)
	s_nop 1
	v_add_f32_dpp v53, v53, v53 quad_perm:[1,0,3,2] row_mask:0xf bank_mask:0xf
	v_add_f32_dpp v52, v52, v52 quad_perm:[1,0,3,2] row_mask:0xf bank_mask:0xf
	s_waitcnt lgkmcnt(0)
	s_nop 0
	v_pk_fma_f32 v[52:53], v[52:53], s[96:97], v[44:45] op_sel_hi:[1,0,0]
	s_nop 0
	v_cmp_gt_f32_e64 s[0:1], s77, v53
	v_cmp_gt_f32_e32 vcc, s77, v52
	s_nop 0
	v_rsq_f32_e32 v53, v53
	s_nop 0
	v_mov_b32_e32 v58, v53
	v_pk_mul_f32 v[48:49], v[58:59], v[48:49] op_sel_hi:[0,1]
	v_pk_mul_f32 v[48:49], v[2:3], v[48:49]
	v_and_b32_e32 v53, 0xffff0000, v72
	v_pk_mul_f32 v[48:49], v[50:51], v[48:49]
	s_nop 0
	v_cvt_pk_bf16_f32 v48, v48, v49
	global_store_dword v[46:47], v48, off
	v_rsq_f32_e32 v46, v52
	v_mul_f32_e32 v49, 0xbfb8aa3b, v57
	v_exp_f32_e32 v49, v49
	v_lshlrev_b32_e32 v52, 16, v72
	v_mul_f32_e32 v47, 0xbfb8aa3b, v56
	v_exp_f32_e32 v47, v47
	v_add_f32_e32 v49, 1.0, v49
	v_rcp_f32_e32 v49, v49
	v_add_f32_e32 v47, 1.0, v47
	v_rcp_f32_e32 v48, v47
	v_pk_mul_f32 v[46:47], v[46:47], v[54:55] op_sel_hi:[0,1]
	v_pk_mul_f32 v[46:47], v[2:3], v[46:47]
	v_pk_mul_f32 v[48:49], v[48:49], v[56:57]
	s_nop 0
	v_pk_mul_f32 v[46:47], v[48:49], v[46:47]
	s_nop 0
	v_cvt_pk_bf16_f32 v46, v46, v47
	global_store_dword v[42:43], v46, off
	v_lshlrev_b32_e32 v46, 16, v74
	v_and_b32_e32 v47, 0xffff0000, v74
	v_mul_f32_e32 v50, 0xbfb8aa3b, v46
	v_mul_f32_e32 v51, 0xbfb8aa3b, v47
	v_exp_f32_e32 v50, v50
	v_exp_f32_e32 v51, v51
	s_waitcnt vmcnt(15)
	v_lshlrev_b32_e32 v42, 16, v73
	v_and_b32_e32 v43, 0xffff0000, v73
	v_add_f32_e32 v50, 1.0, v50
	v_add_f32_e32 v51, 1.0, v51
	v_rcp_f32_e32 v50, v50
	v_rcp_f32_e32 v51, v51
	v_pk_mul_f32 v[48:49], v[42:43], v[42:43]
	v_pk_mul_f32 v[46:47], v[50:51], v[46:47]
	s_waitcnt vmcnt(14)
	v_lshlrev_b32_e32 v50, 16, v0
	v_and_b32_e32 v51, 0xffff0000, v0
	v_pk_mul_f32 v[54:55], v[50:51], v[50:51]
	v_mov_b32_e32 v57, v48
	v_mov_b32_e32 v56, v54
	v_mov_b32_e32 v48, v55
	v_pk_add_f32 v[48:49], v[56:57], v[48:49]
	v_mov_b32_e32 v55, v49
	v_mov_b32_e32 v54, v48
	s_nop 0
	v_permlane32_swap_b32_e32 v55, v49
	v_permlane32_swap_b32_e32 v54, v48
	s_waitcnt lgkmcnt(0)
	v_pk_add_f32 v[48:49], v[48:49], v[54:55]
	v_mov_b32_e32 v55, v49
	v_mov_b32_e32 v54, v48
	s_nop 0
	v_permlane16_swap_b32_e32 v55, v49
	v_permlane16_swap_b32_e32 v54, v48
	s_waitcnt lgkmcnt(0)
	v_pk_add_f32 v[48:49], v[48:49], v[54:55]
	s_nop 1
	v_add_f32_dpp v49, v49, v49 row_ror:8 row_mask:0xf bank_mask:0xf
	v_add_f32_dpp v48, v48, v48 row_ror:8 row_mask:0xf bank_mask:0xf
	s_waitcnt lgkmcnt(0)
	s_nop 1
	v_add_f32_dpp v49, v49, v49 row_ror:4 row_mask:0xf bank_mask:0xf
	v_add_f32_dpp v48, v48, v48 row_ror:4 row_mask:0xf bank_mask:0xf
	s_waitcnt lgkmcnt(0)
	s_nop 1
	v_add_f32_dpp v49, v49, v49 quad_perm:[2,3,0,1] row_mask:0xf bank_mask:0xf
	v_add_f32_dpp v48, v48, v48 quad_perm:[2,3,0,1] row_mask:0xf bank_mask:0xf
	s_waitcnt lgkmcnt(0)
	s_nop 1
	v_add_f32_dpp v49, v49, v49 quad_perm:[1,0,3,2] row_mask:0xf bank_mask:0xf
	v_add_f32_dpp v48, v48, v48 quad_perm:[1,0,3,2] row_mask:0xf bank_mask:0xf
	s_waitcnt lgkmcnt(0)
	s_nop 0
	v_pk_fma_f32 v[44:45], v[48:49], s[96:97], v[44:45] op_sel_hi:[1,0,0]
	s_nop 0
	v_cmp_gt_f32_e64 s[0:1], s77, v45
	v_cmp_gt_f32_e32 vcc, s77, v44
	s_nop 0
	v_rsq_f32_e32 v0, v45
	s_nop 0
	v_pk_mul_f32 v[42:43], v[0:1], v[42:43] op_sel_hi:[0,1]
	v_pk_mul_f32 v[42:43], v[2:3], v[42:43]
	s_nop 0
	v_pk_mul_f32 v[42:43], v[46:47], v[42:43]
	s_nop 0
	v_cvt_pk_bf16_f32 v0, v42, v43
	global_store_dword v[40:41], v0, off
	v_rsq_f32_e32 v0, v44
	s_nop 0
	v_mul_f32_e32 v40, 0xbfb8aa3b, v52
	v_pk_mul_f32 v[42:43], v[0:1], v[50:51] op_sel_hi:[0,1]
	v_mul_f32_e32 v0, 0xbfb8aa3b, v53
	v_exp_f32_e32 v40, v40
	v_exp_f32_e32 v0, v0
	v_pk_mul_f32 v[42:43], v[2:3], v[42:43]
	v_add_f32_e32 v40, 1.0, v40
	v_add_f32_e32 v0, 1.0, v0
	v_rcp_f32_e32 v40, v40
	v_rcp_f32_e32 v41, v0
	s_nop 0
	v_pk_mul_f32 v[40:41], v[40:41], v[52:53]
	s_nop 0
	v_pk_mul_f32 v[40:41], v[40:41], v[42:43]
	s_nop 0
	v_cvt_pk_bf16_f32 v0, v40, v41
	global_store_dword v[38:39], v0, off
	s_branch .LBB0_313

; DI bf16_t f2bf(float f) { unsigned u = __float_as_uint(f); u += 0x7fffu + ((u >> 16) & 1u); return (bf16_t)(u >> 16); }
; DI float wave_sum(float v) { for (int o = 32; o; o >>= 1) v += __shfl_xor(v, o); return v; }
; DI void run_phase(const Params& p, int ph, unsigned char* smem, const int tid, const int rep) {
;     ...
;             for (int u = 0; u < 2; ++u) { const int t = t0 + u;
;                 const float ang = (float)ps[u] * invf; float sn, cs; sincosf(ang, &sn, &cs);
;                 const float kr = krv[u];
; #pragma unroll
;                 for (int h = 0; h < 4; ++h) {
;                     { const float a0 = qa[u][h][0], a1 = qa[u][h][1], a2 = qa[u][h][2];
;                       const float rs = rsqrtf(wave_sum(a0 * a0 + a1 * a1 + a2 * a2) * (1.f / 192.f) + NEPS) * (0.07216878364870322f * LOG2E);
;                       const float y2 = a2 * rs * gq2; const float oth = __shfl_xor(y2, 32);
;                       const float rot = (lane < 32) ? (y2 * cs - oth * sn) : (y2 * cs + oth * sn);
;                       bf16_t* qo = mlaq + (size_t)t * 768 + h * 192; qo[lane] = f2bf(a0 * rs * gq0); qo[lane + 64] = f2bf(a1 * rs * gq1); qo[lane + 128] = f2bf(rot); }
;                     { const float a0 = ka[u][h][0], a1 = ka[u][h][1];
;                       const float rs = rsqrtf(wave_sum(a0 * a0 + a1 * a1 + kr * kr) * (1.f / 192.f) + NEPS);
;                       const float y2 = kr * rs * gk2; const float oth = __shfl_xor(y2, 32);
;                       const float rot = (lane < 32) ? (y2 * cs - oth * sn) : (y2 * cs + oth * sn);
;                       bf16_t* ko = mlak + (size_t)t * 768 + h * 192; ko[lane] = f2bf(a0 * rs * gk0); ko[lane + 64] = f2bf(a1 * rs * gk1); ko[lane + 128] = f2bf(rot); }
.LBB0_331:
	s_or_b64 exec, exec, s[0:1]
	v_mul_f32_e32 v26, v24, v24
	v_fmamk_f32 v27, v26, 0xb94c1982, v249
	v_fmaak_f32 v27, v26, v27, 0xbe2aaa9d
	v_mul_f32_e32 v27, v26, v27
	v_fmac_f32_e32 v24, v24, v27
	v_fmamk_f32 v27, v26, 0x37d75334, v223
	v_fmaak_f32 v27, v26, v27, 0x3d2aabf7
	v_fmaak_f32 v27, v26, v27, 0xbf000004
	v_fma_f32 v26, v26, v27, 1.0
	v_lshlrev_b32_e32 v27, 30, v25
	v_and_b32_e32 v25, 1, v25
	v_cmp_eq_u32_e32 vcc, 0, v25
	s_brev_b32 s0, 1
	s_waitcnt vmcnt(41)
	v_lshlrev_b32_e32 v19, 16, v58
	v_cndmask_b32_e32 v25, v26, v24, vcc
	v_xor_b32_e32 v24, 0x80000000, v24
	v_cndmask_b32_e32 v24, v24, v26, vcc
	v_lshlrev_b32_e32 v18, 16, v51
	s_waitcnt vmcnt(39)
	v_lshlrev_b32_e32 v33, 16, v53
	v_lshlrev_b32_e32 v32, 16, v50
	v_xor_b32_e32 v17, v17, v16
	v_bitop3_b32 v24, v24, v27, s0 bitop3:0x78
	s_movk_i32 s0, 0x1f8
	v_lshlrev_b32_e32 v70, 16, v57
	s_waitcnt vmcnt(38)
	v_lshlrev_b32_e32 v30, 16, v55
	s_waitcnt vmcnt(35)
	v_lshlrev_b32_e32 v28, 16, v54
	s_waitcnt vmcnt(25)
	v_lshlrev_b32_e32 v13, 16, v61
	v_lshlrev_b32_e32 v12, 16, v49
	v_and_b32_e32 v34, 0x80000000, v27
	v_xor_b32_e32 v17, v17, v25
	v_cmp_class_f32_e64 vcc, v16, s0
	v_pk_mul_f32 v[26:27], v[18:19], v[18:19]
	v_pk_mul_f32 v[54:55], v[32:33], v[32:33]
	v_lshlrev_b32_e32 v11, 16, v52
	s_waitcnt vmcnt(24)
	v_lshlrev_b32_e32 v10, 16, v56
	v_xor_b32_e32 v17, v17, v34
	v_cndmask_b32_e32 v34, v224, v24, vcc
	v_pk_mul_f32 v[24:25], v[12:13], v[12:13]
	v_mul_f32_e32 v53, v70, v70
	v_mov_b32_e32 v56, v54
	v_mov_b32_e32 v57, v26
	v_mov_b32_e32 v52, v55
	v_pk_add_f32 v[52:53], v[56:57], v[52:53]
	v_mov_b32_e32 v26, v24
	v_pk_add_f32 v[26:27], v[26:27], v[52:53]
	v_mov_b32_e32 v53, v27
	v_mov_b32_e32 v52, v26
	s_nop 0
	v_permlane32_swap_b32_e32 v53, v27
	v_permlane32_swap_b32_e32 v52, v26
	s_mov_b32 s4, 0x3baaaaab
	v_cndmask_b32_e32 v35, v224, v17, vcc
	v_mad_i64_i32 v[16:17], s[0:1], v3, s7, v[6:7]
	s_waitcnt lgkmcnt(0)
	v_pk_add_f32 v[26:27], v[26:27], v[52:53]
	v_mov_b32_e32 v53, v27
	v_mov_b32_e32 v52, v26
	s_nop 0
	v_permlane16_swap_b32_e32 v53, v27
	v_permlane16_swap_b32_e32 v52, v26
	v_lshlrev_b32_e32 v31, 16, v63
	v_lshlrev_b32_e32 v29, 16, v59
	v_lshlrev_b32_e32 v51, 16, v62
	v_pk_mul_f32 v[54:55], v[28:29], v[28:29]
	s_waitcnt lgkmcnt(0)
	v_pk_add_f32 v[26:27], v[26:27], v[52:53]
	s_nop 1
	v_mov_b32_dpp v53, v27 row_ror:8 row_mask:0xf bank_mask:0xf
	v_mov_b32_dpp v52, v26 row_ror:8 row_mask:0xf bank_mask:0xf
	v_mov_b32_e32 v56, v54
	v_lshlrev_b32_e32 v23, 16, v66
	v_lshlrev_b32_e32 v22, 16, v60
	v_lshlrev_b32_e32 v21, 16, v67
	s_waitcnt lgkmcnt(0)
	v_pk_add_f32 v[26:27], v[26:27], v[52:53]
	s_nop 1
	v_mov_b32_dpp v53, v27 row_shl:4 row_mask:0xf bank_mask:0x5
	s_nop 1
	v_mov_b32_dpp v53, v27 row_shr:4 row_mask:0xf bank_mask:0xa
	v_mov_b32_dpp v52, v26 row_shl:4 row_mask:0xf bank_mask:0x5
	s_nop 1
	v_mov_b32_dpp v52, v26 row_shr:4 row_mask:0xf bank_mask:0xa
	v_lshlrev_b32_e32 v20, 16, v64
	v_lshlrev_b32_e32 v50, 16, v65
	v_lshlrev_b32_e32 v15, 16, v69
	v_lshlrev_b32_e32 v14, 16, v68
	s_waitcnt lgkmcnt(0)
	v_pk_add_f32 v[26:27], v[26:27], v[52:53]
	s_nop 1
	v_mov_b32_dpp v53, v27 quad_perm:[2,3,0,1] row_mask:0xf bank_mask:0xf
	v_mov_b32_dpp v52, v26 quad_perm:[2,3,0,1] row_mask:0xf bank_mask:0xf
	v_add_u32_e32 v2, s17, v2
	s_waitcnt lgkmcnt(0)
	v_pk_add_f32 v[26:27], v[26:27], v[52:53]
	s_nop 1
	v_add_f32_dpp v53, v27, v27 quad_perm:[1,0,3,2] row_mask:0xf bank_mask:0xf
	v_add_f32_dpp v52, v26, v26 quad_perm:[1,0,3,2] row_mask:0xf bank_mask:0xf
	s_waitcnt lgkmcnt(0)
	v_mov_b64_e32 v[26:27], s[72:73]
	v_pk_fma_f32 v[52:53], v[52:53], s[4:5], v[26:27] op_sel_hi:[1,0,0]
	s_nop 0
	v_cmp_gt_f32_e64 s[0:1], s77, v53
	v_cmp_gt_f32_e32 vcc, s77, v52
	s_nop 0
	v_rsq_f32_e32 v49, v53
	s_nop 0
	v_mul_f32_e32 v49, 0x3dd53b94, v49
	v_mul_f32_e32 v19, v49, v19
	v_mul_f32_e32 v19, v41, v19
	ds_bpermute_b32 v53, v43, v19
	v_mul_f32_e32 v18, v49, v18
	v_mul_f32_e32 v18, v36, v18
	s_waitcnt lgkmcnt(0)
	v_mul_f32_e32 v53, v35, v53
	v_cndmask_b32_e64 v53, v53, -v53, s[38:39]
	v_fmac_f32_e32 v53, v34, v19
	v_bfe_u32 v19, v18, 16, 1
	v_add3_u32 v18, v18, v19, s11
	global_store_short_d16_hi v[16:17], v18, off
	v_mul_f32_e32 v18, v49, v70
	v_mul_f32_e32 v18, v37, v18
	v_bfe_u32 v19, v18, 16, 1
	v_add3_u32 v18, v18, v19, s11
	global_store_short_d16_hi v[16:17], v18, off offset:128
	v_bfe_u32 v18, v53, 16, 1
	v_add3_u32 v18, v53, v18, s11
	global_store_short_d16_hi v[16:17], v18, off offset:256
	v_rsq_f32_e32 v18, v52
	v_mul_f32_e32 v53, v51, v51
	v_mov_b32_e32 v49, v18
	v_mul_f32_e32 v18, v49, v12
	v_mul_f32_e32 v18, v40, v18
	ds_bpermute_b32 v19, v43, v18
	s_waitcnt lgkmcnt(0)
	v_mul_f32_e32 v19, v35, v19
	v_cndmask_b32_e64 v52, v19, -v19, s[38:39]
	v_fmac_f32_e32 v52, v34, v18
	v_mul_f32_e32 v18, v49, v32
	v_mul_f32_e32 v18, v38, v18
	v_bfe_u32 v19, v18, 16, 1
	v_add3_u32 v32, v18, v19, s11
	v_mad_i64_i32 v[18:19], s[0:1], v3, s7, v[8:9]
	v_mul_f32_e32 v3, v49, v33
	v_mul_f32_e32 v3, v39, v3
	global_store_short_d16_hi v[18:19], v32, off
	v_bfe_u32 v32, v3, 16, 1
	v_add3_u32 v3, v3, v32, s11
	global_store_short_d16_hi v[18:19], v3, off offset:128
	v_bfe_u32 v3, v52, 16, 1
	v_pk_mul_f32 v[32:33], v[30:31], v[30:31]
	v_add3_u32 v3, v52, v3, s11
	v_mov_b32_e32 v57, v32
	v_mov_b32_e32 v52, v55
	v_pk_add_f32 v[52:53], v[56:57], v[52:53]
	v_mov_b32_e32 v32, v24
	v_pk_add_f32 v[32:33], v[32:33], v[52:53]
	v_mov_b32_e32 v53, v33
	v_mov_b32_e32 v52, v32
	s_nop 0
	v_permlane32_swap_b32_e32 v53, v33
	v_permlane32_swap_b32_e32 v52, v32
	global_store_short_d16_hi v[18:19], v3, off offset:256
	s_waitcnt lgkmcnt(0)
; DI bf16_t f2bf(float f) { unsigned u = __float_as_uint(f); u += 0x7fffu + ((u >> 16) & 1u); return (bf16_t)(u >> 16); }
; DI float wave_sum(float v) { for (int o = 32; o; o >>= 1) v += __shfl_xor(v, o); return v; }
; DI void run_phase(const Params& p, int ph, unsigned char* smem, const int tid, const int rep) {
;     ...
;                 for (int h = 0; h < 4; ++h) {
;                     { const float a0 = qa[u][h][0], a1 = qa[u][h][1], a2 = qa[u][h][2];
;                       const float rs = rsqrtf(wave_sum(a0 * a0 + a1 * a1 + a2 * a2) * (1.f / 192.f) + NEPS) * (0.07216878364870322f * LOG2E);
;                       const float y2 = a2 * rs * gq2; const float oth = __shfl_xor(y2, 32);
;                       const float rot = (lane < 32) ? (y2 * cs - oth * sn) : (y2 * cs + oth * sn);
;                       bf16_t* qo = mlaq + (size_t)t * 768 + h * 192; qo[lane] = f2bf(a0 * rs * gq0); qo[lane + 64] = f2bf(a1 * rs * gq1); qo[lane + 128] = f2bf(rot); }
;                     { const float a0 = ka[u][h][0], a1 = ka[u][h][1];
;                       const float rs = rsqrtf(wave_sum(a0 * a0 + a1 * a1 + kr * kr) * (1.f / 192.f) + NEPS);
;                       const float y2 = kr * rs * gk2; const float oth = __shfl_xor(y2, 32);
;                       const float rot = (lane < 32) ? (y2 * cs - oth * sn) : (y2 * cs + oth * sn);
;                       bf16_t* ko = mlak + (size_t)t * 768 + h * 192; ko[lane] = f2bf(a0 * rs * gk0); ko[lane + 64] = f2bf(a1 * rs * gk1); ko[lane + 128] = f2bf(rot); }
	v_pk_add_f32 v[32:33], v[32:33], v[52:53]
	v_mov_b32_e32 v53, v33
	v_mov_b32_e32 v52, v32
	s_nop 0
	v_permlane16_swap_b32_e32 v53, v33
	v_permlane16_swap_b32_e32 v52, v32
	s_waitcnt lgkmcnt(0)
	v_pk_add_f32 v[32:33], v[32:33], v[52:53]
	s_nop 1
	v_add_f32_dpp v33, v33, v33 row_ror:8 row_mask:0xf bank_mask:0xf
	v_add_f32_dpp v32, v32, v32 row_ror:8 row_mask:0xf bank_mask:0xf
	s_waitcnt lgkmcnt(0)
	s_nop 1
	v_add_f32_dpp v33, v33, v33 row_ror:4 row_mask:0xf bank_mask:0xf
	v_add_f32_dpp v32, v32, v32 row_ror:4 row_mask:0xf bank_mask:0xf
	s_waitcnt lgkmcnt(0)
	s_nop 1
	v_add_f32_dpp v33, v33, v33 quad_perm:[2,3,0,1] row_mask:0xf bank_mask:0xf
	v_add_f32_dpp v32, v32, v32 quad_perm:[2,3,0,1] row_mask:0xf bank_mask:0xf
	s_waitcnt lgkmcnt(0)
	s_nop 1
	v_add_f32_dpp v33, v33, v33 quad_perm:[1,0,3,2] row_mask:0xf bank_mask:0xf
	v_add_f32_dpp v32, v32, v32 quad_perm:[1,0,3,2] row_mask:0xf bank_mask:0xf
	s_waitcnt lgkmcnt(0)
	s_nop 0
	v_pk_fma_f32 v[32:33], v[32:33], s[4:5], v[26:27] op_sel_hi:[1,0,0]
	s_nop 0
	v_cmp_gt_f32_e64 s[0:1], s77, v33
	v_cmp_gt_f32_e32 vcc, s77, v32
	s_nop 0
	v_rsq_f32_e32 v3, v33
	s_nop 0
	v_mul_f32_e32 v3, 0x3dd53b94, v3
	v_mul_f32_e32 v31, v3, v31
	v_mul_f32_e32 v31, v41, v31
	ds_bpermute_b32 v33, v43, v31
	v_mul_f32_e32 v30, v3, v30
	v_mul_f32_e32 v30, v36, v30
	v_mul_f32_e32 v3, v3, v51
	v_mul_f32_e32 v3, v37, v3
	s_waitcnt lgkmcnt(0)
	v_mul_f32_e32 v33, v35, v33
	v_cndmask_b32_e64 v33, v33, -v33, s[38:39]
	v_fmac_f32_e32 v33, v34, v31
	v_bfe_u32 v31, v30, 16, 1
	v_add3_u32 v30, v30, v31, s11
	global_store_short_d16_hi v[16:17], v30, off offset:384
	v_bfe_u32 v30, v3, 16, 1
	v_add3_u32 v3, v3, v30, s11
	global_store_short_d16_hi v[16:17], v3, off offset:512
	v_bfe_u32 v3, v33, 16, 1
	v_add3_u32 v3, v33, v3, s11
	global_store_short_d16_hi v[16:17], v3, off offset:640
	v_rsq_f32_e32 v3, v32
	v_pk_mul_f32 v[32:33], v[20:21], v[20:21]
	v_mul_f32_e32 v30, v3, v12
	v_mul_f32_e32 v30, v40, v30
	ds_bpermute_b32 v31, v43, v30
	v_mul_f32_e32 v28, v3, v28
	v_mul_f32_e32 v28, v38, v28
	v_mul_f32_e32 v3, v3, v29
	v_mul_f32_e32 v3, v39, v3
	s_waitcnt lgkmcnt(0)
	v_mul_f32_e32 v31, v35, v31
	v_cndmask_b32_e64 v31, v31, -v31, s[38:39]
	v_fmac_f32_e32 v31, v34, v30
	v_bfe_u32 v30, v28, 16, 1
	v_add3_u32 v28, v28, v30, s11
	global_store_short_d16_hi v[18:19], v28, off offset:384
	v_bfe_u32 v28, v3, 16, 1
	v_add3_u32 v3, v3, v28, s11
	global_store_short_d16_hi v[18:19], v3, off offset:512
	v_bfe_u32 v3, v31, 16, 1
	v_pk_mul_f32 v[28:29], v[22:23], v[22:23]
	v_add3_u32 v3, v31, v3, s11
	v_mul_f32_e32 v31, v50, v50
	v_mov_b32_e32 v52, v32
	v_mov_b32_e32 v53, v28
	v_mov_b32_e32 v30, v33
	v_pk_add_f32 v[30:31], v[52:53], v[30:31]
	v_mov_b32_e32 v28, v24
	v_pk_add_f32 v[28:29], v[28:29], v[30:31]
	v_mov_b32_e32 v31, v29
	v_mov_b32_e32 v30, v28
	s_nop 0
	v_permlane32_swap_b32_e32 v31, v29
	v_permlane32_swap_b32_e32 v30, v28
	global_store_short_d16_hi v[18:19], v3, off offset:640
	s_waitcnt lgkmcnt(0)
	v_pk_add_f32 v[28:29], v[28:29], v[30:31]
	v_mov_b32_e32 v31, v29
	v_mov_b32_e32 v30, v28
	s_nop 0
	v_permlane16_swap_b32_e32 v31, v29
	v_permlane16_swap_b32_e32 v30, v28
	s_waitcnt lgkmcnt(0)
	v_pk_add_f32 v[28:29], v[28:29], v[30:31]
	s_nop 1
	v_add_f32_dpp v29, v29, v29 row_ror:8 row_mask:0xf bank_mask:0xf
	v_add_f32_dpp v28, v28, v28 row_ror:8 row_mask:0xf bank_mask:0xf
	s_waitcnt lgkmcnt(0)
	s_nop 1
	v_add_f32_dpp v29, v29, v29 row_ror:4 row_mask:0xf bank_mask:0xf
	v_add_f32_dpp v28, v28, v28 row_ror:4 row_mask:0xf bank_mask:0xf
	s_waitcnt lgkmcnt(0)
	s_nop 1
	v_add_f32_dpp v29, v29, v29 quad_perm:[2,3,0,1] row_mask:0xf bank_mask:0xf
	v_add_f32_dpp v28, v28, v28 quad_perm:[2,3,0,1] row_mask:0xf bank_mask:0xf
	s_waitcnt lgkmcnt(0)
	s_nop 1
	v_add_f32_dpp v29, v29, v29 quad_perm:[1,0,3,2] row_mask:0xf bank_mask:0xf
	v_add_f32_dpp v28, v28, v28 quad_perm:[1,0,3,2] row_mask:0xf bank_mask:0xf
	s_waitcnt lgkmcnt(0)
	s_nop 0
	v_pk_fma_f32 v[28:29], v[28:29], s[4:5], v[26:27] op_sel_hi:[1,0,0]
	s_nop 0
	v_cmp_gt_f32_e64 s[0:1], s77, v29
	v_cmp_gt_f32_e32 vcc, s77, v28
	s_nop 0
	v_rsq_f32_e32 v3, v29
	s_nop 0
	v_mul_f32_e32 v3, 0x3dd53b94, v3
	v_mul_f32_e32 v23, v3, v23
	v_mul_f32_e32 v23, v41, v23
	ds_bpermute_b32 v29, v43, v23
	v_mul_f32_e32 v22, v3, v22
	v_mul_f32_e32 v22, v36, v22
	v_mul_f32_e32 v3, v3, v50
	v_mul_f32_e32 v3, v37, v3
	s_waitcnt lgkmcnt(0)
; DI bf16_t f2bf(float f) { unsigned u = __float_as_uint(f); u += 0x7fffu + ((u >> 16) & 1u); return (bf16_t)(u >> 16); }
; DI float wave_sum(float v) { for (int o = 32; o; o >>= 1) v += __shfl_xor(v, o); return v; }
; DI void run_phase(const Params& p, int ph, unsigned char* smem, const int tid, const int rep) {
;     ...
;                 for (int h = 0; h < 4; ++h) {
;                     { const float a0 = qa[u][h][0], a1 = qa[u][h][1], a2 = qa[u][h][2];
;                       const float rs = rsqrtf(wave_sum(a0 * a0 + a1 * a1 + a2 * a2) * (1.f / 192.f) + NEPS) * (0.07216878364870322f * LOG2E);
;                       const float y2 = a2 * rs * gq2; const float oth = __shfl_xor(y2, 32);
;                       const float rot = (lane < 32) ? (y2 * cs - oth * sn) : (y2 * cs + oth * sn);
;                       bf16_t* qo = mlaq + (size_t)t * 768 + h * 192; qo[lane] = f2bf(a0 * rs * gq0); qo[lane + 64] = f2bf(a1 * rs * gq1); qo[lane + 128] = f2bf(rot); }
;                     { const float a0 = ka[u][h][0], a1 = ka[u][h][1];
;                       const float rs = rsqrtf(wave_sum(a0 * a0 + a1 * a1 + kr * kr) * (1.f / 192.f) + NEPS);
;                       const float y2 = kr * rs * gk2; const float oth = __shfl_xor(y2, 32);
;                       const float rot = (lane < 32) ? (y2 * cs - oth * sn) : (y2 * cs + oth * sn);
;                       bf16_t* ko = mlak + (size_t)t * 768 + h * 192; ko[lane] = f2bf(a0 * rs * gk0); ko[lane + 64] = f2bf(a1 * rs * gk1); ko[lane + 128] = f2bf(rot); }
	v_mul_f32_e32 v29, v35, v29
	v_cndmask_b32_e64 v29, v29, -v29, s[38:39]
	v_fmac_f32_e32 v29, v34, v23
	v_bfe_u32 v23, v22, 16, 1
	v_add3_u32 v22, v22, v23, s11
	global_store_short_d16_hi v[16:17], v22, off offset:768
	v_bfe_u32 v22, v3, 16, 1
	v_add3_u32 v3, v3, v22, s11
	global_store_short_d16_hi v[16:17], v3, off offset:896
	v_bfe_u32 v3, v29, 16, 1
	v_add3_u32 v3, v29, v3, s11
	global_store_short_d16_hi v[16:17], v3, off offset:1024
	v_rsq_f32_e32 v3, v28
	s_nop 0
	v_mul_f32_e32 v22, v3, v12
	v_mul_f32_e32 v22, v40, v22
	ds_bpermute_b32 v23, v43, v22
	v_mul_f32_e32 v20, v3, v20
	v_mul_f32_e32 v20, v38, v20
	v_mul_f32_e32 v3, v3, v21
	v_mul_f32_e32 v3, v39, v3
	s_waitcnt lgkmcnt(0)
	v_mul_f32_e32 v23, v35, v23
	v_cndmask_b32_e64 v23, v23, -v23, s[38:39]
	v_fmac_f32_e32 v23, v34, v22
	v_bfe_u32 v22, v20, 16, 1
	v_add3_u32 v20, v20, v22, s11
	global_store_short_d16_hi v[18:19], v20, off offset:768
	v_bfe_u32 v20, v3, 16, 1
	v_add3_u32 v3, v3, v20, s11
	global_store_short_d16_hi v[18:19], v3, off offset:896
	v_bfe_u32 v3, v23, 16, 1
	v_pk_mul_f32 v[20:21], v[14:15], v[14:15]
	v_add3_u32 v3, v23, v3, s11
	v_pk_mov_b32 v[22:23], v[24:25], v[20:21] op_sel:[1,0]
	v_mov_b32_e32 v25, v21
	v_pk_fma_f32 v[22:23], v[10:11], v[10:11], v[22:23]
	global_store_short_d16_hi v[18:19], v3, off offset:1024
	v_pk_add_f32 v[20:21], v[24:25], v[22:23]
	v_mov_b32_e32 v23, v21
	v_mov_b32_e32 v22, v20
	s_nop 0
	v_permlane32_swap_b32_e32 v23, v21
	v_permlane32_swap_b32_e32 v22, v20
	s_waitcnt lgkmcnt(0)
	v_pk_add_f32 v[20:21], v[20:21], v[22:23]
	v_mov_b32_e32 v23, v21
	v_mov_b32_e32 v22, v20
	s_nop 0
	v_permlane16_swap_b32_e32 v23, v21
	v_permlane16_swap_b32_e32 v22, v20
	s_waitcnt lgkmcnt(0)
	v_pk_add_f32 v[20:21], v[20:21], v[22:23]
	s_nop 1
	v_add_f32_dpp v21, v21, v21 row_ror:8 row_mask:0xf bank_mask:0xf
	v_add_f32_dpp v20, v20, v20 row_ror:8 row_mask:0xf bank_mask:0xf
	s_waitcnt lgkmcnt(0)
	s_nop 1
	v_add_f32_dpp v21, v21, v21 row_ror:4 row_mask:0xf bank_mask:0xf
	v_add_f32_dpp v20, v20, v20 row_ror:4 row_mask:0xf bank_mask:0xf
	s_waitcnt lgkmcnt(0)
	s_nop 1
	v_add_f32_dpp v21, v21, v21 quad_perm:[2,3,0,1] row_mask:0xf bank_mask:0xf
	v_add_f32_dpp v20, v20, v20 quad_perm:[2,3,0,1] row_mask:0xf bank_mask:0xf
	s_waitcnt lgkmcnt(0)
	s_nop 1
	v_add_f32_dpp v21, v21, v21 quad_perm:[1,0,3,2] row_mask:0xf bank_mask:0xf
	v_add_f32_dpp v20, v20, v20 quad_perm:[1,0,3,2] row_mask:0xf bank_mask:0xf
	s_waitcnt lgkmcnt(0)
	s_nop 0
	v_pk_fma_f32 v[20:21], v[20:21], s[4:5], v[26:27] op_sel_hi:[1,0,0]
	s_nop 0
	v_cmp_gt_f32_e64 s[0:1], s77, v21
	v_cmp_gt_f32_e32 vcc, s77, v20
	s_nop 0
	v_rsq_f32_e32 v3, v21
	s_nop 0
	v_mul_f32_e32 v3, 0x3dd53b94, v3
	v_mul_f32_e32 v15, v3, v15
	v_mul_f32_e32 v15, v41, v15
	ds_bpermute_b32 v21, v43, v15
	v_mul_f32_e32 v14, v3, v14
	v_mul_f32_e32 v3, v3, v11
	v_mul_f32_e32 v3, v37, v3
	v_bfe_u32 v11, v3, 16, 1
	s_waitcnt lgkmcnt(0)
	v_mul_f32_e32 v21, v35, v21
	v_cndmask_b32_e64 v21, v21, -v21, s[38:39]
	v_fmac_f32_e32 v21, v34, v15
	v_add3_u32 v3, v3, v11, s11
	global_store_short_d16_hi v[16:17], v3, off offset:1280
	v_bfe_u32 v3, v21, 16, 1
	v_add3_u32 v3, v21, v3, s11
	global_store_short_d16_hi v[16:17], v3, off offset:1408
	v_rsq_f32_e32 v3, v20
	v_mul_f32_e32 v14, v36, v14
	v_bfe_u32 v15, v14, 16, 1
	v_add3_u32 v14, v14, v15, s11
	v_mul_f32_e32 v11, v3, v12
	v_mul_f32_e32 v11, v40, v11
	ds_bpermute_b32 v12, v43, v11
	v_cmp_lt_i32_e32 vcc, s11, v2
	s_or_b64 s[34:35], vcc, s[34:35]
	global_store_short_d16_hi v[16:17], v14, off offset:1152
	s_waitcnt lgkmcnt(0)
	v_mul_f32_e32 v12, v35, v12
	v_cndmask_b32_e64 v12, v12, -v12, s[38:39]
	v_fmac_f32_e32 v12, v34, v11
	v_mul_f32_e32 v11, v3, v13
	v_mul_f32_e32 v3, v3, v10
	v_mul_f32_e32 v3, v39, v3
	v_bfe_u32 v10, v3, 16, 1
	v_mul_f32_e32 v11, v38, v11
	v_add3_u32 v3, v3, v10, s11
	v_bfe_u32 v13, v11, 16, 1
	global_store_short_d16_hi v[18:19], v3, off offset:1280
	v_bfe_u32 v3, v12, 16, 1
	v_add3_u32 v11, v11, v13, s11
	v_add3_u32 v3, v12, v3, s11
	global_store_short_d16_hi v[18:19], v11, off offset:1152
	global_store_short_d16_hi v[18:19], v3, off offset:1408
	s_andn2_b64 exec, exec, s[34:35]
	s_cbranch_execz .LBB0_340

; DI bf16_t f2bf(float f) { unsigned u = __float_as_uint(f); u += 0x7fffu + ((u >> 16) & 1u); return (bf16_t)(u >> 16); }
; DI float wave_sum(float v) { for (int o = 32; o; o >>= 1) v += __shfl_xor(v, o); return v; }
; DI void run_phase(const Params& p, int ph, unsigned char* smem, const int tid, const int rep) {
;     ...
;             for (int u = 0; u < 2; ++u) { const int t = t0 + u;
;                 const float ang = (float)ps[u] * invf; float sn, cs; sincosf(ang, &sn, &cs);
;                 const float kr = krv[u];
; #pragma unroll
;                 for (int h = 0; h < 4; ++h) {
;                     { const float a0 = qa[u][h][0], a1 = qa[u][h][1], a2 = qa[u][h][2];
;                       const float rs = rsqrtf(wave_sum(a0 * a0 + a1 * a1 + a2 * a2) * (1.f / 192.f) + NEPS) * (0.07216878364870322f * LOG2E);
;                       const float y2 = a2 * rs * gq2; const float oth = __shfl_xor(y2, 32);
;                       const float rot = (lane < 32) ? (y2 * cs - oth * sn) : (y2 * cs + oth * sn);
;                       bf16_t* qo = mlaq + (size_t)t * 768 + h * 192; qo[lane] = f2bf(a0 * rs * gq0); qo[lane + 64] = f2bf(a1 * rs * gq1); qo[lane + 128] = f2bf(rot); }
;                     { const float a0 = ka[u][h][0], a1 = ka[u][h][1];
;                       const float rs = rsqrtf(wave_sum(a0 * a0 + a1 * a1 + kr * kr) * (1.f / 192.f) + NEPS);
;                       const float y2 = kr * rs * gk2; const float oth = __shfl_xor(y2, 32);
;                       const float rot = (lane < 32) ? (y2 * cs - oth * sn) : (y2 * cs + oth * sn);
;                       bf16_t* ko = mlak + (size_t)t * 768 + h * 192; ko[lane] = f2bf(a0 * rs * gk0); ko[lane + 64] = f2bf(a1 * rs * gk1); ko[lane + 128] = f2bf(rot); }
.LBB0_336:
	s_or_b64 exec, exec, s[0:1]
	s_waitcnt vmcnt(40)
	v_lshlrev_b32_e32 v20, 16, v15
	s_waitcnt vmcnt(22)
	v_lshlrev_b32_e32 v15, 16, v14
	v_lshlrev_b32_e32 v14, 16, v12
	s_waitcnt vmcnt(21)
	v_lshlrev_b32_e32 v12, 16, v18
	v_mul_f32_e32 v18, v78, v78
	v_lshlrev_b32_e32 v32, 16, v19
	v_fmamk_f32 v19, v18, 0xb94c1982, v249
	v_fmaak_f32 v19, v18, v19, 0xbe2aaa9d
	v_mul_f32_e32 v19, v18, v19
	v_fmac_f32_e32 v78, v78, v19
	v_fmamk_f32 v19, v18, 0x37d75334, v223
	v_fmaak_f32 v19, v18, v19, 0x3d2aabf7
	v_lshlrev_b32_e32 v30, 16, v27
	v_fmaak_f32 v19, v18, v19, 0xbf000004
	v_and_b32_e32 v27, 1, v79
	v_fma_f32 v18, v18, v19, 1.0
	v_cmp_eq_u32_e32 vcc, 0, v27
	v_lshlrev_b32_e32 v31, 16, v28
	v_lshlrev_b32_e32 v19, 30, v79
	v_cndmask_b32_e32 v27, v18, v78, vcc
	v_xor_b32_e32 v28, v77, v10
	v_lshlrev_b32_e32 v33, 16, v24
	v_lshlrev_b32_e32 v24, 16, v26
	v_and_b32_e32 v26, 0x80000000, v19
	v_xor_b32_e32 v27, v28, v27
	v_xor_b32_e32 v26, v27, v26
	v_xor_b32_e32 v27, 0x80000000, v78
	v_cndmask_b32_e32 v18, v27, v18, vcc
	s_brev_b32 s0, 1
	v_lshlrev_b32_e32 v21, 16, v17
	v_lshlrev_b32_e32 v35, 16, v25
	v_lshlrev_b32_e32 v34, 16, v22
	v_bitop3_b32 v18, v18, v19, s0 bitop3:0x78
	s_movk_i32 s0, 0x1f8
	v_lshlrev_b32_e32 v80, 16, v16
	v_lshlrev_b32_e32 v22, 16, v29
	v_lshlrev_b32_e32 v17, 16, v76
	v_cmp_class_f32_e64 vcc, v10, s0
	v_pk_mul_f32 v[28:29], v[20:21], v[20:21]
	v_pk_mul_f32 v[76:77], v[34:35], v[34:35]
	v_lshlrev_b32_e32 v72, 16, v23
	v_lshlrev_b32_e32 v71, 16, v70
	v_lshlrev_b32_e32 v23, 16, v74
	v_lshlrev_b32_e32 v16, 16, v75
	v_cndmask_b32_e32 v70, v224, v26, vcc
	v_pk_mul_f32 v[26:27], v[14:15], v[14:15]
	v_mul_f32_e32 v75, v80, v80
	v_mov_b32_e32 v78, v76
	v_mov_b32_e32 v79, v28
	v_mov_b32_e32 v74, v77
	v_pk_add_f32 v[74:75], v[78:79], v[74:75]
	v_mov_b32_e32 v28, v26
	v_pk_add_f32 v[28:29], v[28:29], v[74:75]
	v_mov_b32_e32 v75, v29
	v_mov_b32_e32 v74, v28
	s_nop 0
	v_permlane32_swap_b32_e32 v75, v29
	v_permlane32_swap_b32_e32 v74, v28
	s_mov_b32 s4, 0x3baaaaab
	v_cndmask_b32_e32 v10, v224, v18, vcc
	v_mad_i64_i32 v[18:19], s[0:1], v2, s7, v[6:7]
	s_waitcnt lgkmcnt(0)
	v_pk_add_f32 v[28:29], v[28:29], v[74:75]
	v_mov_b32_e32 v75, v29
	v_mov_b32_e32 v74, v28
	s_nop 0
	v_permlane16_swap_b32_e32 v75, v29
	v_permlane16_swap_b32_e32 v74, v28
	v_lshlrev_b32_e32 v25, 16, v73
	v_pk_mul_f32 v[76:77], v[30:31], v[30:31]
	v_lshlrev_b32_e32 v13, 16, v13
	v_mov_b32_e32 v78, v76
	s_waitcnt lgkmcnt(0)
	v_pk_add_f32 v[28:29], v[28:29], v[74:75]
	s_nop 1
	v_add_f32_dpp v29, v29, v29 row_ror:8 row_mask:0xf bank_mask:0xf
	v_add_f32_dpp v28, v28, v28 row_ror:8 row_mask:0xf bank_mask:0xf
	s_waitcnt lgkmcnt(0)
	s_nop 1
	v_add_f32_dpp v29, v29, v29 row_ror:4 row_mask:0xf bank_mask:0xf
	v_add_f32_dpp v28, v28, v28 row_ror:4 row_mask:0xf bank_mask:0xf
	s_waitcnt lgkmcnt(0)
	s_nop 1
	v_add_f32_dpp v29, v29, v29 quad_perm:[2,3,0,1] row_mask:0xf bank_mask:0xf
	v_add_f32_dpp v28, v28, v28 quad_perm:[2,3,0,1] row_mask:0xf bank_mask:0xf
	s_waitcnt lgkmcnt(0)
	s_nop 1
	v_add_f32_dpp v75, v29, v29 quad_perm:[1,0,3,2] row_mask:0xf bank_mask:0xf
	v_add_f32_dpp v74, v28, v28 quad_perm:[1,0,3,2] row_mask:0xf bank_mask:0xf
	s_waitcnt lgkmcnt(0)
	v_mov_b64_e32 v[28:29], s[72:73]
	v_pk_fma_f32 v[74:75], v[74:75], s[4:5], v[28:29] op_sel_hi:[1,0,0]
	s_nop 0
	v_cmp_gt_f32_e64 s[0:1], s77, v75
	v_cmp_gt_f32_e32 vcc, s77, v74
	s_nop 0
	v_rsq_f32_e32 v73, v75
	s_nop 0
	v_mul_f32_e32 v73, 0x3dd53b94, v73
	v_mul_f32_e32 v21, v73, v21
	v_mul_f32_e32 v21, v41, v21
	ds_bpermute_b32 v75, v43, v21
	v_mul_f32_e32 v20, v73, v20
	v_mul_f32_e32 v20, v36, v20
	s_waitcnt lgkmcnt(0)
	v_mul_f32_e32 v75, v70, v75
	v_cndmask_b32_e64 v75, v75, -v75, s[38:39]
	v_fmac_f32_e32 v75, v10, v21
	v_bfe_u32 v21, v20, 16, 1
	v_add3_u32 v20, v20, v21, s11
	global_store_short_d16_hi v[18:19], v20, off
	v_mul_f32_e32 v20, v73, v80
	v_mul_f32_e32 v20, v37, v20
	v_bfe_u32 v21, v20, 16, 1
	v_add3_u32 v20, v20, v21, s11
	global_store_short_d16_hi v[18:19], v20, off offset:128
	v_bfe_u32 v20, v75, 16, 1
	v_add3_u32 v20, v75, v20, s11
	global_store_short_d16_hi v[18:19], v20, off offset:256
	v_rsq_f32_e32 v20, v74
	v_mul_f32_e32 v75, v72, v72
	v_mov_b32_e32 v73, v20
	v_mul_f32_e32 v20, v73, v14
	v_mul_f32_e32 v20, v40, v20
	ds_bpermute_b32 v21, v43, v20
	s_waitcnt lgkmcnt(0)
	v_mul_f32_e32 v21, v70, v21
	v_cndmask_b32_e64 v74, v21, -v21, s[38:39]
	v_fmac_f32_e32 v74, v10, v20
	v_mul_f32_e32 v20, v73, v34
	v_mul_f32_e32 v20, v38, v20
	v_bfe_u32 v21, v20, 16, 1
	v_add3_u32 v34, v20, v21, s11
	v_mad_i64_i32 v[20:21], s[0:1], v2, s7, v[8:9]
	global_store_short_d16_hi v[20:21], v34, off
	v_mul_f32_e32 v34, v73, v35
	v_mul_f32_e32 v34, v39, v34
	v_bfe_u32 v35, v34, 16, 1
	v_add3_u32 v34, v34, v35, s11
	global_store_short_d16_hi v[20:21], v34, off offset:128
	v_bfe_u32 v34, v74, 16, 1
	v_add3_u32 v34, v74, v34, s11
	global_store_short_d16_hi v[20:21], v34, off offset:256
	v_pk_mul_f32 v[34:35], v[32:33], v[32:33]
	v_mov_b32_e32 v74, v77
	v_mov_b32_e32 v79, v34
	v_pk_add_f32 v[74:75], v[78:79], v[74:75]
	v_mov_b32_e32 v34, v26
	v_pk_add_f32 v[34:35], v[34:35], v[74:75]
	v_mov_b32_e32 v75, v35
	v_mov_b32_e32 v74, v34
	s_nop 0
	v_permlane32_swap_b32_e32 v75, v35
	v_permlane32_swap_b32_e32 v74, v34
	s_waitcnt lgkmcnt(0)
	v_pk_add_f32 v[34:35], v[34:35], v[74:75]
	v_mov_b32_e32 v75, v35
	v_mov_b32_e32 v74, v34
	s_nop 0
	v_permlane16_swap_b32_e32 v75, v35
	v_permlane16_swap_b32_e32 v74, v34
	s_waitcnt lgkmcnt(0)
	v_pk_add_f32 v[34:35], v[34:35], v[74:75]
	s_nop 1
	v_add_f32_dpp v35, v35, v35 row_ror:8 row_mask:0xf bank_mask:0xf
	v_add_f32_dpp v34, v34, v34 row_ror:8 row_mask:0xf bank_mask:0xf
	s_waitcnt lgkmcnt(0)
; DI bf16_t f2bf(float f) { unsigned u = __float_as_uint(f); u += 0x7fffu + ((u >> 16) & 1u); return (bf16_t)(u >> 16); }
; DI float wave_sum(float v) { for (int o = 32; o; o >>= 1) v += __shfl_xor(v, o); return v; }
; DI void run_phase(const Params& p, int ph, unsigned char* smem, const int tid, const int rep) {
;     ...
;                 for (int h = 0; h < 4; ++h) {
;                     { const float a0 = qa[u][h][0], a1 = qa[u][h][1], a2 = qa[u][h][2];
;                       const float rs = rsqrtf(wave_sum(a0 * a0 + a1 * a1 + a2 * a2) * (1.f / 192.f) + NEPS) * (0.07216878364870322f * LOG2E);
;                       const float y2 = a2 * rs * gq2; const float oth = __shfl_xor(y2, 32);
;                       const float rot = (lane < 32) ? (y2 * cs - oth * sn) : (y2 * cs + oth * sn);
;                       bf16_t* qo = mlaq + (size_t)t * 768 + h * 192; qo[lane] = f2bf(a0 * rs * gq0); qo[lane + 64] = f2bf(a1 * rs * gq1); qo[lane + 128] = f2bf(rot); }
;                     { const float a0 = ka[u][h][0], a1 = ka[u][h][1];
;                       const float rs = rsqrtf(wave_sum(a0 * a0 + a1 * a1 + kr * kr) * (1.f / 192.f) + NEPS);
;                       const float y2 = kr * rs * gk2; const float oth = __shfl_xor(y2, 32);
;                       const float rot = (lane < 32) ? (y2 * cs - oth * sn) : (y2 * cs + oth * sn);
;                       bf16_t* ko = mlak + (size_t)t * 768 + h * 192; ko[lane] = f2bf(a0 * rs * gk0); ko[lane + 64] = f2bf(a1 * rs * gk1); ko[lane + 128] = f2bf(rot); }
	s_nop 1
	v_add_f32_dpp v35, v35, v35 row_ror:4 row_mask:0xf bank_mask:0xf
	v_add_f32_dpp v34, v34, v34 row_ror:4 row_mask:0xf bank_mask:0xf
	s_waitcnt lgkmcnt(0)
	s_nop 1
	v_add_f32_dpp v35, v35, v35 quad_perm:[2,3,0,1] row_mask:0xf bank_mask:0xf
	v_add_f32_dpp v34, v34, v34 quad_perm:[2,3,0,1] row_mask:0xf bank_mask:0xf
	s_waitcnt lgkmcnt(0)
	s_nop 1
	v_add_f32_dpp v35, v35, v35 quad_perm:[1,0,3,2] row_mask:0xf bank_mask:0xf
	v_add_f32_dpp v34, v34, v34 quad_perm:[1,0,3,2] row_mask:0xf bank_mask:0xf
	s_waitcnt lgkmcnt(0)
	s_nop 0
	v_pk_fma_f32 v[34:35], v[34:35], s[4:5], v[28:29] op_sel_hi:[1,0,0]
	s_nop 0
	v_cmp_gt_f32_e64 s[0:1], s77, v35
	v_cmp_gt_f32_e32 vcc, s77, v34
	s_nop 0
	v_rsq_f32_e32 v35, v35
	s_nop 0
	v_mul_f32_e32 v35, 0x3dd53b94, v35
	v_mul_f32_e32 v33, v35, v33
	v_mul_f32_e32 v33, v41, v33
	ds_bpermute_b32 v73, v43, v33
	v_mul_f32_e32 v32, v35, v32
	v_mul_f32_e32 v32, v36, v32
	s_waitcnt lgkmcnt(0)
	v_mul_f32_e32 v73, v70, v73
	v_cndmask_b32_e64 v73, v73, -v73, s[38:39]
	v_fmac_f32_e32 v73, v10, v33
	v_bfe_u32 v33, v32, 16, 1
	v_add3_u32 v32, v32, v33, s11
	global_store_short_d16_hi v[18:19], v32, off offset:384
	v_mul_f32_e32 v32, v35, v72
	v_mul_f32_e32 v32, v37, v32
	v_bfe_u32 v33, v32, 16, 1
	v_add3_u32 v32, v32, v33, s11
	global_store_short_d16_hi v[18:19], v32, off offset:512
	v_bfe_u32 v32, v73, 16, 1
	v_add3_u32 v32, v73, v32, s11
	global_store_short_d16_hi v[18:19], v32, off offset:640
	v_rsq_f32_e32 v32, v34
	s_nop 0
	v_mul_f32_e32 v33, v32, v14
	v_mul_f32_e32 v33, v40, v33
	ds_bpermute_b32 v34, v43, v33
	v_mul_f32_e32 v30, v32, v30
	v_mul_f32_e32 v30, v38, v30
	s_waitcnt lgkmcnt(0)
	v_mul_f32_e32 v34, v70, v34
	v_cndmask_b32_e64 v34, v34, -v34, s[38:39]
	v_fmac_f32_e32 v34, v10, v33
	v_bfe_u32 v33, v30, 16, 1
	v_add3_u32 v30, v30, v33, s11
	global_store_short_d16_hi v[20:21], v30, off offset:384
	v_mul_f32_e32 v30, v32, v31
	v_mul_f32_e32 v30, v39, v30
	v_bfe_u32 v31, v30, 16, 1
	v_add3_u32 v30, v30, v31, s11
	global_store_short_d16_hi v[20:21], v30, off offset:512
	v_bfe_u32 v30, v34, 16, 1
	v_add3_u32 v30, v34, v30, s11
	global_store_short_d16_hi v[20:21], v30, off offset:640
	v_pk_mul_f32 v[30:31], v[24:25], v[24:25]
	v_pk_mul_f32 v[34:35], v[22:23], v[22:23]
	v_mul_f32_e32 v33, v71, v71
	v_mov_b32_e32 v72, v34
	v_mov_b32_e32 v73, v30
	v_mov_b32_e32 v32, v35
	v_pk_add_f32 v[32:33], v[72:73], v[32:33]
	v_mov_b32_e32 v30, v26
	v_pk_add_f32 v[30:31], v[30:31], v[32:33]
	v_mov_b32_e32 v33, v31
	v_mov_b32_e32 v32, v30
	s_nop 0
	v_permlane32_swap_b32_e32 v33, v31
	v_permlane32_swap_b32_e32 v32, v30
	s_waitcnt lgkmcnt(0)
	v_pk_add_f32 v[30:31], v[30:31], v[32:33]
	v_mov_b32_e32 v33, v31
	v_mov_b32_e32 v32, v30
	s_nop 0
	v_permlane16_swap_b32_e32 v33, v31
	v_permlane16_swap_b32_e32 v32, v30
	s_waitcnt lgkmcnt(0)
	v_pk_add_f32 v[30:31], v[30:31], v[32:33]
	s_nop 1
	v_add_f32_dpp v31, v31, v31 row_ror:8 row_mask:0xf bank_mask:0xf
	v_add_f32_dpp v30, v30, v30 row_ror:8 row_mask:0xf bank_mask:0xf
	s_waitcnt lgkmcnt(0)
	s_nop 1
	v_add_f32_dpp v31, v31, v31 row_ror:4 row_mask:0xf bank_mask:0xf
	v_add_f32_dpp v30, v30, v30 row_ror:4 row_mask:0xf bank_mask:0xf
	s_waitcnt lgkmcnt(0)
	s_nop 1
	v_add_f32_dpp v31, v31, v31 quad_perm:[2,3,0,1] row_mask:0xf bank_mask:0xf
	v_add_f32_dpp v30, v30, v30 quad_perm:[2,3,0,1] row_mask:0xf bank_mask:0xf
	s_waitcnt lgkmcnt(0)
	s_nop 1
	v_add_f32_dpp v31, v31, v31 quad_perm:[1,0,3,2] row_mask:0xf bank_mask:0xf
	v_add_f32_dpp v30, v30, v30 quad_perm:[1,0,3,2] row_mask:0xf bank_mask:0xf
	s_waitcnt lgkmcnt(0)
	s_nop 0
	v_pk_fma_f32 v[30:31], v[30:31], s[4:5], v[28:29] op_sel_hi:[1,0,0]
	s_nop 0
	v_cmp_gt_f32_e64 s[0:1], s77, v31
	v_cmp_gt_f32_e32 vcc, s77, v30
	s_nop 0
	v_rsq_f32_e32 v31, v31
	s_nop 0
	v_mul_f32_e32 v31, 0x3dd53b94, v31
	v_mul_f32_e32 v25, v31, v25
	v_mul_f32_e32 v25, v41, v25
	ds_bpermute_b32 v32, v43, v25
	v_mul_f32_e32 v24, v31, v24
	v_mul_f32_e32 v24, v36, v24
	s_waitcnt lgkmcnt(0)
	v_mul_f32_e32 v32, v70, v32
	v_cndmask_b32_e64 v32, v32, -v32, s[38:39]
	v_fmac_f32_e32 v32, v10, v25
	v_bfe_u32 v25, v24, 16, 1
	v_add3_u32 v24, v24, v25, s11
	global_store_short_d16_hi v[18:19], v24, off offset:768
	v_mul_f32_e32 v24, v31, v71
	v_mul_f32_e32 v24, v37, v24
	v_bfe_u32 v25, v24, 16, 1
	v_add3_u32 v24, v24, v25, s11
	global_store_short_d16_hi v[18:19], v24, off offset:896
	v_bfe_u32 v24, v32, 16, 1
	v_add3_u32 v24, v32, v24, s11
	global_store_short_d16_hi v[18:19], v24, off offset:1024
	v_rsq_f32_e32 v24, v30
	s_nop 0
	v_mul_f32_e32 v25, v24, v14
	v_mul_f32_e32 v25, v40, v25
	ds_bpermute_b32 v30, v43, v25
	v_mul_f32_e32 v22, v24, v22
	v_mul_f32_e32 v22, v38, v22
	s_waitcnt lgkmcnt(0)
	v_mul_f32_e32 v30, v70, v30
	v_cndmask_b32_e64 v30, v30, -v30, s[38:39]
	v_fmac_f32_e32 v30, v10, v25
	v_bfe_u32 v25, v22, 16, 1
	v_add3_u32 v22, v22, v25, s11
	global_store_short_d16_hi v[20:21], v22, off offset:768
	v_mul_f32_e32 v22, v24, v23
	v_mul_f32_e32 v22, v39, v22
	v_bfe_u32 v23, v22, 16, 1
	v_add3_u32 v22, v22, v23, s11
	global_store_short_d16_hi v[20:21], v22, off offset:896
	v_bfe_u32 v22, v30, 16, 1
	v_add3_u32 v22, v30, v22, s11
	global_store_short_d16_hi v[20:21], v22, off offset:1024
	v_pk_mul_f32 v[22:23], v[16:17], v[16:17]
	s_nop 0
	v_pk_mov_b32 v[24:25], v[26:27], v[22:23] op_sel:[1,0]
	v_mov_b32_e32 v27, v23
	v_pk_fma_f32 v[24:25], v[12:13], v[12:13], v[24:25]
	s_nop 0
	v_pk_add_f32 v[22:23], v[26:27], v[24:25]
	v_mov_b32_e32 v25, v23
	v_mov_b32_e32 v24, v22
	s_nop 0
	v_permlane32_swap_b32_e32 v25, v23
	v_permlane32_swap_b32_e32 v24, v22
	s_waitcnt lgkmcnt(0)
	v_pk_add_f32 v[22:23], v[22:23], v[24:25]
	v_mov_b32_e32 v25, v23
	v_mov_b32_e32 v24, v22
	s_nop 0
	v_permlane16_swap_b32_e32 v25, v23
	v_permlane16_swap_b32_e32 v24, v22
	s_waitcnt lgkmcnt(0)
; DI bf16_t f2bf(float f) { unsigned u = __float_as_uint(f); u += 0x7fffu + ((u >> 16) & 1u); return (bf16_t)(u >> 16); }
; DI float wave_sum(float v) { for (int o = 32; o; o >>= 1) v += __shfl_xor(v, o); return v; }
; DI void run_phase(const Params& p, int ph, unsigned char* smem, const int tid, const int rep) {
;     ...
;                 const float ang = (float)ps[u] * invf; float sn, cs; sincosf(ang, &sn, &cs);
;     ...
;                 for (int h = 0; h < 4; ++h) {
;                     { const float a0 = qa[u][h][0], a1 = qa[u][h][1], a2 = qa[u][h][2];
;                       const float rs = rsqrtf(wave_sum(a0 * a0 + a1 * a1 + a2 * a2) * (1.f / 192.f) + NEPS) * (0.07216878364870322f * LOG2E);
;                       const float y2 = a2 * rs * gq2; const float oth = __shfl_xor(y2, 32);
;                       const float rot = (lane < 32) ? (y2 * cs - oth * sn) : (y2 * cs + oth * sn);
;                       bf16_t* qo = mlaq + (size_t)t * 768 + h * 192; qo[lane] = f2bf(a0 * rs * gq0); qo[lane + 64] = f2bf(a1 * rs * gq1); qo[lane + 128] = f2bf(rot); }
;                     { const float a0 = ka[u][h][0], a1 = ka[u][h][1];
;                       const float rs = rsqrtf(wave_sum(a0 * a0 + a1 * a1 + kr * kr) * (1.f / 192.f) + NEPS);
;                       const float y2 = kr * rs * gk2; const float oth = __shfl_xor(y2, 32);
;                       const float rot = (lane < 32) ? (y2 * cs - oth * sn) : (y2 * cs + oth * sn);
;                       bf16_t* ko = mlak + (size_t)t * 768 + h * 192; ko[lane] = f2bf(a0 * rs * gk0); ko[lane + 64] = f2bf(a1 * rs * gk1); ko[lane + 128] = f2bf(rot); }
	v_pk_add_f32 v[22:23], v[22:23], v[24:25]
	s_nop 1
	v_add_f32_dpp v23, v23, v23 row_ror:8 row_mask:0xf bank_mask:0xf
	v_add_f32_dpp v22, v22, v22 row_ror:8 row_mask:0xf bank_mask:0xf
	s_waitcnt lgkmcnt(0)
	s_nop 1
	v_add_f32_dpp v23, v23, v23 row_ror:4 row_mask:0xf bank_mask:0xf
	v_add_f32_dpp v22, v22, v22 row_ror:4 row_mask:0xf bank_mask:0xf
	s_waitcnt lgkmcnt(0)
	s_nop 1
	v_add_f32_dpp v23, v23, v23 quad_perm:[2,3,0,1] row_mask:0xf bank_mask:0xf
	v_add_f32_dpp v22, v22, v22 quad_perm:[2,3,0,1] row_mask:0xf bank_mask:0xf
	s_waitcnt lgkmcnt(0)
	s_nop 1
	v_add_f32_dpp v23, v23, v23 quad_perm:[1,0,3,2] row_mask:0xf bank_mask:0xf
	v_add_f32_dpp v22, v22, v22 quad_perm:[1,0,3,2] row_mask:0xf bank_mask:0xf
	s_waitcnt lgkmcnt(0)
	s_nop 0
	v_pk_fma_f32 v[22:23], v[22:23], s[4:5], v[28:29] op_sel_hi:[1,0,0]
	s_nop 0
	v_cmp_gt_f32_e64 s[0:1], s77, v23
	v_cmp_gt_f32_e32 vcc, s77, v22
	s_nop 0
	v_rsq_f32_e32 v23, v23
	s_nop 0
	v_mul_f32_e32 v23, 0x3dd53b94, v23
	v_mul_f32_e32 v17, v23, v17
	v_mul_f32_e32 v17, v41, v17
	ds_bpermute_b32 v24, v43, v17
	v_mul_f32_e32 v16, v23, v16
	v_mul_f32_e32 v16, v36, v16
	v_mul_f32_e32 v13, v23, v13
	v_mul_f32_e32 v13, v37, v13
	s_waitcnt lgkmcnt(0)
	v_mul_f32_e32 v24, v70, v24
	v_cndmask_b32_e64 v24, v24, -v24, s[38:39]
	v_fmac_f32_e32 v24, v10, v17
	v_bfe_u32 v17, v16, 16, 1
	v_add3_u32 v16, v16, v17, s11
	global_store_short_d16_hi v[18:19], v16, off offset:1152
	v_bfe_u32 v16, v13, 16, 1
	v_add3_u32 v13, v13, v16, s11
	global_store_short_d16_hi v[18:19], v13, off offset:1280
	v_bfe_u32 v13, v24, 16, 1
	v_add3_u32 v13, v24, v13, s11
	global_store_short_d16_hi v[18:19], v13, off offset:1408
	v_rsq_f32_e32 v13, v22
	s_brev_b32 s0, 18
	v_mul_f32_e32 v14, v13, v14
	v_mul_f32_e32 v14, v40, v14
	ds_bpermute_b32 v16, v43, v14
	s_waitcnt lgkmcnt(0)
	v_mul_f32_e32 v16, v70, v16
	v_cndmask_b32_e64 v16, v16, -v16, s[38:39]
	v_fmac_f32_e32 v16, v10, v14
	v_mul_f32_e32 v10, v13, v15
	v_mul_f32_e32 v10, v38, v10
	v_bfe_u32 v14, v10, 16, 1
	v_add3_u32 v10, v10, v14, s11
	global_store_short_d16_hi v[20:21], v10, off offset:1152
	v_mul_f32_e32 v10, v13, v12
	v_mul_f32_e32 v10, v39, v10
	v_bfe_u32 v12, v10, 16, 1
	v_add3_u32 v10, v10, v12, s11
	global_store_short_d16_hi v[20:21], v10, off offset:1280
	v_bfe_u32 v10, v16, 16, 1
	v_add3_u32 v10, v16, v10, s11
	global_store_short_d16_hi v[20:21], v10, off offset:1408
	v_cvt_f32_i32_e32 v10, v11
	v_mul_f32_e32 v16, v42, v10
	v_and_b32_e32 v17, 0x7fffffff, v16
	v_cmp_nlt_f32_e64 s[0:1], |v16|, s0
	s_and_saveexec_b64 s[40:41], s[0:1]
	s_xor_b64 s[44:45], exec, s[40:41]
	s_cbranch_execz .LBB0_338
	v_lshrrev_b32_e32 v10, 23, v17
	v_add_u32_e32 v10, 0xffffff88, v10
	v_cmp_lt_u32_e32 vcc, 63, v10
	s_mov_b32 s4, 0xfe5163ab
	v_mov_b32_e32 v13, v1
	v_cndmask_b32_e32 v11, 0, v195, vcc
	v_add_u32_e32 v10, v11, v10
	v_cmp_lt_u32_e64 s[0:1], 31, v10
	v_mov_b32_e32 v15, v1
	v_mov_b32_e32 v19, v1
	v_cndmask_b32_e64 v11, 0, v184, s[0:1]
	v_add_u32_e32 v10, v11, v10
	v_cmp_lt_u32_e64 s[40:41], 31, v10
	v_mov_b32_e32 v21, v1
	v_mov_b32_e32 v23, v1
	v_cndmask_b32_e64 v11, 0, v184, s[40:41]
	v_add_u32_e32 v26, v11, v10
	v_and_b32_e32 v10, 0x7fffff, v17
	v_or_b32_e32 v27, 0x800000, v10
	v_mad_u64_u32 v[10:11], s[42:43], v27, s4, 0
	v_mov_b32_e32 v12, v11
	s_mov_b32 s4, 0x3c439041
	v_mad_u64_u32 v[12:13], s[42:43], v27, s4, v[12:13]
	v_mov_b32_e32 v14, v13
	s_mov_b32 s4, 0xdb629599
	v_mad_u64_u32 v[14:15], s[42:43], v27, s4, v[14:15]
	v_mov_b32_e32 v18, v15
	s_mov_b32 s4, 0xf534ddc0
	v_mad_u64_u32 v[18:19], s[42:43], v27, s4, v[18:19]
	v_mov_b32_e32 v20, v19
	s_mov_b32 s4, 0xfc2757d1
	v_mad_u64_u32 v[20:21], s[42:43], v27, s4, v[20:21]
	v_mov_b32_e32 v22, v21
	s_mov_b32 s4, 0x4e441529
	v_mad_u64_u32 v[22:23], s[42:43], v27, s4, v[22:23]
	v_mov_b32_e32 v24, v23
	v_mov_b32_e32 v25, v1
	s_mov_b32 s4, 0xa2f9836e
	v_mad_u64_u32 v[24:25], s[42:43], v27, s4, v[24:25]
	v_cndmask_b32_e32 v11, v22, v18, vcc
	v_cndmask_b32_e32 v13, v24, v20, vcc
	v_cndmask_b32_e32 v19, v25, v22, vcc
	v_cndmask_b32_e64 v15, v13, v11, s[0:1]
	v_cndmask_b32_e64 v13, v19, v13, s[0:1]
	v_cndmask_b32_e32 v19, v20, v14, vcc
	v_cndmask_b32_e64 v11, v11, v19, s[0:1]
	v_cndmask_b32_e32 v12, v18, v12, vcc
	v_cndmask_b32_e64 v13, v13, v15, s[40:41]
	v_cndmask_b32_e64 v15, v15, v11, s[40:41]
	v_sub_u32_e32 v20, 32, v26
	v_cndmask_b32_e64 v18, v19, v12, s[0:1]
	v_alignbit_b32 v21, v13, v15, v20
	v_cmp_eq_u32_e64 s[42:43], 0, v26
	v_cndmask_b32_e64 v11, v11, v18, s[40:41]
	v_alignbit_b32 v19, v15, v11, v20
	v_cndmask_b32_e64 v13, v21, v13, s[42:43]
	v_cndmask_b32_e32 v10, v14, v10, vcc
	v_cndmask_b32_e64 v15, v19, v15, s[42:43]
	v_bfe_u32 v22, v13, 29, 1
	v_cndmask_b32_e64 v10, v12, v10, s[0:1]
	v_alignbit_b32 v19, v13, v15, 30
	v_sub_u32_e32 v23, 0, v22
	v_cndmask_b32_e64 v10, v18, v10, s[40:41]
	v_xor_b32_e32 v19, v19, v23
	v_alignbit_b32 v12, v11, v10, v20
	v_cndmask_b32_e64 v11, v12, v11, s[42:43]
	v_ffbh_u32_e32 v14, v19
	v_alignbit_b32 v12, v15, v11, 30
	v_min_u32_e32 v14, 32, v14
	v_alignbit_b32 v10, v11, v10, 30
	v_xor_b32_e32 v12, v12, v23
	v_sub_u32_e32 v15, 31, v14
	v_xor_b32_e32 v10, v10, v23
	v_alignbit_b32 v18, v19, v12, v15
	v_alignbit_b32 v10, v12, v10, v15
	v_alignbit_b32 v11, v18, v10, 9
	v_ffbh_u32_e32 v12, v11
	v_min_u32_e32 v12, 32, v12
	v_lshrrev_b32_e32 v21, 29, v13
	v_not_b32_e32 v15, v12
	v_alignbit_b32 v10, v11, v10, v15
	v_lshlrev_b32_e32 v11, 31, v21
	v_or_b32_e32 v15, 0x33000000, v11
	v_add_lshl_u32 v12, v12, v14, 23
	v_lshrrev_b32_e32 v10, 9, v10
	v_sub_u32_e32 v12, v15, v12
	v_or_b32_e32 v11, 0.5, v11
	v_lshlrev_b32_e32 v14, 23, v14
	v_or_b32_e32 v10, v12, v10
	v_lshrrev_b32_e32 v12, 9, v18
	v_sub_u32_e32 v11, v11, v14
	v_or_b32_e32 v11, v12, v11
	v_mul_f32_e32 v12, 0x3fc90fda, v11
	s_mov_b32 s0, 0x3fc90fda
	v_fma_f32 v14, v11, s0, -v12
	v_fmac_f32_e32 v14, 0x33a22168, v11
	v_fmac_f32_e32 v14, 0x3fc90fda, v10
	v_lshrrev_b32_e32 v10, 30, v13
	v_add_f32_e32 v24, v12, v14
	v_add_u32_e32 v25, v22, v10

; DI float wave_sum(float v) { for (int o = 32; o; o >>= 1) v += __shfl_xor(v, o); return v; }
; DI void run_phase(const Params& p, int ph, unsigned char* smem, const int tid, const int rep) {
;     ...
;           for (int t0 = (blockIdx.x * 8 + wv) * 4; t0 < TS; t0 += gridDim.x * 32) {
;               u32x2 vq[4]; unsigned vkv[4], vf[4][8];
; #pragma unroll
;               for (int u = 0; u < 4; ++u) { const bf16_t* pr = proj + (size_t)(t0 + u) * PLD; vq[u] = *(const u32x2*)(pr + 2048 + 4 * lane); vkv[u] = *(const unsigned*)(pr + 2304 + 2 * lane);
; #pragma unroll
;                   for (int hq = 0; hq < 8; ++hq) vf[u][hq] = *(const unsigned*)(pr + 3520 + hq * 128 + 2 * lane); }
; #pragma unroll
;               for (int u = 0; u < 4; ++u) { const int t = t0 + u; bf16_t* pr = proj + (size_t)t * PLD;
;                   { const u32x2 v = vq[u]; const float a0 = __uint_as_float(v[0] << 16), a1 = __uint_as_float(v[0] & 0xffff0000u), a2 = __uint_as_float(v[1] << 16), a3 = __uint_as_float(v[1] & 0xffff0000u);
;                     const float rs = rsqrtf(wave_sum(a0 * a0 + a1 * a1 + a2 * a2 + a3 * a3) * (1.f / 256.f) + NEPS);
.LBB0_372:
	v_mov_b64_e32 v[14:15], s[30:31]
	v_mad_i64_i32 v[16:17], s[0:1], v44, s3, v[14:15]
	v_lshl_add_u64 v[18:19], v[16:17], 0, v[0:1]
	v_add_co_u32_e32 v18, vcc, 0x1000, v18
	v_mov_b32_e32 v13, v1
	s_nop 0
	v_addc_co_u32_e32 v19, vcc, 0, v19, vcc
	v_lshl_add_u64 v[16:17], v[16:17], 0, v[12:13]
	global_load_dwordx2 v[18:19], v[18:19], off
	v_add_co_u32_e32 v36, vcc, 0x1000, v16
	v_add_u32_e32 v79, 1, v44
	s_nop 0
	v_addc_co_u32_e32 v37, vcc, 0, v17, vcc
	global_load_dword v89, v[36:37], off offset:512
	v_lshl_add_u64 v[34:35], v[16:17], 0, s[34:35]
	global_load_dword v88, v[36:37], off offset:2944
	global_load_dword v87, v[34:35], off offset:256
	global_load_dword v86, v[34:35], off offset:512
	global_load_dword v85, v[34:35], off offset:768
	global_load_dword v84, v[34:35], off offset:1024
	global_load_dword v83, v[34:35], off offset:1280
	global_load_dword v82, v[34:35], off offset:1536
	global_load_dword v81, v[34:35], off offset:1792
	v_mad_i64_i32 v[16:17], s[0:1], v79, s3, v[14:15]
	v_lshl_add_u64 v[20:21], v[16:17], 0, v[0:1]
	v_add_co_u32_e32 v20, vcc, s87, v20
	v_lshl_add_u64 v[16:17], v[16:17], 0, v[12:13]
	s_nop 0
	v_addc_co_u32_e32 v21, vcc, 0, v21, vcc
	v_add_co_u32_e32 v32, vcc, s87, v16
	v_add_u32_e32 v69, 2, v44
	s_nop 0
	v_addc_co_u32_e32 v33, vcc, 0, v17, vcc
	v_lshl_add_u64 v[28:29], v[16:17], 0, s[34:35]
	v_mad_i64_i32 v[16:17], s[0:1], v69, s3, v[14:15]
	global_load_dwordx2 v[40:41], v[20:21], off
	global_load_dword v80, v[32:33], off offset:512
	v_lshl_add_u64 v[20:21], v[16:17], 0, v[0:1]
	v_add_co_u32_e32 v20, vcc, s87, v20
	v_lshl_add_u64 v[16:17], v[16:17], 0, v[12:13]
	s_nop 0
	v_addc_co_u32_e32 v21, vcc, 0, v21, vcc
	v_add_co_u32_e32 v26, vcc, s87, v16
	v_add_u32_e32 v59, 3, v44
	s_nop 0
	v_addc_co_u32_e32 v27, vcc, 0, v17, vcc
	v_mad_i64_i32 v[14:15], s[0:1], v59, s3, v[14:15]
	global_load_dword v78, v[32:33], off offset:2944
	global_load_dword v77, v[28:29], off offset:256
	global_load_dword v76, v[28:29], off offset:512
	global_load_dword v75, v[28:29], off offset:768
	global_load_dword v74, v[28:29], off offset:1024
	global_load_dword v73, v[28:29], off offset:1280
	global_load_dword v72, v[28:29], off offset:1536
	global_load_dword v71, v[28:29], off offset:1792
	global_load_dwordx2 v[30:31], v[20:21], off
	global_load_dword v70, v[26:27], off offset:512
	v_lshl_add_u64 v[22:23], v[16:17], 0, s[34:35]
	v_lshl_add_u64 v[16:17], v[14:15], 0, v[0:1]
	v_add_co_u32_e32 v16, vcc, s87, v16
	v_lshl_add_u64 v[14:15], v[14:15], 0, v[12:13]
	s_nop 0
	v_addc_co_u32_e32 v17, vcc, 0, v17, vcc
	global_load_dword v68, v[26:27], off offset:2944
	global_load_dword v67, v[22:23], off offset:256
	global_load_dword v66, v[22:23], off offset:512
	global_load_dword v65, v[22:23], off offset:768
	global_load_dword v64, v[22:23], off offset:1024
	global_load_dword v63, v[22:23], off offset:1280
	global_load_dword v62, v[22:23], off offset:1536
	global_load_dword v61, v[22:23], off offset:1792
	global_load_dwordx2 v[24:25], v[16:17], off
	v_add_co_u32_e32 v16, vcc, s87, v14
	s_waitcnt vmcnt(0)
	v_and_b32_e32 v43, 0xffff0000, v18
	v_and_b32_e32 v21, 0xffff0000, v19
	v_and_b32_e32 v20, s0, v18
	v_lshlrev_b32_e32 v42, 16, v18
	v_mul_f32_e32 v18, v43, v43
	v_lshlrev_b32_e32 v38, 16, v19
	v_mov_b32_e32 v39, v21
	v_pk_fma_f32 v[18:19], v[42:43], v[42:43], v[18:19] op_sel_hi:[1,1,0]
	v_lshlrev_b32_e32 v96, 16, v89
	v_and_b32_e32 v97, 0xffff0000, v89
	v_pk_mul_f32 v[90:91], v[20:21], v[20:21]
	v_pk_fma_f32 v[18:19], v[38:39], v[38:39], v[18:19]
	v_pk_mul_f32 v[98:99], v[96:97], v[96:97]
	v_mov_b64_e32 v[20:21], s[12:13]
	v_mov_b32_e32 v90, v98
	v_pk_mov_b32 v[18:19], v[98:99], v[18:19] op_sel:[1,0]
	v_mad_i64_i32 v[92:93], s[0:1], v44, s22, v[20:21]
	v_pk_add_f32 v[18:19], v[90:91], v[18:19]
	v_mov_b32_e32 v91, v19
	v_mov_b32_e32 v90, v18
	s_nop 0
	v_permlane32_swap_b32_e32 v91, v19
	v_permlane32_swap_b32_e32 v90, v18
	v_addc_co_u32_e32 v17, vcc, 0, v15, vcc
	v_lshl_add_u64 v[94:95], v[92:93], 0, v[0:1]
	global_load_dword v60, v[16:17], off offset:512
	s_waitcnt lgkmcnt(0)
	v_pk_add_f32 v[18:19], v[18:19], v[90:91]
	v_mov_b32_e32 v91, v19
	v_mov_b32_e32 v90, v18
	s_nop 0
	v_permlane16_swap_b32_e32 v91, v19
	v_permlane16_swap_b32_e32 v90, v18
	v_lshl_add_u64 v[14:15], v[14:15], 0, s[34:35]
	global_load_dword v58, v[16:17], off offset:2944
	global_load_dword v57, v[14:15], off offset:256
	global_load_dword v56, v[14:15], off offset:512
	global_load_dword v55, v[14:15], off offset:768
	global_load_dword v54, v[14:15], off offset:1024
	global_load_dword v53, v[14:15], off offset:1280
	global_load_dword v52, v[14:15], off offset:1536
	global_load_dword v51, v[14:15], off offset:1792
	v_add_u32_e32 v44, s4, v44
	s_waitcnt lgkmcnt(0)
	v_pk_add_f32 v[18:19], v[18:19], v[90:91]
	s_nop 1
	v_add_f32_dpp v19, v19, v19 row_ror:8 row_mask:0xf bank_mask:0xf
	v_add_f32_dpp v18, v18, v18 row_ror:8 row_mask:0xf bank_mask:0xf
	s_waitcnt lgkmcnt(0)
	s_nop 1
	v_add_f32_dpp v19, v19, v19 row_ror:4 row_mask:0xf bank_mask:0xf
	v_add_f32_dpp v18, v18, v18 row_ror:4 row_mask:0xf bank_mask:0xf
	s_waitcnt lgkmcnt(0)
	s_nop 1
	v_add_f32_dpp v19, v19, v19 quad_perm:[2,3,0,1] row_mask:0xf bank_mask:0xf
	v_add_f32_dpp v18, v18, v18 quad_perm:[2,3,0,1] row_mask:0xf bank_mask:0xf
	s_waitcnt lgkmcnt(0)
	s_nop 1
	v_add_f32_dpp v91, v19, v19 quad_perm:[1,0,3,2] row_mask:0xf bank_mask:0xf
	v_add_f32_dpp v90, v18, v18 quad_perm:[1,0,3,2] row_mask:0xf bank_mask:0xf
	s_waitcnt lgkmcnt(0)
; DI unsigned pk2(float lo, float hi) { const f32x2 v = {lo, hi}; return __builtin_bit_cast(unsigned, __builtin_convertvector(v, bf16v2_t)); }
; DI float wave_sum(float v) { for (int o = 32; o; o >>= 1) v += __shfl_xor(v, o); return v; }
; DI void run_phase(const Params& p, int ph, unsigned char* smem, const int tid, const int rep) {
;     ...
;               for (int u = 0; u < 4; ++u) { const int t = t0 + u; bf16_t* pr = proj + (size_t)t * PLD;
;                   { const u32x2 v = vq[u]; const float a0 = __uint_as_float(v[0] << 16), a1 = __uint_as_float(v[0] & 0xffff0000u), a2 = __uint_as_float(v[1] << 16), a3 = __uint_as_float(v[1] & 0xffff0000u);
;                     const float rs = rsqrtf(wave_sum(a0 * a0 + a1 * a1 + a2 * a2 + a3 * a3) * (1.f / 256.f) + NEPS);
;                     u32x2 o; o[0] = pk2(a0 * rs * ggq[0], a1 * rs * ggq[1]); o[1] = pk2(a2 * rs * ggq[2], a3 * rs * ggq[3]); *(u32x2*)(mlaa + (size_t)t * 384 + 4 * lane) = o; }
;                   { const unsigned v = vkv[u]; const float a0 = __uint_as_float(v << 16), a1 = __uint_as_float(v & 0xffff0000u);
;                     const float rs = rsqrtf(wave_sum(a0 * a0 + a1 * a1) * (1.f / 128.f) + NEPS);
;                     *(unsigned*)(mlaa + (size_t)t * 384 + 256 + 2 * lane) = pk2(a0 * rs * gkv0, a1 * rs * gkv1); }
; #pragma unroll
;                   for (int hq = 0; hq < 8; ++hq) { const unsigned v = vf[u][hq]; const float a0 = __uint_as_float(v << 16), a1 = __uint_as_float(v & 0xffff0000u);
;                     const float rs = rsqrtf(wave_sum(a0 * a0 + a1 * a1) * (1.f / 128.f) + NEPS) * ((hq < 4) ? 0.08838834764831845f * LOG2E : 1.f);
;                     *(unsigned*)(pr + 3520 + hq * 128 + 2 * lane) = pk2(a0 * rs * ((hq < 4) ? fq0 : fk0), a1 * rs * ((hq < 4) ? fq1 : fk1)); } } } }
	v_mov_b64_e32 v[18:19], s[72:73]
	v_pk_fma_f32 v[90:91], v[90:91], s[96:97], v[18:19] op_sel_hi:[1,1,0]
	s_nop 0
	v_cmp_gt_f32_e64 s[0:1], s77, v91
	v_cmp_gt_f32_e32 vcc, s77, v90
	s_nop 0
	v_rsq_f32_e32 v89, v91
	s_nop 0
	v_mov_b32_e32 v98, v89
	v_pk_mul_f32 v[42:43], v[98:99], v[42:43] op_sel_hi:[0,1]
	v_pk_mul_f32 v[38:39], v[98:99], v[38:39] op_sel_hi:[0,1]
	v_pk_mul_f32 v[42:43], v[2:3], v[42:43]
	v_pk_mul_f32 v[38:39], v[4:5], v[38:39]
	v_cvt_pk_bf16_f32 v42, v42, v43
	v_cvt_pk_bf16_f32 v43, v38, v39
	v_rsq_f32_e32 v38, v90
	global_store_dwordx2 v[94:95], v[42:43], off
	v_and_b32_e32 v89, 0xffff0000, v87
	v_pk_mul_f32 v[38:39], v[38:39], v[96:97] op_sel_hi:[0,1]
	v_pk_mul_f32 v[38:39], v[6:7], v[38:39]
	s_nop 0
	v_cvt_pk_bf16_f32 v42, v38, v39
	v_lshl_add_u64 v[38:39], v[92:93], 0, v[12:13]
	global_store_dword v[38:39], v42, off offset:512
	v_lshlrev_b32_e32 v38, 16, v88
	v_and_b32_e32 v39, 0xffff0000, v88
	v_lshlrev_b32_e32 v88, 16, v87
	v_pk_mul_f32 v[42:43], v[38:39], v[38:39]
	v_pk_mul_f32 v[90:91], v[88:89], v[88:89]
	v_mov_b32_e32 v93, v42
	v_mov_b32_e32 v92, v90
	v_mov_b32_e32 v42, v91
	v_pk_add_f32 v[42:43], v[92:93], v[42:43]
	v_mov_b32_e32 v91, v43
	v_mov_b32_e32 v90, v42
	s_nop 0
	v_permlane32_swap_b32_e32 v91, v43
	v_permlane32_swap_b32_e32 v90, v42
	s_waitcnt lgkmcnt(0)
	v_pk_add_f32 v[42:43], v[42:43], v[90:91]
	v_mov_b32_e32 v91, v43
	v_mov_b32_e32 v90, v42
	s_nop 0
	v_permlane16_swap_b32_e32 v91, v43
	v_permlane16_swap_b32_e32 v90, v42
	s_waitcnt lgkmcnt(0)
	v_pk_add_f32 v[42:43], v[42:43], v[90:91]
	s_nop 1
	v_add_f32_dpp v43, v43, v43 row_ror:8 row_mask:0xf bank_mask:0xf
	v_add_f32_dpp v42, v42, v42 row_ror:8 row_mask:0xf bank_mask:0xf
	s_waitcnt lgkmcnt(0)
	s_nop 1
	v_add_f32_dpp v43, v43, v43 row_ror:4 row_mask:0xf bank_mask:0xf
	v_add_f32_dpp v42, v42, v42 row_ror:4 row_mask:0xf bank_mask:0xf
	s_waitcnt lgkmcnt(0)
	s_nop 1
	v_add_f32_dpp v43, v43, v43 quad_perm:[2,3,0,1] row_mask:0xf bank_mask:0xf
	v_add_f32_dpp v42, v42, v42 quad_perm:[2,3,0,1] row_mask:0xf bank_mask:0xf
	s_waitcnt lgkmcnt(0)
	s_nop 1
	v_add_f32_dpp v43, v43, v43 quad_perm:[1,0,3,2] row_mask:0xf bank_mask:0xf
	v_add_f32_dpp v42, v42, v42 quad_perm:[1,0,3,2] row_mask:0xf bank_mask:0xf
	s_waitcnt lgkmcnt(0)
	s_nop 0
	v_pk_fma_f32 v[42:43], v[42:43], s[96:97], v[18:19] op_sel_hi:[1,0,0]
	s_nop 0
	v_cmp_gt_f32_e64 s[0:1], s77, v43
	v_cmp_gt_f32_e32 vcc, s77, v42
	s_nop 0
	v_rsq_f32_e32 v43, v43
	s_nop 0
	v_mul_f32_e32 v90, 0x3e0293ee, v43
	v_pk_mul_f32 v[38:39], v[90:91], v[38:39] op_sel_hi:[0,1]
	v_pk_mul_f32 v[38:39], v[8:9], v[38:39]
	v_and_b32_e32 v43, 0xffff0000, v85
	v_cvt_pk_bf16_f32 v38, v38, v39
	global_store_dword v[36:37], v38, off offset:2944
	v_rsq_f32_e32 v36, v42
	v_lshlrev_b32_e32 v42, 16, v85
	v_mul_f32_e32 v36, 0x3e0293ee, v36
	v_pk_mul_f32 v[36:37], v[36:37], v[88:89] op_sel_hi:[0,1]
	v_pk_mul_f32 v[36:37], v[8:9], v[36:37]
	s_nop 0
	v_cvt_pk_bf16_f32 v36, v36, v37
	global_store_dword v[34:35], v36, off offset:256
	v_lshlrev_b32_e32 v36, 16, v86
	v_and_b32_e32 v37, 0xffff0000, v86
	v_pk_mul_f32 v[38:39], v[36:37], v[36:37]
	v_pk_mul_f32 v[86:87], v[42:43], v[42:43]
	v_mov_b32_e32 v89, v38
	v_mov_b32_e32 v88, v86
	v_mov_b32_e32 v38, v87
	v_pk_add_f32 v[38:39], v[88:89], v[38:39]
	v_mov_b32_e32 v87, v39
	v_mov_b32_e32 v86, v38
	s_nop 0
	v_permlane32_swap_b32_e32 v87, v39
	v_permlane32_swap_b32_e32 v86, v38
	s_waitcnt lgkmcnt(0)
	v_pk_add_f32 v[38:39], v[38:39], v[86:87]
	v_mov_b32_e32 v87, v39
	v_mov_b32_e32 v86, v38
	s_nop 0
	v_permlane16_swap_b32_e32 v87, v39
	v_permlane16_swap_b32_e32 v86, v38
	s_waitcnt lgkmcnt(0)
	v_pk_add_f32 v[38:39], v[38:39], v[86:87]
	s_nop 1
	v_add_f32_dpp v39, v39, v39 row_ror:8 row_mask:0xf bank_mask:0xf
	v_add_f32_dpp v38, v38, v38 row_ror:8 row_mask:0xf bank_mask:0xf
	s_waitcnt lgkmcnt(0)
	s_nop 1
	v_add_f32_dpp v39, v39, v39 row_ror:4 row_mask:0xf bank_mask:0xf
	v_add_f32_dpp v38, v38, v38 row_ror:4 row_mask:0xf bank_mask:0xf
	s_waitcnt lgkmcnt(0)
	s_nop 1
	v_add_f32_dpp v39, v39, v39 quad_perm:[2,3,0,1] row_mask:0xf bank_mask:0xf
	v_add_f32_dpp v38, v38, v38 quad_perm:[2,3,0,1] row_mask:0xf bank_mask:0xf
	s_waitcnt lgkmcnt(0)
	s_nop 1
	v_add_f32_dpp v39, v39, v39 quad_perm:[1,0,3,2] row_mask:0xf bank_mask:0xf
	v_add_f32_dpp v38, v38, v38 quad_perm:[1,0,3,2] row_mask:0xf bank_mask:0xf
	s_waitcnt lgkmcnt(0)
	s_nop 0
	v_pk_fma_f32 v[38:39], v[38:39], s[96:97], v[18:19] op_sel_hi:[1,0,0]
	s_nop 0
	v_cmp_gt_f32_e64 s[0:1], s77, v39
	v_cmp_gt_f32_e32 vcc, s77, v38
	s_nop 0
	v_rsq_f32_e32 v39, v39
	s_nop 0
	v_mul_f32_e32 v86, 0x3e0293ee, v39
	v_pk_mul_f32 v[36:37], v[86:87], v[36:37] op_sel_hi:[0,1]
	v_pk_mul_f32 v[36:37], v[8:9], v[36:37]
	s_nop 0
	v_cvt_pk_bf16_f32 v36, v36, v37
	global_store_dword v[34:35], v36, off offset:512
	v_rsq_f32_e32 v36, v38
	s_nop 0
	v_mul_f32_e32 v36, 0x3e0293ee, v36
	v_pk_mul_f32 v[36:37], v[36:37], v[42:43] op_sel_hi:[0,1]
	v_pk_mul_f32 v[36:37], v[8:9], v[36:37]
	v_lshlrev_b32_e32 v42, 16, v83
	v_cvt_pk_bf16_f32 v36, v36, v37
	global_store_dword v[34:35], v36, off offset:768
	v_lshlrev_b32_e32 v36, 16, v84
	v_and_b32_e32 v37, 0xffff0000, v84
	v_and_b32_e32 v43, 0xffff0000, v83
	v_pk_mul_f32 v[38:39], v[36:37], v[36:37]
	v_pk_mul_f32 v[84:85], v[42:43], v[42:43]
	v_mov_b32_e32 v87, v38
	v_mov_b32_e32 v86, v84
	v_mov_b32_e32 v38, v85
	v_pk_add_f32 v[38:39], v[86:87], v[38:39]
	v_mov_b32_e32 v85, v39
	v_mov_b32_e32 v84, v38
	s_nop 0
	v_permlane32_swap_b32_e32 v85, v39
	v_permlane32_swap_b32_e32 v84, v38
	s_waitcnt lgkmcnt(0)
	v_pk_add_f32 v[38:39], v[38:39], v[84:85]
	v_mov_b32_e32 v85, v39
	v_mov_b32_e32 v84, v38
	s_nop 0
	v_permlane16_swap_b32_e32 v85, v39
	v_permlane16_swap_b32_e32 v84, v38
	s_waitcnt lgkmcnt(0)
; DI unsigned pk2(float lo, float hi) { const f32x2 v = {lo, hi}; return __builtin_bit_cast(unsigned, __builtin_convertvector(v, bf16v2_t)); }
; DI float wave_sum(float v) { for (int o = 32; o; o >>= 1) v += __shfl_xor(v, o); return v; }
; DI void run_phase(const Params& p, int ph, unsigned char* smem, const int tid, const int rep) {
;     ...
;                   { const unsigned v = vkv[u]; const float a0 = __uint_as_float(v << 16), a1 = __uint_as_float(v & 0xffff0000u);
;                     const float rs = rsqrtf(wave_sum(a0 * a0 + a1 * a1) * (1.f / 128.f) + NEPS);
;                     *(unsigned*)(mlaa + (size_t)t * 384 + 256 + 2 * lane) = pk2(a0 * rs * gkv0, a1 * rs * gkv1); }
; #pragma unroll
;                   for (int hq = 0; hq < 8; ++hq) { const unsigned v = vf[u][hq]; const float a0 = __uint_as_float(v << 16), a1 = __uint_as_float(v & 0xffff0000u);
;                     const float rs = rsqrtf(wave_sum(a0 * a0 + a1 * a1) * (1.f / 128.f) + NEPS) * ((hq < 4) ? 0.08838834764831845f * LOG2E : 1.f);
;                     *(unsigned*)(pr + 3520 + hq * 128 + 2 * lane) = pk2(a0 * rs * ((hq < 4) ? fq0 : fk0), a1 * rs * ((hq < 4) ? fq1 : fk1)); } } } }
	v_pk_add_f32 v[38:39], v[38:39], v[84:85]
	s_nop 1
	v_add_f32_dpp v39, v39, v39 row_ror:8 row_mask:0xf bank_mask:0xf
	v_add_f32_dpp v38, v38, v38 row_ror:8 row_mask:0xf bank_mask:0xf
	s_waitcnt lgkmcnt(0)
	s_nop 1
	v_add_f32_dpp v39, v39, v39 row_ror:4 row_mask:0xf bank_mask:0xf
	v_add_f32_dpp v38, v38, v38 row_ror:4 row_mask:0xf bank_mask:0xf
	s_waitcnt lgkmcnt(0)
	s_nop 1
	v_add_f32_dpp v39, v39, v39 quad_perm:[2,3,0,1] row_mask:0xf bank_mask:0xf
	v_add_f32_dpp v38, v38, v38 quad_perm:[2,3,0,1] row_mask:0xf bank_mask:0xf
	s_waitcnt lgkmcnt(0)
	s_nop 1
	v_add_f32_dpp v39, v39, v39 quad_perm:[1,0,3,2] row_mask:0xf bank_mask:0xf
	v_add_f32_dpp v38, v38, v38 quad_perm:[1,0,3,2] row_mask:0xf bank_mask:0xf
	s_waitcnt lgkmcnt(0)
	s_nop 0
	v_pk_fma_f32 v[38:39], v[38:39], s[96:97], v[18:19] op_sel_hi:[1,0,0]
	s_nop 0
	v_cmp_gt_f32_e64 s[0:1], s77, v39
	v_cmp_gt_f32_e32 vcc, s77, v38
	s_nop 0
	v_rsq_f32_e32 v39, v39
	s_nop 0
	v_mov_b32_e32 v84, v39
	v_pk_mul_f32 v[36:37], v[84:85], v[36:37] op_sel_hi:[0,1]
	v_pk_mul_f32 v[36:37], v[10:11], v[36:37]
	s_nop 0
	v_cvt_pk_bf16_f32 v36, v36, v37
	global_store_dword v[34:35], v36, off offset:1024
	v_rsq_f32_e32 v36, v38
	s_nop 0
	v_pk_mul_f32 v[36:37], v[36:37], v[42:43] op_sel_hi:[0,1]
	v_pk_mul_f32 v[36:37], v[10:11], v[36:37]
	v_lshlrev_b32_e32 v42, 16, v81
	v_cvt_pk_bf16_f32 v36, v36, v37
	global_store_dword v[34:35], v36, off offset:1280
	v_lshlrev_b32_e32 v36, 16, v82
	v_and_b32_e32 v37, 0xffff0000, v82
	v_and_b32_e32 v43, 0xffff0000, v81
	v_pk_mul_f32 v[38:39], v[36:37], v[36:37]
	v_pk_mul_f32 v[82:83], v[42:43], v[42:43]
	v_mov_b32_e32 v85, v38
	v_mov_b32_e32 v84, v82
	v_mov_b32_e32 v38, v83
	v_pk_add_f32 v[38:39], v[84:85], v[38:39]
	v_mov_b32_e32 v83, v39
	v_mov_b32_e32 v82, v38
	s_nop 0
	v_permlane32_swap_b32_e32 v83, v39
	v_permlane32_swap_b32_e32 v82, v38
	v_lshlrev_b32_e32 v84, 16, v80
	v_and_b32_e32 v85, 0xffff0000, v80
	s_waitcnt lgkmcnt(0)
	v_pk_add_f32 v[38:39], v[38:39], v[82:83]
	v_mov_b32_e32 v83, v39
	v_mov_b32_e32 v82, v38
	s_nop 0
	v_permlane16_swap_b32_e32 v83, v39
	v_permlane16_swap_b32_e32 v82, v38
	s_waitcnt lgkmcnt(0)
	v_pk_add_f32 v[38:39], v[38:39], v[82:83]
	s_nop 1
	v_add_f32_dpp v39, v39, v39 row_ror:8 row_mask:0xf bank_mask:0xf
	v_add_f32_dpp v38, v38, v38 row_ror:8 row_mask:0xf bank_mask:0xf
	s_waitcnt lgkmcnt(0)
	s_nop 1
	v_add_f32_dpp v39, v39, v39 row_ror:4 row_mask:0xf bank_mask:0xf
	v_add_f32_dpp v38, v38, v38 row_ror:4 row_mask:0xf bank_mask:0xf
	s_waitcnt lgkmcnt(0)
	s_nop 1
	v_add_f32_dpp v39, v39, v39 quad_perm:[2,3,0,1] row_mask:0xf bank_mask:0xf
	v_add_f32_dpp v38, v38, v38 quad_perm:[2,3,0,1] row_mask:0xf bank_mask:0xf
	s_waitcnt lgkmcnt(0)
	s_nop 1
	v_add_f32_dpp v39, v39, v39 quad_perm:[1,0,3,2] row_mask:0xf bank_mask:0xf
	v_add_f32_dpp v38, v38, v38 quad_perm:[1,0,3,2] row_mask:0xf bank_mask:0xf
	s_waitcnt lgkmcnt(0)
	s_nop 0
	v_pk_fma_f32 v[38:39], v[38:39], s[96:97], v[18:19] op_sel_hi:[1,0,0]
	s_nop 0
	v_cmp_gt_f32_e64 s[0:1], s77, v39
	v_cmp_gt_f32_e32 vcc, s77, v38
	s_nop 0
	v_rsq_f32_e32 v39, v39
	s_nop 0
	v_mov_b32_e32 v82, v39
	v_pk_mul_f32 v[36:37], v[82:83], v[36:37] op_sel_hi:[0,1]
	v_pk_mul_f32 v[36:37], v[10:11], v[36:37]
	v_pk_mul_f32 v[80:81], v[84:85], v[84:85]
	v_cvt_pk_bf16_f32 v36, v36, v37
	global_store_dword v[34:35], v36, off offset:1536
	v_rsq_f32_e32 v36, v38
	s_nop 0
	v_pk_mul_f32 v[36:37], v[36:37], v[42:43] op_sel_hi:[0,1]
	v_pk_mul_f32 v[36:37], v[10:11], v[36:37]
	s_nop 0
	v_cvt_pk_bf16_f32 v36, v36, v37
	global_store_dword v[34:35], v36, off offset:1792
	v_and_b32_e32 v37, 0xffff0000, v41
	v_and_b32_e32 v36, s0, v40
	v_mov_b32_e32 v35, v37
	v_pk_mul_f32 v[38:39], v[36:37], v[36:37]
	v_and_b32_e32 v37, 0xffff0000, v40
	v_lshlrev_b32_e32 v36, 16, v40
	v_mul_f32_e32 v38, v37, v37
	v_lshlrev_b32_e32 v34, 16, v41
	v_pk_fma_f32 v[40:41], v[36:37], v[36:37], v[38:39] op_sel_hi:[1,1,0]
	v_mov_b32_e32 v38, v80
	v_pk_fma_f32 v[40:41], v[34:35], v[34:35], v[40:41]
	v_mad_i64_i32 v[42:43], s[0:1], v79, s22, v[20:21]
	v_pk_mov_b32 v[40:41], v[80:81], v[40:41] op_sel:[1,0]
	v_lshl_add_u64 v[82:83], v[42:43], 0, v[0:1]
	v_pk_add_f32 v[38:39], v[38:39], v[40:41]
	v_mov_b32_e32 v41, v39
	v_mov_b32_e32 v40, v38
	s_nop 0
	v_permlane32_swap_b32_e32 v41, v39
	v_permlane32_swap_b32_e32 v40, v38
	s_waitcnt lgkmcnt(0)
	v_pk_add_f32 v[38:39], v[38:39], v[40:41]
	v_mov_b32_e32 v41, v39
	v_mov_b32_e32 v40, v38
	s_nop 0
	v_permlane16_swap_b32_e32 v41, v39
	v_permlane16_swap_b32_e32 v40, v38
	s_waitcnt lgkmcnt(0)
	v_pk_add_f32 v[38:39], v[38:39], v[40:41]
	s_nop 1
	v_add_f32_dpp v39, v39, v39 row_ror:8 row_mask:0xf bank_mask:0xf
	v_add_f32_dpp v38, v38, v38 row_ror:8 row_mask:0xf bank_mask:0xf
	s_waitcnt lgkmcnt(0)
	s_nop 1
	v_add_f32_dpp v39, v39, v39 row_ror:4 row_mask:0xf bank_mask:0xf
	v_add_f32_dpp v38, v38, v38 row_ror:4 row_mask:0xf bank_mask:0xf
	s_waitcnt lgkmcnt(0)
	s_nop 1
	v_add_f32_dpp v39, v39, v39 quad_perm:[2,3,0,1] row_mask:0xf bank_mask:0xf
	v_add_f32_dpp v38, v38, v38 quad_perm:[2,3,0,1] row_mask:0xf bank_mask:0xf
	s_waitcnt lgkmcnt(0)
	s_nop 1
	v_add_f32_dpp v39, v39, v39 quad_perm:[1,0,3,2] row_mask:0xf bank_mask:0xf
	v_add_f32_dpp v38, v38, v38 quad_perm:[1,0,3,2] row_mask:0xf bank_mask:0xf
	s_waitcnt lgkmcnt(0)
; DI unsigned pk2(float lo, float hi) { const f32x2 v = {lo, hi}; return __builtin_bit_cast(unsigned, __builtin_convertvector(v, bf16v2_t)); }
; DI float wave_sum(float v) { for (int o = 32; o; o >>= 1) v += __shfl_xor(v, o); return v; }
; DI void run_phase(const Params& p, int ph, unsigned char* smem, const int tid, const int rep) {
;     ...
;               for (int u = 0; u < 4; ++u) { const int t = t0 + u; bf16_t* pr = proj + (size_t)t * PLD;
;                   { const u32x2 v = vq[u]; const float a0 = __uint_as_float(v[0] << 16), a1 = __uint_as_float(v[0] & 0xffff0000u), a2 = __uint_as_float(v[1] << 16), a3 = __uint_as_float(v[1] & 0xffff0000u);
;                     const float rs = rsqrtf(wave_sum(a0 * a0 + a1 * a1 + a2 * a2 + a3 * a3) * (1.f / 256.f) + NEPS);
;                     u32x2 o; o[0] = pk2(a0 * rs * ggq[0], a1 * rs * ggq[1]); o[1] = pk2(a2 * rs * ggq[2], a3 * rs * ggq[3]); *(u32x2*)(mlaa + (size_t)t * 384 + 4 * lane) = o; }
;                   { const unsigned v = vkv[u]; const float a0 = __uint_as_float(v << 16), a1 = __uint_as_float(v & 0xffff0000u);
;                     const float rs = rsqrtf(wave_sum(a0 * a0 + a1 * a1) * (1.f / 128.f) + NEPS);
;                     *(unsigned*)(mlaa + (size_t)t * 384 + 256 + 2 * lane) = pk2(a0 * rs * gkv0, a1 * rs * gkv1); }
; #pragma unroll
;                   for (int hq = 0; hq < 8; ++hq) { const unsigned v = vf[u][hq]; const float a0 = __uint_as_float(v << 16), a1 = __uint_as_float(v & 0xffff0000u);
;                     const float rs = rsqrtf(wave_sum(a0 * a0 + a1 * a1) * (1.f / 128.f) + NEPS) * ((hq < 4) ? 0.08838834764831845f * LOG2E : 1.f);
;                     *(unsigned*)(pr + 3520 + hq * 128 + 2 * lane) = pk2(a0 * rs * ((hq < 4) ? fq0 : fk0), a1 * rs * ((hq < 4) ? fq1 : fk1)); } } } }
	s_nop 0
	v_pk_fma_f32 v[38:39], v[38:39], s[96:97], v[18:19] op_sel_hi:[1,1,0]
	s_nop 0
	v_cmp_gt_f32_e64 s[0:1], s77, v39
	v_cmp_gt_f32_e32 vcc, s77, v38
	s_nop 0
	v_rsq_f32_e32 v39, v39
	s_nop 0
	v_mov_b32_e32 v40, v39
	v_pk_mul_f32 v[36:37], v[40:41], v[36:37] op_sel_hi:[0,1]
	v_pk_mul_f32 v[34:35], v[40:41], v[34:35] op_sel_hi:[0,1]
	v_pk_mul_f32 v[36:37], v[2:3], v[36:37]
	v_pk_mul_f32 v[34:35], v[4:5], v[34:35]
	v_cvt_pk_bf16_f32 v36, v36, v37
	v_cvt_pk_bf16_f32 v37, v34, v35
	v_rsq_f32_e32 v34, v38
	global_store_dwordx2 v[82:83], v[36:37], off
	v_lshlrev_b32_e32 v38, 16, v77
	v_and_b32_e32 v39, 0xffff0000, v77
	v_pk_mul_f32 v[34:35], v[34:35], v[84:85] op_sel_hi:[0,1]
	v_pk_mul_f32 v[34:35], v[6:7], v[34:35]
	v_pk_mul_f32 v[40:41], v[38:39], v[38:39]
	v_cvt_pk_bf16_f32 v36, v34, v35
	v_lshl_add_u64 v[34:35], v[42:43], 0, v[12:13]
	global_store_dword v[34:35], v36, off offset:512
	v_lshlrev_b32_e32 v34, 16, v78
	v_and_b32_e32 v35, 0xffff0000, v78
	v_pk_mul_f32 v[36:37], v[34:35], v[34:35]
	v_mov_b32_e32 v42, v40
	v_mov_b32_e32 v43, v36
	v_mov_b32_e32 v36, v41
	v_pk_add_f32 v[36:37], v[42:43], v[36:37]
	v_mov_b32_e32 v41, v37
	v_mov_b32_e32 v40, v36
	s_nop 0
	v_permlane32_swap_b32_e32 v41, v37
	v_permlane32_swap_b32_e32 v40, v36
	s_waitcnt lgkmcnt(0)
	v_pk_add_f32 v[36:37], v[36:37], v[40:41]
	v_mov_b32_e32 v41, v37
	v_mov_b32_e32 v40, v36
	s_nop 0
	v_permlane16_swap_b32_e32 v41, v37
	v_permlane16_swap_b32_e32 v40, v36
	s_waitcnt lgkmcnt(0)
	v_pk_add_f32 v[36:37], v[36:37], v[40:41]
	s_nop 1
	v_add_f32_dpp v37, v37, v37 row_ror:8 row_mask:0xf bank_mask:0xf
	v_add_f32_dpp v36, v36, v36 row_ror:8 row_mask:0xf bank_mask:0xf
	s_waitcnt lgkmcnt(0)
	s_nop 1
	v_add_f32_dpp v37, v37, v37 row_ror:4 row_mask:0xf bank_mask:0xf
	v_add_f32_dpp v36, v36, v36 row_ror:4 row_mask:0xf bank_mask:0xf
	s_waitcnt lgkmcnt(0)
	s_nop 1
	v_add_f32_dpp v37, v37, v37 quad_perm:[2,3,0,1] row_mask:0xf bank_mask:0xf
	v_add_f32_dpp v36, v36, v36 quad_perm:[2,3,0,1] row_mask:0xf bank_mask:0xf
	s_waitcnt lgkmcnt(0)
	s_nop 1
	v_add_f32_dpp v37, v37, v37 quad_perm:[1,0,3,2] row_mask:0xf bank_mask:0xf
	v_add_f32_dpp v36, v36, v36 quad_perm:[1,0,3,2] row_mask:0xf bank_mask:0xf
	s_waitcnt lgkmcnt(0)
	s_nop 0
	v_pk_fma_f32 v[36:37], v[36:37], s[96:97], v[18:19] op_sel_hi:[1,0,0]
	s_nop 0
	v_cmp_gt_f32_e64 s[0:1], s77, v37
	v_cmp_gt_f32_e32 vcc, s77, v36
	s_nop 0
	v_rsq_f32_e32 v37, v37
	s_nop 0
	v_mul_f32_e32 v40, 0x3e0293ee, v37
	v_pk_mul_f32 v[34:35], v[40:41], v[34:35] op_sel_hi:[0,1]
	v_pk_mul_f32 v[34:35], v[8:9], v[34:35]
	v_and_b32_e32 v37, 0xffff0000, v75
	v_cvt_pk_bf16_f32 v34, v34, v35
	global_store_dword v[32:33], v34, off offset:2944
	v_rsq_f32_e32 v32, v36
	v_lshlrev_b32_e32 v36, 16, v75
	v_mul_f32_e32 v32, 0x3e0293ee, v32
	v_pk_mul_f32 v[32:33], v[32:33], v[38:39] op_sel_hi:[0,1]
	v_pk_mul_f32 v[32:33], v[8:9], v[32:33]
	v_pk_mul_f32 v[38:39], v[36:37], v[36:37]
	v_cvt_pk_bf16_f32 v32, v32, v33
	global_store_dword v[28:29], v32, off offset:256
	v_lshlrev_b32_e32 v32, 16, v76
	v_and_b32_e32 v33, 0xffff0000, v76
	v_pk_mul_f32 v[34:35], v[32:33], v[32:33]
	v_mov_b32_e32 v40, v38
	v_mov_b32_e32 v41, v34
	v_mov_b32_e32 v34, v39
	v_pk_add_f32 v[34:35], v[40:41], v[34:35]
	v_mov_b32_e32 v39, v35
	v_mov_b32_e32 v38, v34
	s_nop 0
	v_permlane32_swap_b32_e32 v39, v35
	v_permlane32_swap_b32_e32 v38, v34
	s_waitcnt lgkmcnt(0)
	v_pk_add_f32 v[34:35], v[34:35], v[38:39]
	v_mov_b32_e32 v39, v35
	v_mov_b32_e32 v38, v34
	s_nop 0
	v_permlane16_swap_b32_e32 v39, v35
	v_permlane16_swap_b32_e32 v38, v34
	s_waitcnt lgkmcnt(0)
	v_pk_add_f32 v[34:35], v[34:35], v[38:39]
	s_nop 1
	v_add_f32_dpp v35, v35, v35 row_ror:8 row_mask:0xf bank_mask:0xf
	v_add_f32_dpp v34, v34, v34 row_ror:8 row_mask:0xf bank_mask:0xf
	s_waitcnt lgkmcnt(0)
	s_nop 1
	v_add_f32_dpp v35, v35, v35 row_ror:4 row_mask:0xf bank_mask:0xf
	v_add_f32_dpp v34, v34, v34 row_ror:4 row_mask:0xf bank_mask:0xf
	s_waitcnt lgkmcnt(0)
	s_nop 1
	v_add_f32_dpp v35, v35, v35 quad_perm:[2,3,0,1] row_mask:0xf bank_mask:0xf
	v_add_f32_dpp v34, v34, v34 quad_perm:[2,3,0,1] row_mask:0xf bank_mask:0xf
	s_waitcnt lgkmcnt(0)
	s_nop 1
	v_add_f32_dpp v35, v35, v35 quad_perm:[1,0,3,2] row_mask:0xf bank_mask:0xf
	v_add_f32_dpp v34, v34, v34 quad_perm:[1,0,3,2] row_mask:0xf bank_mask:0xf
	s_waitcnt lgkmcnt(0)
	s_nop 0
	v_pk_fma_f32 v[34:35], v[34:35], s[96:97], v[18:19] op_sel_hi:[1,0,0]
	s_nop 0
	v_cmp_gt_f32_e64 s[0:1], s77, v35
	v_cmp_gt_f32_e32 vcc, s77, v34
	s_nop 0
	v_rsq_f32_e32 v35, v35
	s_nop 0
	v_mul_f32_e32 v38, 0x3e0293ee, v35
	v_pk_mul_f32 v[32:33], v[38:39], v[32:33] op_sel_hi:[0,1]
	v_pk_mul_f32 v[32:33], v[8:9], v[32:33]
	s_nop 0
	v_cvt_pk_bf16_f32 v32, v32, v33
	global_store_dword v[28:29], v32, off offset:512
	v_rsq_f32_e32 v32, v34
	s_nop 0
	v_mul_f32_e32 v32, 0x3e0293ee, v32
	v_pk_mul_f32 v[32:33], v[32:33], v[36:37] op_sel_hi:[0,1]
	v_pk_mul_f32 v[32:33], v[8:9], v[32:33]
	v_lshlrev_b32_e32 v36, 16, v73
	v_cvt_pk_bf16_f32 v32, v32, v33
	global_store_dword v[28:29], v32, off offset:768
	v_lshlrev_b32_e32 v32, 16, v74
	v_and_b32_e32 v33, 0xffff0000, v74
	v_and_b32_e32 v37, 0xffff0000, v73
	v_pk_mul_f32 v[34:35], v[32:33], v[32:33]
	v_pk_mul_f32 v[38:39], v[36:37], v[36:37]
	v_mov_b32_e32 v41, v34
	v_mov_b32_e32 v40, v38
	v_mov_b32_e32 v34, v39
	v_pk_add_f32 v[34:35], v[40:41], v[34:35]
	v_mov_b32_e32 v39, v35
	v_mov_b32_e32 v38, v34
	s_nop 0
	v_permlane32_swap_b32_e32 v39, v35
	v_permlane32_swap_b32_e32 v38, v34
	s_waitcnt lgkmcnt(0)
	v_pk_add_f32 v[34:35], v[34:35], v[38:39]
	v_mov_b32_e32 v39, v35
	v_mov_b32_e32 v38, v34
	s_nop 0
	v_permlane16_swap_b32_e32 v39, v35
	v_permlane16_swap_b32_e32 v38, v34
	s_waitcnt lgkmcnt(0)
; DI unsigned pk2(float lo, float hi) { const f32x2 v = {lo, hi}; return __builtin_bit_cast(unsigned, __builtin_convertvector(v, bf16v2_t)); }
; DI float wave_sum(float v) { for (int o = 32; o; o >>= 1) v += __shfl_xor(v, o); return v; }
; DI void run_phase(const Params& p, int ph, unsigned char* smem, const int tid, const int rep) {
;     ...
;               for (int u = 0; u < 4; ++u) { const int t = t0 + u; bf16_t* pr = proj + (size_t)t * PLD;
;                   { const u32x2 v = vq[u]; const float a0 = __uint_as_float(v[0] << 16), a1 = __uint_as_float(v[0] & 0xffff0000u), a2 = __uint_as_float(v[1] << 16), a3 = __uint_as_float(v[1] & 0xffff0000u);
;                     const float rs = rsqrtf(wave_sum(a0 * a0 + a1 * a1 + a2 * a2 + a3 * a3) * (1.f / 256.f) + NEPS);
;                     u32x2 o; o[0] = pk2(a0 * rs * ggq[0], a1 * rs * ggq[1]); o[1] = pk2(a2 * rs * ggq[2], a3 * rs * ggq[3]); *(u32x2*)(mlaa + (size_t)t * 384 + 4 * lane) = o; }
;                   { const unsigned v = vkv[u]; const float a0 = __uint_as_float(v << 16), a1 = __uint_as_float(v & 0xffff0000u);
;                     const float rs = rsqrtf(wave_sum(a0 * a0 + a1 * a1) * (1.f / 128.f) + NEPS);
;                     *(unsigned*)(mlaa + (size_t)t * 384 + 256 + 2 * lane) = pk2(a0 * rs * gkv0, a1 * rs * gkv1); }
; #pragma unroll
;                   for (int hq = 0; hq < 8; ++hq) { const unsigned v = vf[u][hq]; const float a0 = __uint_as_float(v << 16), a1 = __uint_as_float(v & 0xffff0000u);
;                     const float rs = rsqrtf(wave_sum(a0 * a0 + a1 * a1) * (1.f / 128.f) + NEPS) * ((hq < 4) ? 0.08838834764831845f * LOG2E : 1.f);
;                     *(unsigned*)(pr + 3520 + hq * 128 + 2 * lane) = pk2(a0 * rs * ((hq < 4) ? fq0 : fk0), a1 * rs * ((hq < 4) ? fq1 : fk1)); } } } }
	v_pk_add_f32 v[34:35], v[34:35], v[38:39]
	s_nop 1
	v_add_f32_dpp v35, v35, v35 row_ror:8 row_mask:0xf bank_mask:0xf
	v_add_f32_dpp v34, v34, v34 row_ror:8 row_mask:0xf bank_mask:0xf
	s_waitcnt lgkmcnt(0)
	s_nop 1
	v_add_f32_dpp v35, v35, v35 row_ror:4 row_mask:0xf bank_mask:0xf
	v_add_f32_dpp v34, v34, v34 row_ror:4 row_mask:0xf bank_mask:0xf
	s_waitcnt lgkmcnt(0)
	s_nop 1
	v_add_f32_dpp v35, v35, v35 quad_perm:[2,3,0,1] row_mask:0xf bank_mask:0xf
	v_add_f32_dpp v34, v34, v34 quad_perm:[2,3,0,1] row_mask:0xf bank_mask:0xf
	s_waitcnt lgkmcnt(0)
	s_nop 1
	v_add_f32_dpp v35, v35, v35 quad_perm:[1,0,3,2] row_mask:0xf bank_mask:0xf
	v_add_f32_dpp v34, v34, v34 quad_perm:[1,0,3,2] row_mask:0xf bank_mask:0xf
	s_waitcnt lgkmcnt(0)
	s_nop 0
	v_pk_fma_f32 v[34:35], v[34:35], s[96:97], v[18:19] op_sel_hi:[1,0,0]
	s_nop 0
	v_cmp_gt_f32_e64 s[0:1], s77, v35
	v_cmp_gt_f32_e32 vcc, s77, v34
	s_nop 0
	v_rsq_f32_e32 v35, v35
	s_nop 0
	v_mov_b32_e32 v38, v35
	v_pk_mul_f32 v[32:33], v[38:39], v[32:33] op_sel_hi:[0,1]
	v_pk_mul_f32 v[32:33], v[10:11], v[32:33]
	s_nop 0
	v_cvt_pk_bf16_f32 v32, v32, v33
	global_store_dword v[28:29], v32, off offset:1024
	v_rsq_f32_e32 v32, v34
	s_nop 0
	v_pk_mul_f32 v[32:33], v[32:33], v[36:37] op_sel_hi:[0,1]
	v_pk_mul_f32 v[32:33], v[10:11], v[32:33]
	v_lshlrev_b32_e32 v36, 16, v71
	v_cvt_pk_bf16_f32 v32, v32, v33
	global_store_dword v[28:29], v32, off offset:1280
	v_lshlrev_b32_e32 v32, 16, v72
	v_and_b32_e32 v33, 0xffff0000, v72
	v_and_b32_e32 v37, 0xffff0000, v71
	v_pk_mul_f32 v[34:35], v[32:33], v[32:33]
	v_pk_mul_f32 v[38:39], v[36:37], v[36:37]
	v_mov_b32_e32 v41, v34
	v_mov_b32_e32 v40, v38
	v_mov_b32_e32 v34, v39
	v_pk_add_f32 v[34:35], v[40:41], v[34:35]
	v_mov_b32_e32 v39, v35
	v_mov_b32_e32 v38, v34
	s_nop 0
	v_permlane32_swap_b32_e32 v39, v35
	v_permlane32_swap_b32_e32 v38, v34
	v_lshlrev_b32_e32 v40, 16, v70
	v_and_b32_e32 v41, 0xffff0000, v70
	v_pk_mul_f32 v[42:43], v[40:41], v[40:41]
	s_waitcnt lgkmcnt(0)
	v_pk_add_f32 v[34:35], v[34:35], v[38:39]
	v_mov_b32_e32 v39, v35
	v_mov_b32_e32 v38, v34
	s_nop 0
	v_permlane16_swap_b32_e32 v39, v35
	v_permlane16_swap_b32_e32 v38, v34
	s_waitcnt lgkmcnt(0)
	v_pk_add_f32 v[34:35], v[34:35], v[38:39]
	s_nop 1
	v_add_f32_dpp v35, v35, v35 row_ror:8 row_mask:0xf bank_mask:0xf
	v_add_f32_dpp v34, v34, v34 row_ror:8 row_mask:0xf bank_mask:0xf
	s_waitcnt lgkmcnt(0)
	s_nop 1
	v_add_f32_dpp v35, v35, v35 row_ror:4 row_mask:0xf bank_mask:0xf
	v_add_f32_dpp v34, v34, v34 row_ror:4 row_mask:0xf bank_mask:0xf
	s_waitcnt lgkmcnt(0)
	s_nop 1
	v_add_f32_dpp v35, v35, v35 quad_perm:[2,3,0,1] row_mask:0xf bank_mask:0xf
	v_add_f32_dpp v34, v34, v34 quad_perm:[2,3,0,1] row_mask:0xf bank_mask:0xf
	s_waitcnt lgkmcnt(0)
	s_nop 1
	v_add_f32_dpp v35, v35, v35 quad_perm:[1,0,3,2] row_mask:0xf bank_mask:0xf
	v_add_f32_dpp v34, v34, v34 quad_perm:[1,0,3,2] row_mask:0xf bank_mask:0xf
	s_waitcnt lgkmcnt(0)
	s_nop 0
	v_pk_fma_f32 v[34:35], v[34:35], s[96:97], v[18:19] op_sel_hi:[1,0,0]
	s_nop 0
	v_cmp_gt_f32_e64 s[0:1], s77, v35
	v_cmp_gt_f32_e32 vcc, s77, v34
	s_nop 0
	v_rsq_f32_e32 v35, v35
	s_nop 0
	v_mov_b32_e32 v38, v35
	v_pk_mul_f32 v[32:33], v[38:39], v[32:33] op_sel_hi:[0,1]
	v_pk_mul_f32 v[32:33], v[10:11], v[32:33]
	s_nop 0
	v_cvt_pk_bf16_f32 v32, v32, v33
	global_store_dword v[28:29], v32, off offset:1536
	v_rsq_f32_e32 v32, v34
	s_nop 0
	v_pk_mul_f32 v[32:33], v[32:33], v[36:37] op_sel_hi:[0,1]
	v_pk_mul_f32 v[32:33], v[10:11], v[32:33]
	s_nop 0
	v_cvt_pk_bf16_f32 v32, v32, v33
	global_store_dword v[28:29], v32, off offset:1792
	v_and_b32_e32 v33, 0xffff0000, v31
	v_and_b32_e32 v32, s0, v30
	v_mov_b32_e32 v29, v33
	v_pk_mul_f32 v[34:35], v[32:33], v[32:33]
	v_and_b32_e32 v33, 0xffff0000, v30
	v_lshlrev_b32_e32 v32, 16, v30
	v_mul_f32_e32 v30, v33, v33
	v_lshlrev_b32_e32 v28, 16, v31
	v_pk_fma_f32 v[30:31], v[32:33], v[32:33], v[30:31] op_sel_hi:[1,1,0]
	v_mov_b32_e32 v34, v42
	v_pk_fma_f32 v[30:31], v[28:29], v[28:29], v[30:31]
	v_mad_i64_i32 v[36:37], s[0:1], v69, s22, v[20:21]
	v_pk_mov_b32 v[30:31], v[42:43], v[30:31] op_sel:[1,0]
	v_lshl_add_u64 v[38:39], v[36:37], 0, v[0:1]
	v_pk_add_f32 v[30:31], v[34:35], v[30:31]
	v_mov_b32_e32 v35, v31
	v_mov_b32_e32 v34, v30
	s_nop 0
	v_permlane32_swap_b32_e32 v35, v31
	v_permlane32_swap_b32_e32 v34, v30
	s_waitcnt lgkmcnt(0)
	v_pk_add_f32 v[30:31], v[30:31], v[34:35]
	v_mov_b32_e32 v35, v31
	v_mov_b32_e32 v34, v30
	s_nop 0
	v_permlane16_swap_b32_e32 v35, v31
	v_permlane16_swap_b32_e32 v34, v30
	s_waitcnt lgkmcnt(0)
	v_pk_add_f32 v[30:31], v[30:31], v[34:35]
	s_nop 1
	v_add_f32_dpp v31, v31, v31 row_ror:8 row_mask:0xf bank_mask:0xf
	v_add_f32_dpp v30, v30, v30 row_ror:8 row_mask:0xf bank_mask:0xf
	s_waitcnt lgkmcnt(0)
	s_nop 1
	v_add_f32_dpp v31, v31, v31 row_ror:4 row_mask:0xf bank_mask:0xf
	v_add_f32_dpp v30, v30, v30 row_ror:4 row_mask:0xf bank_mask:0xf
	s_waitcnt lgkmcnt(0)
	s_nop 1
	v_add_f32_dpp v31, v31, v31 quad_perm:[2,3,0,1] row_mask:0xf bank_mask:0xf
	v_add_f32_dpp v30, v30, v30 quad_perm:[2,3,0,1] row_mask:0xf bank_mask:0xf
	s_waitcnt lgkmcnt(0)
	s_nop 1
	v_add_f32_dpp v31, v31, v31 quad_perm:[1,0,3,2] row_mask:0xf bank_mask:0xf
	v_add_f32_dpp v30, v30, v30 quad_perm:[1,0,3,2] row_mask:0xf bank_mask:0xf
	s_waitcnt lgkmcnt(0)
; DI unsigned pk2(float lo, float hi) { const f32x2 v = {lo, hi}; return __builtin_bit_cast(unsigned, __builtin_convertvector(v, bf16v2_t)); }
; DI float wave_sum(float v) { for (int o = 32; o; o >>= 1) v += __shfl_xor(v, o); return v; }
; DI void run_phase(const Params& p, int ph, unsigned char* smem, const int tid, const int rep) {
;     ...
;               for (int u = 0; u < 4; ++u) { const int t = t0 + u; bf16_t* pr = proj + (size_t)t * PLD;
;                   { const u32x2 v = vq[u]; const float a0 = __uint_as_float(v[0] << 16), a1 = __uint_as_float(v[0] & 0xffff0000u), a2 = __uint_as_float(v[1] << 16), a3 = __uint_as_float(v[1] & 0xffff0000u);
;                     const float rs = rsqrtf(wave_sum(a0 * a0 + a1 * a1 + a2 * a2 + a3 * a3) * (1.f / 256.f) + NEPS);
;                     u32x2 o; o[0] = pk2(a0 * rs * ggq[0], a1 * rs * ggq[1]); o[1] = pk2(a2 * rs * ggq[2], a3 * rs * ggq[3]); *(u32x2*)(mlaa + (size_t)t * 384 + 4 * lane) = o; }
;                   { const unsigned v = vkv[u]; const float a0 = __uint_as_float(v << 16), a1 = __uint_as_float(v & 0xffff0000u);
;                     const float rs = rsqrtf(wave_sum(a0 * a0 + a1 * a1) * (1.f / 128.f) + NEPS);
;                     *(unsigned*)(mlaa + (size_t)t * 384 + 256 + 2 * lane) = pk2(a0 * rs * gkv0, a1 * rs * gkv1); }
; #pragma unroll
;                   for (int hq = 0; hq < 8; ++hq) { const unsigned v = vf[u][hq]; const float a0 = __uint_as_float(v << 16), a1 = __uint_as_float(v & 0xffff0000u);
;                     const float rs = rsqrtf(wave_sum(a0 * a0 + a1 * a1) * (1.f / 128.f) + NEPS) * ((hq < 4) ? 0.08838834764831845f * LOG2E : 1.f);
;                     *(unsigned*)(pr + 3520 + hq * 128 + 2 * lane) = pk2(a0 * rs * ((hq < 4) ? fq0 : fk0), a1 * rs * ((hq < 4) ? fq1 : fk1)); } } } }
	s_nop 0
	v_pk_fma_f32 v[30:31], v[30:31], s[96:97], v[18:19] op_sel_hi:[1,1,0]
	s_nop 0
	v_cmp_gt_f32_e64 s[0:1], s77, v31
	v_cmp_gt_f32_e32 vcc, s77, v30
	s_nop 0
	v_rsq_f32_e32 v31, v31
	s_nop 0
	v_mov_b32_e32 v34, v31
	v_pk_mul_f32 v[32:33], v[34:35], v[32:33] op_sel_hi:[0,1]
	v_pk_mul_f32 v[28:29], v[34:35], v[28:29] op_sel_hi:[0,1]
	v_pk_mul_f32 v[32:33], v[2:3], v[32:33]
	v_pk_mul_f32 v[28:29], v[4:5], v[28:29]
	v_cvt_pk_bf16_f32 v32, v32, v33
	v_cvt_pk_bf16_f32 v33, v28, v29
	v_rsq_f32_e32 v28, v30
	global_store_dwordx2 v[38:39], v[32:33], off
	v_lshlrev_b32_e32 v32, 16, v67
	v_and_b32_e32 v33, 0xffff0000, v67
	v_pk_mul_f32 v[28:29], v[28:29], v[40:41] op_sel_hi:[0,1]
	v_pk_mul_f32 v[28:29], v[6:7], v[28:29]
	v_pk_mul_f32 v[34:35], v[32:33], v[32:33]
	v_cvt_pk_bf16_f32 v30, v28, v29
	v_lshl_add_u64 v[28:29], v[36:37], 0, v[12:13]
	global_store_dword v[28:29], v30, off offset:512
	v_lshlrev_b32_e32 v28, 16, v68
	v_and_b32_e32 v29, 0xffff0000, v68
	v_pk_mul_f32 v[30:31], v[28:29], v[28:29]
	v_mov_b32_e32 v36, v34
	v_mov_b32_e32 v37, v30
	v_mov_b32_e32 v30, v35
	v_pk_add_f32 v[30:31], v[36:37], v[30:31]
	v_mov_b32_e32 v35, v31
	v_mov_b32_e32 v34, v30
	s_nop 0
	v_permlane32_swap_b32_e32 v35, v31
	v_permlane32_swap_b32_e32 v34, v30
	s_waitcnt lgkmcnt(0)
	v_pk_add_f32 v[30:31], v[30:31], v[34:35]
	v_mov_b32_e32 v35, v31
	v_mov_b32_e32 v34, v30
	s_nop 0
	v_permlane16_swap_b32_e32 v35, v31
	v_permlane16_swap_b32_e32 v34, v30
	s_waitcnt lgkmcnt(0)
	v_pk_add_f32 v[30:31], v[30:31], v[34:35]
	s_nop 1
	v_add_f32_dpp v31, v31, v31 row_ror:8 row_mask:0xf bank_mask:0xf
	v_add_f32_dpp v30, v30, v30 row_ror:8 row_mask:0xf bank_mask:0xf
	s_waitcnt lgkmcnt(0)
	s_nop 1
	v_add_f32_dpp v31, v31, v31 row_ror:4 row_mask:0xf bank_mask:0xf
	v_add_f32_dpp v30, v30, v30 row_ror:4 row_mask:0xf bank_mask:0xf
	s_waitcnt lgkmcnt(0)
	s_nop 1
	v_add_f32_dpp v31, v31, v31 quad_perm:[2,3,0,1] row_mask:0xf bank_mask:0xf
	v_add_f32_dpp v30, v30, v30 quad_perm:[2,3,0,1] row_mask:0xf bank_mask:0xf
	s_waitcnt lgkmcnt(0)
	s_nop 1
	v_add_f32_dpp v31, v31, v31 quad_perm:[1,0,3,2] row_mask:0xf bank_mask:0xf
	v_add_f32_dpp v30, v30, v30 quad_perm:[1,0,3,2] row_mask:0xf bank_mask:0xf
	s_waitcnt lgkmcnt(0)
	s_nop 0
	v_pk_fma_f32 v[30:31], v[30:31], s[96:97], v[18:19] op_sel_hi:[1,0,0]
	s_nop 0
	v_cmp_gt_f32_e64 s[0:1], s77, v31
	v_cmp_gt_f32_e32 vcc, s77, v30
	s_nop 0
	v_rsq_f32_e32 v31, v31
	s_nop 0
	v_mul_f32_e32 v34, 0x3e0293ee, v31
	v_pk_mul_f32 v[28:29], v[34:35], v[28:29] op_sel_hi:[0,1]
	v_pk_mul_f32 v[28:29], v[8:9], v[28:29]
	v_and_b32_e32 v31, 0xffff0000, v65
	v_cvt_pk_bf16_f32 v28, v28, v29
	global_store_dword v[26:27], v28, off offset:2944
	v_rsq_f32_e32 v26, v30
	v_lshlrev_b32_e32 v30, 16, v65
	v_mul_f32_e32 v26, 0x3e0293ee, v26
	v_pk_mul_f32 v[26:27], v[26:27], v[32:33] op_sel_hi:[0,1]
	v_pk_mul_f32 v[26:27], v[8:9], v[26:27]
	v_pk_mul_f32 v[32:33], v[30:31], v[30:31]
	v_cvt_pk_bf16_f32 v26, v26, v27
	global_store_dword v[22:23], v26, off offset:256
	v_lshlrev_b32_e32 v26, 16, v66
	v_and_b32_e32 v27, 0xffff0000, v66
	v_pk_mul_f32 v[28:29], v[26:27], v[26:27]
	v_mov_b32_e32 v34, v32
	v_mov_b32_e32 v35, v28
	v_mov_b32_e32 v28, v33
	v_pk_add_f32 v[28:29], v[34:35], v[28:29]
	v_mov_b32_e32 v33, v29
	v_mov_b32_e32 v32, v28
	s_nop 0
	v_permlane32_swap_b32_e32 v33, v29
	v_permlane32_swap_b32_e32 v32, v28
	s_waitcnt lgkmcnt(0)
	v_pk_add_f32 v[28:29], v[28:29], v[32:33]
	v_mov_b32_e32 v33, v29
	v_mov_b32_e32 v32, v28
	s_nop 0
	v_permlane16_swap_b32_e32 v33, v29
	v_permlane16_swap_b32_e32 v32, v28
	s_waitcnt lgkmcnt(0)
	v_pk_add_f32 v[28:29], v[28:29], v[32:33]
	s_nop 1
	v_add_f32_dpp v29, v29, v29 row_ror:8 row_mask:0xf bank_mask:0xf
	v_add_f32_dpp v28, v28, v28 row_ror:8 row_mask:0xf bank_mask:0xf
	s_waitcnt lgkmcnt(0)
	s_nop 1
	v_add_f32_dpp v29, v29, v29 row_ror:4 row_mask:0xf bank_mask:0xf
	v_add_f32_dpp v28, v28, v28 row_ror:4 row_mask:0xf bank_mask:0xf
	s_waitcnt lgkmcnt(0)
	s_nop 1
	v_add_f32_dpp v29, v29, v29 quad_perm:[2,3,0,1] row_mask:0xf bank_mask:0xf
	v_add_f32_dpp v28, v28, v28 quad_perm:[2,3,0,1] row_mask:0xf bank_mask:0xf
	s_waitcnt lgkmcnt(0)
	s_nop 1
	v_add_f32_dpp v29, v29, v29 quad_perm:[1,0,3,2] row_mask:0xf bank_mask:0xf
	v_add_f32_dpp v28, v28, v28 quad_perm:[1,0,3,2] row_mask:0xf bank_mask:0xf
	s_waitcnt lgkmcnt(0)
	s_nop 0
	v_pk_fma_f32 v[28:29], v[28:29], s[96:97], v[18:19] op_sel_hi:[1,0,0]
	s_nop 0
	v_cmp_gt_f32_e64 s[0:1], s77, v29
	v_cmp_gt_f32_e32 vcc, s77, v28
	s_nop 0
	v_rsq_f32_e32 v29, v29
	s_nop 0
	v_mul_f32_e32 v32, 0x3e0293ee, v29
	v_pk_mul_f32 v[26:27], v[32:33], v[26:27] op_sel_hi:[0,1]
	v_pk_mul_f32 v[26:27], v[8:9], v[26:27]
	s_nop 0
	v_cvt_pk_bf16_f32 v26, v26, v27
	global_store_dword v[22:23], v26, off offset:512
	v_rsq_f32_e32 v26, v28
	s_nop 0
	v_mul_f32_e32 v26, 0x3e0293ee, v26
	v_pk_mul_f32 v[26:27], v[26:27], v[30:31] op_sel_hi:[0,1]
	v_pk_mul_f32 v[26:27], v[8:9], v[26:27]
	v_lshlrev_b32_e32 v30, 16, v63
	v_cvt_pk_bf16_f32 v26, v26, v27
	global_store_dword v[22:23], v26, off offset:768
	v_lshlrev_b32_e32 v26, 16, v64
	v_and_b32_e32 v27, 0xffff0000, v64
	v_and_b32_e32 v31, 0xffff0000, v63
	v_pk_mul_f32 v[28:29], v[26:27], v[26:27]
	v_pk_mul_f32 v[32:33], v[30:31], v[30:31]
	v_mov_b32_e32 v35, v28
	v_mov_b32_e32 v34, v32
	v_mov_b32_e32 v28, v33
	v_pk_add_f32 v[28:29], v[34:35], v[28:29]
	v_mov_b32_e32 v33, v29
	v_mov_b32_e32 v32, v28
	s_nop 0
	v_permlane32_swap_b32_e32 v33, v29
	v_permlane32_swap_b32_e32 v32, v28
	s_waitcnt lgkmcnt(0)
	v_pk_add_f32 v[28:29], v[28:29], v[32:33]
	v_mov_b32_e32 v33, v29
	v_mov_b32_e32 v32, v28
	s_nop 0
	v_permlane16_swap_b32_e32 v33, v29
	v_permlane16_swap_b32_e32 v32, v28
	s_waitcnt lgkmcnt(0)
; DI unsigned pk2(float lo, float hi) { const f32x2 v = {lo, hi}; return __builtin_bit_cast(unsigned, __builtin_convertvector(v, bf16v2_t)); }
; DI float wave_sum(float v) { for (int o = 32; o; o >>= 1) v += __shfl_xor(v, o); return v; }
; DI void run_phase(const Params& p, int ph, unsigned char* smem, const int tid, const int rep) {
;     ...
;               for (int u = 0; u < 4; ++u) { const int t = t0 + u; bf16_t* pr = proj + (size_t)t * PLD;
;                   { const u32x2 v = vq[u]; const float a0 = __uint_as_float(v[0] << 16), a1 = __uint_as_float(v[0] & 0xffff0000u), a2 = __uint_as_float(v[1] << 16), a3 = __uint_as_float(v[1] & 0xffff0000u);
;                     const float rs = rsqrtf(wave_sum(a0 * a0 + a1 * a1 + a2 * a2 + a3 * a3) * (1.f / 256.f) + NEPS);
;                     u32x2 o; o[0] = pk2(a0 * rs * ggq[0], a1 * rs * ggq[1]); o[1] = pk2(a2 * rs * ggq[2], a3 * rs * ggq[3]); *(u32x2*)(mlaa + (size_t)t * 384 + 4 * lane) = o; }
;                   { const unsigned v = vkv[u]; const float a0 = __uint_as_float(v << 16), a1 = __uint_as_float(v & 0xffff0000u);
;                     const float rs = rsqrtf(wave_sum(a0 * a0 + a1 * a1) * (1.f / 128.f) + NEPS);
;                     *(unsigned*)(mlaa + (size_t)t * 384 + 256 + 2 * lane) = pk2(a0 * rs * gkv0, a1 * rs * gkv1); }
; #pragma unroll
;                   for (int hq = 0; hq < 8; ++hq) { const unsigned v = vf[u][hq]; const float a0 = __uint_as_float(v << 16), a1 = __uint_as_float(v & 0xffff0000u);
;                     const float rs = rsqrtf(wave_sum(a0 * a0 + a1 * a1) * (1.f / 128.f) + NEPS) * ((hq < 4) ? 0.08838834764831845f * LOG2E : 1.f);
;                     *(unsigned*)(pr + 3520 + hq * 128 + 2 * lane) = pk2(a0 * rs * ((hq < 4) ? fq0 : fk0), a1 * rs * ((hq < 4) ? fq1 : fk1)); } } } }
	v_pk_add_f32 v[28:29], v[28:29], v[32:33]
	s_nop 1
	v_add_f32_dpp v29, v29, v29 row_ror:8 row_mask:0xf bank_mask:0xf
	v_add_f32_dpp v28, v28, v28 row_ror:8 row_mask:0xf bank_mask:0xf
	s_waitcnt lgkmcnt(0)
	s_nop 1
	v_add_f32_dpp v29, v29, v29 row_ror:4 row_mask:0xf bank_mask:0xf
	v_add_f32_dpp v28, v28, v28 row_ror:4 row_mask:0xf bank_mask:0xf
	s_waitcnt lgkmcnt(0)
	s_nop 1
	v_add_f32_dpp v29, v29, v29 quad_perm:[2,3,0,1] row_mask:0xf bank_mask:0xf
	v_add_f32_dpp v28, v28, v28 quad_perm:[2,3,0,1] row_mask:0xf bank_mask:0xf
	s_waitcnt lgkmcnt(0)
	s_nop 1
	v_add_f32_dpp v29, v29, v29 quad_perm:[1,0,3,2] row_mask:0xf bank_mask:0xf
	v_add_f32_dpp v28, v28, v28 quad_perm:[1,0,3,2] row_mask:0xf bank_mask:0xf
	s_waitcnt lgkmcnt(0)
	s_nop 0
	v_pk_fma_f32 v[28:29], v[28:29], s[96:97], v[18:19] op_sel_hi:[1,0,0]
	s_nop 0
	v_cmp_gt_f32_e64 s[0:1], s77, v29
	v_cmp_gt_f32_e32 vcc, s77, v28
	s_nop 0
	v_rsq_f32_e32 v29, v29
	s_nop 0
	v_mov_b32_e32 v32, v29
	v_pk_mul_f32 v[26:27], v[32:33], v[26:27] op_sel_hi:[0,1]
	v_pk_mul_f32 v[26:27], v[10:11], v[26:27]
	s_nop 0
	v_cvt_pk_bf16_f32 v26, v26, v27
	global_store_dword v[22:23], v26, off offset:1024
	v_rsq_f32_e32 v26, v28
	s_nop 0
	v_pk_mul_f32 v[26:27], v[26:27], v[30:31] op_sel_hi:[0,1]
	v_pk_mul_f32 v[26:27], v[10:11], v[26:27]
	v_lshlrev_b32_e32 v30, 16, v61
	v_cvt_pk_bf16_f32 v26, v26, v27
	global_store_dword v[22:23], v26, off offset:1280
	v_lshlrev_b32_e32 v26, 16, v62
	v_and_b32_e32 v27, 0xffff0000, v62
	v_and_b32_e32 v31, 0xffff0000, v61
	v_pk_mul_f32 v[28:29], v[26:27], v[26:27]
	v_pk_mul_f32 v[32:33], v[30:31], v[30:31]
	v_mov_b32_e32 v35, v28
	v_mov_b32_e32 v34, v32
	v_mov_b32_e32 v28, v33
	v_pk_add_f32 v[28:29], v[34:35], v[28:29]
	v_mov_b32_e32 v33, v29
	v_mov_b32_e32 v32, v28
	s_nop 0
	v_permlane32_swap_b32_e32 v33, v29
	v_permlane32_swap_b32_e32 v32, v28
	s_waitcnt lgkmcnt(0)
	v_pk_add_f32 v[28:29], v[28:29], v[32:33]
	v_mov_b32_e32 v33, v29
	v_mov_b32_e32 v32, v28
	s_nop 0
	v_permlane16_swap_b32_e32 v33, v29
	v_permlane16_swap_b32_e32 v32, v28
	s_waitcnt lgkmcnt(0)
	v_pk_add_f32 v[28:29], v[28:29], v[32:33]
	s_nop 1
	v_add_f32_dpp v29, v29, v29 row_ror:8 row_mask:0xf bank_mask:0xf
	v_add_f32_dpp v28, v28, v28 row_ror:8 row_mask:0xf bank_mask:0xf
	s_waitcnt lgkmcnt(0)
	s_nop 1
	v_add_f32_dpp v29, v29, v29 row_ror:4 row_mask:0xf bank_mask:0xf
	v_add_f32_dpp v28, v28, v28 row_ror:4 row_mask:0xf bank_mask:0xf
	s_waitcnt lgkmcnt(0)
	s_nop 1
	v_add_f32_dpp v29, v29, v29 quad_perm:[2,3,0,1] row_mask:0xf bank_mask:0xf
	v_add_f32_dpp v28, v28, v28 quad_perm:[2,3,0,1] row_mask:0xf bank_mask:0xf
	s_waitcnt lgkmcnt(0)
	s_nop 1
	v_add_f32_dpp v29, v29, v29 quad_perm:[1,0,3,2] row_mask:0xf bank_mask:0xf
	v_add_f32_dpp v28, v28, v28 quad_perm:[1,0,3,2] row_mask:0xf bank_mask:0xf
	s_waitcnt lgkmcnt(0)
	s_nop 0
	v_pk_fma_f32 v[28:29], v[28:29], s[96:97], v[18:19] op_sel_hi:[1,0,0]
	s_nop 0
	v_cmp_gt_f32_e64 s[0:1], s77, v29
	v_cmp_gt_f32_e32 vcc, s77, v28
	s_nop 0
	v_rsq_f32_e32 v29, v29
	s_nop 0
	v_mov_b32_e32 v32, v29
	v_pk_mul_f32 v[26:27], v[32:33], v[26:27] op_sel_hi:[0,1]
	v_pk_mul_f32 v[26:27], v[10:11], v[26:27]
	s_waitcnt vmcnt(36)
	v_lshlrev_b32_e32 v32, 16, v60
	v_cvt_pk_bf16_f32 v26, v26, v27
	global_store_dword v[22:23], v26, off offset:1536
	v_rsq_f32_e32 v26, v28
	v_and_b32_e32 v33, 0xffff0000, v60
	v_pk_mul_f32 v[34:35], v[32:33], v[32:33]
	v_pk_mul_f32 v[26:27], v[26:27], v[30:31] op_sel_hi:[0,1]
	v_pk_mul_f32 v[26:27], v[10:11], v[26:27]
	s_nop 0
	v_cvt_pk_bf16_f32 v26, v26, v27
	global_store_dword v[22:23], v26, off offset:1792
	v_and_b32_e32 v27, 0xffff0000, v25
	v_and_b32_e32 v26, s0, v24
	v_mov_b32_e32 v23, v27
	v_pk_mul_f32 v[28:29], v[26:27], v[26:27]
	v_and_b32_e32 v27, 0xffff0000, v24
	v_lshlrev_b32_e32 v26, 16, v24
	v_mul_f32_e32 v24, v27, v27
	v_lshlrev_b32_e32 v22, 16, v25
	v_pk_fma_f32 v[24:25], v[26:27], v[26:27], v[24:25] op_sel_hi:[1,1,0]
	v_mov_b32_e32 v28, v34
	v_pk_fma_f32 v[24:25], v[22:23], v[22:23], v[24:25]
	v_mad_i64_i32 v[20:21], s[0:1], v59, s22, v[20:21]
	v_pk_mov_b32 v[24:25], v[34:35], v[24:25] op_sel:[1,0]
	v_lshl_add_u64 v[30:31], v[20:21], 0, v[0:1]
	v_pk_add_f32 v[24:25], v[28:29], v[24:25]
	v_mov_b32_e32 v29, v25
	v_mov_b32_e32 v28, v24
	s_nop 0
	v_permlane32_swap_b32_e32 v29, v25
	v_permlane32_swap_b32_e32 v28, v24
	v_lshl_add_u64 v[20:21], v[20:21], 0, v[12:13]
	s_waitcnt lgkmcnt(0)
	v_pk_add_f32 v[24:25], v[24:25], v[28:29]
	v_mov_b32_e32 v29, v25
	v_mov_b32_e32 v28, v24
	s_nop 0
	v_permlane16_swap_b32_e32 v29, v25
	v_permlane16_swap_b32_e32 v28, v24
	s_waitcnt lgkmcnt(0)
	v_pk_add_f32 v[24:25], v[24:25], v[28:29]
	s_nop 1
	v_add_f32_dpp v25, v25, v25 row_ror:8 row_mask:0xf bank_mask:0xf
	v_add_f32_dpp v24, v24, v24 row_ror:8 row_mask:0xf bank_mask:0xf
	s_waitcnt lgkmcnt(0)
	s_nop 1
	v_add_f32_dpp v25, v25, v25 row_ror:4 row_mask:0xf bank_mask:0xf
	v_add_f32_dpp v24, v24, v24 row_ror:4 row_mask:0xf bank_mask:0xf
	s_waitcnt lgkmcnt(0)
	s_nop 1
	v_add_f32_dpp v25, v25, v25 quad_perm:[2,3,0,1] row_mask:0xf bank_mask:0xf
	v_add_f32_dpp v24, v24, v24 quad_perm:[2,3,0,1] row_mask:0xf bank_mask:0xf
	s_waitcnt lgkmcnt(0)
	s_nop 1
	v_add_f32_dpp v25, v25, v25 quad_perm:[1,0,3,2] row_mask:0xf bank_mask:0xf
	v_add_f32_dpp v24, v24, v24 quad_perm:[1,0,3,2] row_mask:0xf bank_mask:0xf
	s_waitcnt lgkmcnt(0)
	s_nop 0
	v_pk_fma_f32 v[24:25], v[24:25], s[96:97], v[18:19] op_sel_hi:[1,1,0]
	s_nop 0
	v_cmp_gt_f32_e64 s[0:1], s77, v25
	v_cmp_gt_f32_e32 vcc, s77, v24
	s_nop 0
	v_rsq_f32_e32 v25, v25
	s_nop 0
	v_mov_b32_e32 v28, v25
	v_pk_mul_f32 v[26:27], v[28:29], v[26:27] op_sel_hi:[0,1]
	v_pk_mul_f32 v[22:23], v[28:29], v[22:23] op_sel_hi:[0,1]
	v_pk_mul_f32 v[26:27], v[2:3], v[26:27]
	v_pk_mul_f32 v[22:23], v[4:5], v[22:23]
	v_cvt_pk_bf16_f32 v26, v26, v27
	v_cvt_pk_bf16_f32 v27, v22, v23
	v_rsq_f32_e32 v22, v24
	s_waitcnt vmcnt(36)
; DI unsigned pk2(float lo, float hi) { const f32x2 v = {lo, hi}; return __builtin_bit_cast(unsigned, __builtin_convertvector(v, bf16v2_t)); }
; DI float wave_sum(float v) { for (int o = 32; o; o >>= 1) v += __shfl_xor(v, o); return v; }
; DI void run_phase(const Params& p, int ph, unsigned char* smem, const int tid, const int rep) {
;     ...
; #pragma unroll
;                   for (int hq = 0; hq < 8; ++hq) { const unsigned v = vf[u][hq]; const float a0 = __uint_as_float(v << 16), a1 = __uint_as_float(v & 0xffff0000u);
;                     const float rs = rsqrtf(wave_sum(a0 * a0 + a1 * a1) * (1.f / 128.f) + NEPS) * ((hq < 4) ? 0.08838834764831845f * LOG2E : 1.f);
;                     *(unsigned*)(pr + 3520 + hq * 128 + 2 * lane) = pk2(a0 * rs * ((hq < 4) ? fq0 : fk0), a1 * rs * ((hq < 4) ? fq1 : fk1)); } } } }
	v_lshlrev_b32_e32 v24, 16, v57
	v_and_b32_e32 v25, 0xffff0000, v57
	global_store_dwordx2 v[30:31], v[26:27], off
	v_pk_mul_f32 v[22:23], v[22:23], v[32:33] op_sel_hi:[0,1]
	v_pk_mul_f32 v[22:23], v[6:7], v[22:23]
	v_pk_mul_f32 v[26:27], v[24:25], v[24:25]
	v_cvt_pk_bf16_f32 v22, v22, v23
	global_store_dword v[20:21], v22, off offset:512
	v_lshlrev_b32_e32 v20, 16, v58
	v_and_b32_e32 v21, 0xffff0000, v58
	v_pk_mul_f32 v[22:23], v[20:21], v[20:21]
	v_mov_b32_e32 v28, v26
	v_mov_b32_e32 v29, v22
	v_mov_b32_e32 v22, v27
	v_pk_add_f32 v[22:23], v[28:29], v[22:23]
	v_mov_b32_e32 v27, v23
	v_mov_b32_e32 v26, v22
	s_nop 0
	v_permlane32_swap_b32_e32 v27, v23
	v_permlane32_swap_b32_e32 v26, v22
	s_waitcnt lgkmcnt(0)
	v_pk_add_f32 v[22:23], v[22:23], v[26:27]
	v_mov_b32_e32 v27, v23
	v_mov_b32_e32 v26, v22
	s_nop 0
	v_permlane16_swap_b32_e32 v27, v23
	v_permlane16_swap_b32_e32 v26, v22
	s_waitcnt lgkmcnt(0)
	v_pk_add_f32 v[22:23], v[22:23], v[26:27]
	s_nop 1
	v_add_f32_dpp v23, v23, v23 row_ror:8 row_mask:0xf bank_mask:0xf
	v_add_f32_dpp v22, v22, v22 row_ror:8 row_mask:0xf bank_mask:0xf
	s_waitcnt lgkmcnt(0)
	s_nop 1
	v_add_f32_dpp v23, v23, v23 row_ror:4 row_mask:0xf bank_mask:0xf
	v_add_f32_dpp v22, v22, v22 row_ror:4 row_mask:0xf bank_mask:0xf
	s_waitcnt lgkmcnt(0)
	s_nop 1
	v_add_f32_dpp v23, v23, v23 quad_perm:[2,3,0,1] row_mask:0xf bank_mask:0xf
	v_add_f32_dpp v22, v22, v22 quad_perm:[2,3,0,1] row_mask:0xf bank_mask:0xf
	s_waitcnt lgkmcnt(0)
	s_nop 1
	v_add_f32_dpp v23, v23, v23 quad_perm:[1,0,3,2] row_mask:0xf bank_mask:0xf
	v_add_f32_dpp v22, v22, v22 quad_perm:[1,0,3,2] row_mask:0xf bank_mask:0xf
	s_waitcnt lgkmcnt(0)
	s_nop 0
	v_pk_fma_f32 v[22:23], v[22:23], s[96:97], v[18:19] op_sel_hi:[1,0,0]
	s_nop 0
	v_cmp_gt_f32_e64 s[0:1], s77, v23
	v_cmp_gt_f32_e32 vcc, s77, v22
	s_nop 0
	v_rsq_f32_e32 v13, v23
	s_nop 0
	v_mul_f32_e32 v26, 0x3e0293ee, v13
	v_pk_mul_f32 v[20:21], v[26:27], v[20:21] op_sel_hi:[0,1]
	v_pk_mul_f32 v[20:21], v[8:9], v[20:21]
	s_waitcnt vmcnt(36)
	v_and_b32_e32 v23, 0xffff0000, v55
	v_cvt_pk_bf16_f32 v13, v20, v21
	global_store_dword v[16:17], v13, off offset:2944
	v_rsq_f32_e32 v13, v22
	v_lshlrev_b32_e32 v22, 16, v55
	v_mul_f32_e32 v16, 0x3e0293ee, v13
	v_pk_mul_f32 v[16:17], v[16:17], v[24:25] op_sel_hi:[0,1]
	v_pk_mul_f32 v[16:17], v[8:9], v[16:17]
	v_pk_mul_f32 v[24:25], v[22:23], v[22:23]
	v_cvt_pk_bf16_f32 v13, v16, v17
	v_lshlrev_b32_e32 v16, 16, v56
	v_and_b32_e32 v17, 0xffff0000, v56
	v_pk_mul_f32 v[20:21], v[16:17], v[16:17]
	v_mov_b32_e32 v26, v24
	v_mov_b32_e32 v27, v20
	v_mov_b32_e32 v20, v25
	v_pk_add_f32 v[20:21], v[26:27], v[20:21]
	v_mov_b32_e32 v25, v21
	v_mov_b32_e32 v24, v20
	s_nop 0
	v_permlane32_swap_b32_e32 v25, v21
	v_permlane32_swap_b32_e32 v24, v20
	global_store_dword v[14:15], v13, off offset:256
	s_waitcnt lgkmcnt(0)
	v_pk_add_f32 v[20:21], v[20:21], v[24:25]
	v_mov_b32_e32 v25, v21
	v_mov_b32_e32 v24, v20
	s_nop 0
	v_permlane16_swap_b32_e32 v25, v21
	v_permlane16_swap_b32_e32 v24, v20
	s_waitcnt lgkmcnt(0)
	v_pk_add_f32 v[20:21], v[20:21], v[24:25]
	s_nop 1
	v_add_f32_dpp v21, v21, v21 row_ror:8 row_mask:0xf bank_mask:0xf
	v_add_f32_dpp v20, v20, v20 row_ror:8 row_mask:0xf bank_mask:0xf
	s_waitcnt lgkmcnt(0)
	s_nop 1
	v_add_f32_dpp v21, v21, v21 row_ror:4 row_mask:0xf bank_mask:0xf
	v_add_f32_dpp v20, v20, v20 row_ror:4 row_mask:0xf bank_mask:0xf
	s_waitcnt lgkmcnt(0)
	s_nop 1
	v_add_f32_dpp v21, v21, v21 quad_perm:[2,3,0,1] row_mask:0xf bank_mask:0xf
	v_add_f32_dpp v20, v20, v20 quad_perm:[2,3,0,1] row_mask:0xf bank_mask:0xf
	s_waitcnt lgkmcnt(0)
	s_nop 1
	v_add_f32_dpp v21, v21, v21 quad_perm:[1,0,3,2] row_mask:0xf bank_mask:0xf
	v_add_f32_dpp v20, v20, v20 quad_perm:[1,0,3,2] row_mask:0xf bank_mask:0xf
	s_waitcnt lgkmcnt(0)
	s_nop 0
	v_pk_fma_f32 v[20:21], v[20:21], s[96:97], v[18:19] op_sel_hi:[1,0,0]
	s_nop 0
	v_cmp_gt_f32_e64 s[0:1], s77, v21
	v_cmp_gt_f32_e32 vcc, s77, v20
	s_nop 0
	v_rsq_f32_e32 v13, v21
	s_nop 0
	v_mul_f32_e32 v24, 0x3e0293ee, v13
	v_pk_mul_f32 v[16:17], v[24:25], v[16:17] op_sel_hi:[0,1]
	v_pk_mul_f32 v[16:17], v[8:9], v[16:17]
	s_nop 0
	v_cvt_pk_bf16_f32 v13, v16, v17
	global_store_dword v[14:15], v13, off offset:512
	v_rsq_f32_e32 v13, v20
	s_nop 0
	v_mul_f32_e32 v16, 0x3e0293ee, v13
	v_pk_mul_f32 v[16:17], v[16:17], v[22:23] op_sel_hi:[0,1]
	v_pk_mul_f32 v[16:17], v[8:9], v[16:17]
	s_waitcnt vmcnt(37)
; DI unsigned pk2(float lo, float hi) { const f32x2 v = {lo, hi}; return __builtin_bit_cast(unsigned, __builtin_convertvector(v, bf16v2_t)); }
; DI float wave_sum(float v) { for (int o = 32; o; o >>= 1) v += __shfl_xor(v, o); return v; }
; DI void run_phase(const Params& p, int ph, unsigned char* smem, const int tid, const int rep) {
;     ...
; #pragma unroll
;                   for (int hq = 0; hq < 8; ++hq) { const unsigned v = vf[u][hq]; const float a0 = __uint_as_float(v << 16), a1 = __uint_as_float(v & 0xffff0000u);
;                     const float rs = rsqrtf(wave_sum(a0 * a0 + a1 * a1) * (1.f / 128.f) + NEPS) * ((hq < 4) ? 0.08838834764831845f * LOG2E : 1.f);
;                     *(unsigned*)(pr + 3520 + hq * 128 + 2 * lane) = pk2(a0 * rs * ((hq < 4) ? fq0 : fk0), a1 * rs * ((hq < 4) ? fq1 : fk1)); } } } }
	v_lshlrev_b32_e32 v22, 16, v53
	v_cvt_pk_bf16_f32 v13, v16, v17
	v_lshlrev_b32_e32 v16, 16, v54
	v_and_b32_e32 v17, 0xffff0000, v54
	v_and_b32_e32 v23, 0xffff0000, v53
	v_pk_mul_f32 v[20:21], v[16:17], v[16:17]
	v_pk_mul_f32 v[24:25], v[22:23], v[22:23]
	v_mov_b32_e32 v27, v20
	v_mov_b32_e32 v26, v24
	v_mov_b32_e32 v20, v25
	v_pk_add_f32 v[20:21], v[26:27], v[20:21]
	v_mov_b32_e32 v25, v21
	v_mov_b32_e32 v24, v20
	s_nop 0
	v_permlane32_swap_b32_e32 v25, v21
	v_permlane32_swap_b32_e32 v24, v20
	global_store_dword v[14:15], v13, off offset:768
	s_waitcnt lgkmcnt(0)
	v_pk_add_f32 v[20:21], v[20:21], v[24:25]
	v_mov_b32_e32 v25, v21
	v_mov_b32_e32 v24, v20
	s_nop 0
	v_permlane16_swap_b32_e32 v25, v21
	v_permlane16_swap_b32_e32 v24, v20
	s_waitcnt lgkmcnt(0)
	v_pk_add_f32 v[20:21], v[20:21], v[24:25]
	s_nop 1
	v_add_f32_dpp v21, v21, v21 row_ror:8 row_mask:0xf bank_mask:0xf
	v_add_f32_dpp v20, v20, v20 row_ror:8 row_mask:0xf bank_mask:0xf
	s_waitcnt lgkmcnt(0)
	s_nop 1
	v_add_f32_dpp v21, v21, v21 row_ror:4 row_mask:0xf bank_mask:0xf
	v_add_f32_dpp v20, v20, v20 row_ror:4 row_mask:0xf bank_mask:0xf
	s_waitcnt lgkmcnt(0)
	s_nop 1
	v_add_f32_dpp v21, v21, v21 quad_perm:[2,3,0,1] row_mask:0xf bank_mask:0xf
	v_add_f32_dpp v20, v20, v20 quad_perm:[2,3,0,1] row_mask:0xf bank_mask:0xf
	s_waitcnt lgkmcnt(0)
	s_nop 1
	v_add_f32_dpp v21, v21, v21 quad_perm:[1,0,3,2] row_mask:0xf bank_mask:0xf
	v_add_f32_dpp v20, v20, v20 quad_perm:[1,0,3,2] row_mask:0xf bank_mask:0xf
	s_waitcnt lgkmcnt(0)
	s_nop 0
	v_pk_fma_f32 v[20:21], v[20:21], s[96:97], v[18:19] op_sel_hi:[1,0,0]
	s_nop 0
	v_cmp_gt_f32_e64 s[0:1], s77, v21
	v_cmp_gt_f32_e32 vcc, s77, v20
	s_nop 0
	v_rsq_f32_e32 v13, v21
	s_nop 0
	v_mov_b32_e32 v24, v13
	v_pk_mul_f32 v[16:17], v[24:25], v[16:17] op_sel_hi:[0,1]
	v_pk_mul_f32 v[16:17], v[10:11], v[16:17]
	s_nop 0
	v_cvt_pk_bf16_f32 v13, v16, v17
	global_store_dword v[14:15], v13, off offset:1024
	v_rsq_f32_e32 v13, v20
	s_nop 0
	v_mov_b32_e32 v16, v13
	v_pk_mul_f32 v[16:17], v[16:17], v[22:23] op_sel_hi:[0,1]
	v_pk_mul_f32 v[16:17], v[10:11], v[16:17]
	s_waitcnt vmcnt(37)
	v_lshlrev_b32_e32 v22, 16, v51
	v_cvt_pk_bf16_f32 v13, v16, v17
	v_lshlrev_b32_e32 v16, 16, v52
	v_and_b32_e32 v17, 0xffff0000, v52
	v_and_b32_e32 v23, 0xffff0000, v51
	v_pk_mul_f32 v[20:21], v[16:17], v[16:17]
	v_pk_mul_f32 v[24:25], v[22:23], v[22:23]
	v_mov_b32_e32 v27, v20
	v_mov_b32_e32 v26, v24
	v_mov_b32_e32 v20, v25
	v_pk_add_f32 v[20:21], v[26:27], v[20:21]
	v_mov_b32_e32 v25, v21
	v_mov_b32_e32 v24, v20
	s_nop 0
	v_permlane32_swap_b32_e32 v25, v21
	v_permlane32_swap_b32_e32 v24, v20
	global_store_dword v[14:15], v13, off offset:1280
	s_waitcnt lgkmcnt(0)
	v_pk_add_f32 v[20:21], v[20:21], v[24:25]
	v_mov_b32_e32 v25, v21
	v_mov_b32_e32 v24, v20
	s_nop 0
	v_permlane16_swap_b32_e32 v25, v21
	v_permlane16_swap_b32_e32 v24, v20
	s_waitcnt lgkmcnt(0)
	v_pk_add_f32 v[20:21], v[20:21], v[24:25]
	s_nop 1
	v_add_f32_dpp v21, v21, v21 row_ror:8 row_mask:0xf bank_mask:0xf
	v_add_f32_dpp v20, v20, v20 row_ror:8 row_mask:0xf bank_mask:0xf
	s_waitcnt lgkmcnt(0)
	s_nop 1
	v_add_f32_dpp v21, v21, v21 row_ror:4 row_mask:0xf bank_mask:0xf
	v_add_f32_dpp v20, v20, v20 row_ror:4 row_mask:0xf bank_mask:0xf
	s_waitcnt lgkmcnt(0)
	s_nop 1
	v_add_f32_dpp v21, v21, v21 quad_perm:[2,3,0,1] row_mask:0xf bank_mask:0xf
	v_add_f32_dpp v20, v20, v20 quad_perm:[2,3,0,1] row_mask:0xf bank_mask:0xf
	s_waitcnt lgkmcnt(0)
	s_nop 1
	v_add_f32_dpp v21, v21, v21 quad_perm:[1,0,3,2] row_mask:0xf bank_mask:0xf
	v_add_f32_dpp v20, v20, v20 quad_perm:[1,0,3,2] row_mask:0xf bank_mask:0xf
	s_waitcnt lgkmcnt(0)
	s_nop 0
	v_pk_fma_f32 v[18:19], v[20:21], s[96:97], v[18:19] op_sel_hi:[1,0,0]
	s_nop 0
	v_cmp_gt_f32_e64 s[0:1], s77, v19
	v_cmp_gt_f32_e32 vcc, s77, v18
	s_nop 0
	v_rsq_f32_e32 v13, v19
	s_nop 0
	v_mov_b32_e32 v20, v13
	v_pk_mul_f32 v[16:17], v[20:21], v[16:17] op_sel_hi:[0,1]
	v_pk_mul_f32 v[16:17], v[10:11], v[16:17]
	s_nop 0
	v_cvt_pk_bf16_f32 v13, v16, v17
	global_store_dword v[14:15], v13, off offset:1536
	v_rsq_f32_e32 v13, v18
	s_nop 0
	v_mov_b32_e32 v16, v13
	v_pk_mul_f32 v[16:17], v[16:17], v[22:23] op_sel_hi:[0,1]
	v_pk_mul_f32 v[16:17], v[10:11], v[16:17]
	v_cmp_lt_i32_e32 vcc, s11, v44
	v_cvt_pk_bf16_f32 v13, v16, v17
	s_or_b64 s[40:41], vcc, s[40:41]
	global_store_dword v[14:15], v13, off offset:1792
	s_andn2_b64 exec, exec, s[40:41]
	s_cbranch_execnz .LBB0_372

; DI float siluf_(float x) { return x * __builtin_amdgcn_rcpf(1.f + __builtin_amdgcn_exp2f(-LOG2E * x)); }
;     ...
;     {
;         const int seg = tid >> 7, c = tid & 127, tt0 = seg * 16;
;         float y[3][16];
; #pragma unroll
;         for (int part = 0; part < 3; ++part) { const int col = part * 512 + h * 128 + c;
;             const float w0 = a.convw[col], w1 = a.convw[1536 + col], w2 = a.convw[2 * 1536 + col], w3 = a.convw[3 * 1536 + col];
; #pragma unroll
;             for (int e = 0; e < 16; ++e) y[part][e] = siluf_(w0 * xr[part][e] + w1 * xr[part][e + 1] + w2 * xr[part][e + 2] + w3 * xr[part][e + 3]); }
.LBB0_408:
	s_or_b64 exec, exec, s[0:1]
	v_lshlrev_b32_e32 v46, 16, v46
	v_cndmask_b32_e64 v66, 0, v46, s[62:63]
	v_lshlrev_b32_e32 v46, 16, v53
	v_cndmask_b32_e64 v53, 0, v46, s[64:65]
	v_lshlrev_b32_e32 v46, 16, v52
	v_cndmask_b32_e64 v52, 0, v46, s[68:69]
	v_lshlrev_b32_e32 v46, 16, v51
	v_lshlrev_b32_e32 v57, 16, v57
	v_cndmask_b32_e64 v51, 0, v46, s[70:71]
	v_lshlrev_b32_e32 v46, 16, v56
	v_lshlrev_b32_e32 v0, 16, v58
	v_cndmask_b32_e64 v57, 0, v57, s[46:47]
	v_cndmask_b32_e64 v56, 0, v46, s[72:73]
	v_lshlrev_b32_e32 v46, 16, v54
	v_cndmask_b32_e64 v0, 0, v0, s[44:45]
	v_lshlrev_b32_e32 v41, 16, v41
	v_cndmask_b32_e64 v54, 0, v46, s[74:75]
	s_waitcnt vmcnt(2)
	v_mul_f32_e32 v46, v57, v87
	v_cndmask_b32_e64 v41, 0, v41, s[48:49]
	v_lshlrev_b32_e32 v40, 16, v40
	v_fmac_f32_e32 v46, v0, v86
	v_cndmask_b32_e64 v40, 0, v40, s[50:51]
	v_lshlrev_b32_e32 v48, 16, v48
	s_waitcnt vmcnt(1)
	v_fmac_f32_e32 v46, v41, v89
	s_waitcnt lgkmcnt(0)
	v_cndmask_b32_e64 v65, 0, v48, s[60:61]
	v_lshlrev_b32_e32 v48, 16, v50
	s_waitcnt vmcnt(0)
	v_fmac_f32_e32 v46, v40, v88
	v_cndmask_b32_e64 v50, 0, v48, s[40:41]
	v_mul_f32_e32 v0, 0xbfb8aa3b, v46
	v_mul_f32_e32 v48, v41, v87
	v_lshlrev_b32_e32 v44, 16, v44
	v_exp_f32_e32 v0, v0
	v_fmac_f32_e32 v48, v57, v86
	v_mul_f32_e32 v57, v40, v87
	v_cndmask_b32_e64 v44, v44, 0, s[38:39]
	v_lshlrev_b32_e32 v42, 16, v42
	v_fmac_f32_e32 v57, v41, v86
	v_cndmask_b32_e64 v42, 0, v42, s[42:43]
	v_fmac_f32_e32 v57, v44, v89
	v_fmac_f32_e32 v57, v42, v88
	v_add_f32_e32 v0, 1.0, v0
	v_mul_f32_e32 v41, 0xbfb8aa3b, v57
	v_rcp_f32_e32 v0, v0
	v_exp_f32_e32 v41, v41
	v_lshlrev_b32_e32 v23, 16, v23
	v_fmac_f32_e32 v48, v40, v89
	v_mul_f32_e32 v74, v46, v0
	v_add_f32_e32 v0, 1.0, v41
	v_mul_f32_e32 v41, v44, v87
	v_fmac_f32_e32 v41, v40, v86
	v_cndmask_b32_e64 v23, 0, v23, s[52:53]
	v_lshlrev_b32_e32 v49, 16, v49
	v_fmac_f32_e32 v48, v44, v88
	v_fmac_f32_e32 v41, v42, v89
	v_cndmask_b32_e64 v58, 0, v49, s[58:59]
	v_mul_f32_e32 v49, 0xbfb8aa3b, v48
	v_fmac_f32_e32 v41, v23, v88
	v_exp_f32_e32 v49, v49
	v_mul_f32_e32 v40, 0xbfb8aa3b, v41
	v_exp_f32_e32 v40, v40
	v_lshlrev_b32_e32 v47, 16, v47
	v_add_f32_e32 v49, 1.0, v49
	v_rcp_f32_e32 v49, v49
	v_add_f32_e32 v40, 1.0, v40
	v_rcp_f32_e32 v40, v40
	v_cndmask_b32_e64 v47, 0, v47, s[54:55]
	v_mul_f32_e32 v75, v48, v49
	v_mul_f32_e32 v48, v23, v87
	v_lshlrev_b32_e32 v45, 16, v45
	v_fmac_f32_e32 v48, v42, v86
	v_mul_f32_e32 v77, v41, v40
	v_mul_f32_e32 v40, v47, v87
	v_cndmask_b32_e64 v45, 0, v45, s[56:57]
	v_fmac_f32_e32 v48, v47, v89
	v_fmac_f32_e32 v40, v23, v86
	v_mul_f32_e32 v46, v42, v87
	v_fmac_f32_e32 v48, v45, v88
	v_fmac_f32_e32 v40, v45, v89
	v_fmac_f32_e32 v46, v44, v86
	v_mul_f32_e32 v42, 0xbfb8aa3b, v48
	v_fmac_f32_e32 v40, v58, v88
	v_fmac_f32_e32 v46, v23, v89
	v_rcp_f32_e32 v0, v0
	v_exp_f32_e32 v42, v42
	v_mul_f32_e32 v23, 0xbfb8aa3b, v40
	v_mul_f32_e32 v41, v45, v87
	v_exp_f32_e32 v23, v23
	v_fmac_f32_e32 v41, v47, v86
	v_fmac_f32_e32 v41, v58, v89
	v_fmac_f32_e32 v46, v47, v88
	v_fmac_f32_e32 v41, v65, v88
	v_mul_f32_e32 v44, 0xbfb8aa3b, v46
	v_mul_f32_e32 v76, v57, v0
	v_add_f32_e32 v0, 1.0, v42
	v_mul_f32_e32 v42, 0xbfb8aa3b, v41
	v_exp_f32_e32 v44, v44
	v_exp_f32_e32 v42, v42
	v_add_f32_e32 v23, 1.0, v23
	v_rcp_f32_e32 v23, v23
	v_add_f32_e32 v44, 1.0, v44
	v_add_f32_e32 v42, 1.0, v42
	v_rcp_f32_e32 v44, v44
	v_rcp_f32_e32 v0, v0
	v_rcp_f32_e32 v42, v42
	v_mul_f32_e32 v49, v40, v23
	v_mul_f32_e32 v23, v65, v87
	v_fmac_f32_e32 v23, v58, v86
	v_fmac_f32_e32 v23, v50, v89
	v_fmac_f32_e32 v23, v66, v88
	v_mul_f32_e32 v90, v46, v44
	v_mul_f32_e32 v44, v58, v87
	v_mul_f32_e32 v91, v48, v0
	v_mul_f32_e32 v48, v41, v42
	v_mul_f32_e32 v40, 0xbfb8aa3b, v23
	v_mul_f32_e32 v41, v50, v87
	v_fmac_f32_e32 v44, v45, v86
	v_exp_f32_e32 v40, v40
	v_fmac_f32_e32 v41, v65, v86
	v_fmac_f32_e32 v44, v65, v89
	v_fmac_f32_e32 v41, v66, v89
	v_fmac_f32_e32 v44, v50, v88
	v_fmac_f32_e32 v41, v53, v88
	v_mul_f32_e32 v45, 0xbfb8aa3b, v44
	v_mul_f32_e32 v42, 0xbfb8aa3b, v41
	v_exp_f32_e32 v45, v45
	v_exp_f32_e32 v42, v42
	v_add_f32_e32 v40, 1.0, v40
	v_rcp_f32_e32 v40, v40
	v_add_f32_e32 v0, 1.0, v45
	v_add_f32_e32 v42, 1.0, v42
	v_mul_f32_e32 v45, v66, v87
	v_rcp_f32_e32 v42, v42
	v_fmac_f32_e32 v45, v50, v86
	v_mul_f32_e32 v47, v23, v40
	v_mul_f32_e32 v23, v53, v87
	v_fmac_f32_e32 v45, v53, v89
	v_fmac_f32_e32 v23, v66, v86
	v_fmac_f32_e32 v45, v52, v88
	v_fmac_f32_e32 v23, v52, v89
	v_mul_f32_e32 v46, 0xbfb8aa3b, v45
	v_fmac_f32_e32 v23, v51, v88
	v_exp_f32_e32 v57, v46
	v_mul_f32_e32 v46, v41, v42
	v_mul_f32_e32 v40, 0xbfb8aa3b, v23
	v_mul_f32_e32 v41, v52, v87
	v_exp_f32_e32 v40, v40
	v_fmac_f32_e32 v41, v53, v86
	v_fmac_f32_e32 v41, v51, v89
	v_fmac_f32_e32 v41, v56, v88
	v_mul_f32_e32 v42, 0xbfb8aa3b, v41
	v_rcp_f32_e32 v0, v0
	v_exp_f32_e32 v42, v42
	v_add_f32_e32 v40, 1.0, v40
	v_mul_f32_e32 v53, v51, v87
	v_rcp_f32_e32 v40, v40
	v_fmac_f32_e32 v53, v52, v86
	v_fmac_f32_e32 v53, v56, v89
	v_fmac_f32_e32 v53, v54, v88
	v_mul_f32_e32 v50, v44, v0
	v_add_f32_e32 v42, 1.0, v42
	v_mul_f32_e32 v44, 0xbfb8aa3b, v53
	v_rcp_f32_e32 v42, v42
	v_exp_f32_e32 v52, v44
	v_mul_f32_e32 v44, v23, v40
	v_mul_f32_e32 v23, v56, v87
	v_lshlrev_b32_e32 v43, 16, v43
	v_fmac_f32_e32 v23, v51, v86
	v_cndmask_b32_e64 v43, 0, v43, s[66:67]
	v_fmac_f32_e32 v23, v54, v89
	v_fmac_f32_e32 v23, v43, v88
	v_mul_f32_e32 v40, v41, v42
	v_mul_f32_e32 v41, 0xbfb8aa3b, v23
	v_lshl_add_u32 v42, v20, 3, 0
	v_exp_f32_e32 v41, v41
	s_barrier
; DI bf16_t f2bf(float f) { unsigned u = __float_as_uint(f); u += 0x7fffu + ((u >> 16) & 1u); return (bf16_t)(u >> 16); }
;     ...
;         float rk_[16], rv_[16];
; #pragma unroll
;         for (int e = 0; e < 16; ++e) { const int tt = tt0 + e;
;             const float rq = rsqrtf(ssq[tt * 2] + ssq[tt * 2 + 1] + NEPS) * 0.08838834764831845f, rk = rsqrtf(ssq[(64 + tt) * 2] + ssq[(64 + tt) * 2 + 1] + NEPS);
;             const float bt = betas[tt];
;             qs[tt * 136 + c] = f2bf(y[0][e] * rq);
;             const float kn = y[1][e] * rk; ks[tt * 136 + c] = f2bf(kn);
;             rk_[e] = kn * bt * egs[tt]; rv_[e] = y[2][e] * bt; }
	ds_read_b128 v[66:69], v42 offset:36864
	ds_read_b128 v[70:73], v42 offset:37376
	v_add_f32_e32 v0, 1.0, v57
	v_rcp_f32_e32 v0, v0
	v_add_f32_e32 v41, 1.0, v41
	v_rcp_f32_e32 v43, v41
	s_waitcnt lgkmcnt(1)
	v_add_f32_e32 v41, v66, v67
	v_add_f32_e32 v41, 0x358637bd, v41
	v_mul_f32_e32 v42, 0x4b800000, v41
	v_cmp_gt_f32_e64 s[0:1], s77, v41
	v_mul_f32_e32 v45, v45, v0
	v_add_f32_e32 v0, 1.0, v52
	v_cndmask_b32_e64 v41, v41, v42, s[0:1]
	v_rcp_f32_e32 v0, v0
	v_rsq_f32_e32 v42, v41
	s_movk_i32 s12, 0x88
	s_add_i32 s4, 0, 0x11000
	v_mul_f32_e32 v41, v53, v0
	v_mul_f32_e32 v0, v23, v43
	v_mul_f32_e32 v43, 0x45800000, v42
	v_cndmask_b32_e64 v42, v42, v43, s[0:1]
	v_mul_f32_e32 v51, 0x3db504f3, v42
	v_mul_f32_e32 v51, v84, v51
	v_bfe_u32 v53, v51, 16, 1
	v_add3_u32 v51, v51, v53, s11
	v_mul_lo_u32 v53, v20, s12
	v_or_b32_e32 v56, v53, v19
	v_lshlrev_b32_e32 v56, 1, v56
	v_add_u32_e32 v57, s4, v56
	ds_write_b16_d16_hi v57, v51
	v_add_f32_e32 v51, v68, v69
	v_add_f32_e32 v51, 0x358637bd, v51
	v_cmp_gt_f32_e64 s[0:1], s77, v51
	v_lshlrev_b32_e32 v52, 2, v20
	s_add_i32 s25, 0, 0x25580
	v_rsq_f32_e32 v51, v51
	s_add_i32 s13, 0, 0x25680
	v_add_u32_e32 v54, s25, v52
	v_add_u32_e32 v57, s13, v52
	s_waitcnt lgkmcnt(1)
	v_mov_b32_e32 v42, v71
	v_mov_b32_e32 v43, v72
	v_mul_f32_e32 v51, 0x3db504f3, v51
	v_mov_b32_e32 v71, v73
	v_mul_f32_e32 v51, v83, v51
	v_pk_add_f32 v[42:43], v[42:43], v[70:71]
	s_mov_b32 s72, 0x358637bd
	v_bfe_u32 v52, v51, 16, 1
	v_pk_add_f32 v[42:43], v[42:43], s[72:73] op_sel_hi:[1,0]
	v_add3_u32 v51, v51, v52, s11
	v_mul_f32_e32 v52, 0x4b800000, v42
	v_cmp_gt_f32_e64 s[0:1], s77, v42
	v_cmp_gt_f32_e64 s[38:39], s77, v43
	v_add_lshl_u32 v65, v53, v19, 1
	v_cndmask_b32_e64 v42, v42, v52, s[0:1]
	v_mul_f32_e32 v52, 0x4b800000, v43
	v_cndmask_b32_e64 v43, v43, v52, s[38:39]
	v_rsq_f32_e32 v42, v42
	v_rsq_f32_e32 v43, v43
	v_add_u32_e32 v52, 0x110, v65
	s_mov_b32 s34, 0x45800000
	v_lshl_add_u32 v34, v34, 3, 0
	v_add_u32_e32 v70, s4, v52
	v_add_u32_e32 v71, s18, v52
	v_pk_mul_f32 v[52:53], v[42:43], s[34:35] op_sel_hi:[1,0]
	ds_read2st64_b64 v[66:69], v34 offset0:72 offset1:73
	v_cndmask_b32_e64 v43, v43, v53, s[38:39]
	v_cndmask_b32_e64 v42, v42, v52, s[0:1]
	v_pk_mul_f32 v[12:13], v[12:13], v[42:43]
	v_add_u32_e32 v56, s18, v56
	v_bfe_u32 v42, v12, 16, 1
	v_bfe_u32 v34, v13, 16, 1
	v_add3_u32 v42, v12, v42, s11
	v_add3_u32 v34, v13, v34, s11
	ds_write_b16_d16_hi v56, v42
	ds_write_b16_d16_hi v71, v34
	s_waitcnt lgkmcnt(2)
	v_add_f32_e32 v34, v66, v67
	v_add_f32_e32 v34, 0x358637bd, v34
	v_mul_f32_e32 v43, 0x4b800000, v34
	v_cmp_gt_f32_e64 s[0:1], s77, v34
	ds_write_b16_d16_hi v70, v51
	ds_read_b96 v[52:54], v54
	ds_read_b96 v[56:58], v57
	v_cndmask_b32_e64 v34, v34, v43, s[0:1]
	v_rsq_f32_e32 v43, v34
	v_ashrrev_i32_e32 v23, 6, v38
	s_waitcnt lgkmcnt(1)
	v_pk_mul_f32 v[12:13], v[52:53], v[12:13]
	v_mul_f32_e32 v34, v75, v53
	v_mul_f32_e32 v51, 0x45800000, v43
	v_cndmask_b32_e64 v43, v43, v51, s[0:1]
	v_lshl_add_u32 v51, v35, 3, 0
	ds_read2st64_b64 v[70:73], v51 offset0:72 offset1:73
	s_waitcnt lgkmcnt(1)
	v_pk_mul_f32 v[12:13], v[56:57], v[12:13]
	v_mul_f32_e32 v43, 0x3db504f3, v43
	v_mul_f32_e32 v43, v82, v43
	v_bfe_u32 v51, v43, 16, 1
	s_waitcnt lgkmcnt(0)
	v_add_f32_e32 v53, v70, v71
	v_add_f32_e32 v53, 0x358637bd, v53
	v_cmp_gt_f32_e64 s[0:1], s77, v53
	v_add3_u32 v43, v43, v51, s11
	v_add_u32_e32 v51, 0x220, v65
	v_rsq_f32_e32 v53, v53
	v_mul_f32_e32 v42, v74, v52
	v_add_u32_e32 v52, s4, v51
	ds_write_b16_d16_hi v52, v43
	v_mov_b32_e32 v52, v53
	v_mul_f32_e32 v52, 0x3db504f3, v52
	v_mul_f32_e32 v52, v81, v52
	v_bfe_u32 v53, v52, 16, 1
	v_add3_u32 v65, v52, v53, s11
	v_mov_b32_e32 v52, v68
	v_mov_b32_e32 v53, v72
	v_mov_b32_e32 v72, v69
	v_pk_add_f32 v[52:53], v[52:53], v[72:73]
	v_lshlrev_b32_e32 v56, 2, v35
	v_pk_add_f32 v[52:53], v[52:53], s[72:73] op_sel_hi:[1,0]
	v_mul_lo_u32 v35, v35, s12
	v_mul_f32_e32 v66, 0x4b800000, v52
	v_cmp_gt_f32_e64 s[0:1], s77, v52
	v_cmp_gt_f32_e64 s[38:39], s77, v53
	v_add_u32_e32 v51, s18, v51
	v_cndmask_b32_e64 v52, v52, v66, s[0:1]
	v_mul_f32_e32 v66, 0x4b800000, v53
	v_cndmask_b32_e64 v53, v53, v66, s[38:39]
	v_rsq_f32_e32 v52, v52
	v_rsq_f32_e32 v53, v53
	v_add_u32_e32 v57, s25, v56
	v_add_lshl_u32 v35, v35, v19, 1
	v_add_u32_e32 v70, s4, v35
	v_pk_mul_f32 v[66:67], v[52:53], s[34:35] op_sel_hi:[1,0]
	v_add_u32_e32 v56, s13, v56
	v_cndmask_b32_e64 v53, v53, v67, s[38:39]
	v_cndmask_b32_e64 v52, v52, v66, s[0:1]
	v_pk_mul_f32 v[16:17], v[16:17], v[52:53]
	ds_read_b32 v57, v57
	ds_read_b32 v71, v56
	v_bfe_u32 v52, v16, 16, 1
	v_add3_u32 v52, v16, v52, s11
	ds_write_b16_d16_hi v51, v52
	ds_write_b16_d16_hi v70, v65
	v_lshl_add_u32 v52, v33, 3, 0
	ds_read2st64_b64 v[66:69], v52 offset0:72 offset1:73
	v_bfe_u32 v51, v17, 16, 1
	v_add_u32_e32 v35, s18, v35
	v_add3_u32 v51, v17, v51, s11
	ds_write_b16_d16_hi v35, v51
	s_waitcnt lgkmcnt(1)
	v_add_f32_e32 v35, v66, v67
	v_add_f32_e32 v35, 0x358637bd, v35
	v_mul_f32_e32 v51, 0x4b800000, v35
	v_cmp_gt_f32_e64 s[0:1], s77, v35
	v_mov_b32_e32 v56, v54
	v_pk_mul_f32 v[16:17], v[56:57], v[16:17]
	v_cndmask_b32_e64 v35, v35, v51, s[0:1]
	v_rsq_f32_e32 v51, v35
	v_mov_b32_e32 v70, v58
	v_pk_mul_f32 v[16:17], v[70:71], v[16:17]
	v_mul_f32_e32 v43, v76, v54
	v_mul_f32_e32 v52, 0x45800000, v51
	v_cndmask_b32_e64 v51, v51, v52, s[0:1]
	v_mul_f32_e32 v51, 0x3db504f3, v51
	v_lshlrev_b32_e32 v52, 2, v33
	v_add_u32_e32 v53, s25, v52
	v_mul_f32_e32 v51, v80, v51
	ds_read_b32 v56, v53
	v_bfe_u32 v53, v51, 16, 1
	v_add3_u32 v51, v51, v53, s11
	v_lshl_add_u32 v53, v32, 3, 0
	ds_read2st64_b64 v[70:73], v53 offset0:72 offset1:73
	v_mul_lo_u32 v33, v33, s12
	v_add_lshl_u32 v33, v33, v19, 1
	v_add_u32_e32 v53, s4, v33
	ds_write_b16_d16_hi v53, v51
	v_add_u32_e32 v51, s18, v33
	s_waitcnt lgkmcnt(1)
; DI bf16_t f2bf(float f) { unsigned u = __float_as_uint(f); u += 0x7fffu + ((u >> 16) & 1u); return (bf16_t)(u >> 16); }
;     ...
;         float rk_[16], rv_[16];
; #pragma unroll
;         for (int e = 0; e < 16; ++e) { const int tt = tt0 + e;
;             const float rq = rsqrtf(ssq[tt * 2] + ssq[tt * 2 + 1] + NEPS) * 0.08838834764831845f, rk = rsqrtf(ssq[(64 + tt) * 2] + ssq[(64 + tt) * 2 + 1] + NEPS);
;             const float bt = betas[tt];
;             qs[tt * 136 + c] = f2bf(y[0][e] * rq);
;             const float kn = y[1][e] * rk; ks[tt * 136 + c] = f2bf(kn);
;             rk_[e] = kn * bt * egs[tt]; rv_[e] = y[2][e] * bt; }
	v_add_f32_e32 v33, v70, v71
	v_add_f32_e32 v33, 0x358637bd, v33
	v_mul_f32_e32 v53, 0x4b800000, v33
	v_cmp_gt_f32_e64 s[0:1], s77, v33
	v_lshlrev_b32_e32 v54, 2, v32
	v_mul_lo_u32 v32, v32, s12
	v_cndmask_b32_e64 v33, v33, v53, s[0:1]
	v_rsq_f32_e32 v53, v33
	v_add_u32_e32 v33, s13, v52
	v_add_lshl_u32 v32, v32, v19, 1
	ds_read_b32 v66, v33
	v_mul_f32_e32 v52, 0x45800000, v53
	v_cndmask_b32_e64 v52, v53, v52, s[0:1]
	v_mul_f32_e32 v52, 0x3db504f3, v52
	v_mul_f32_e32 v52, v79, v52
	v_bfe_u32 v53, v52, 16, 1
	v_add3_u32 v58, v52, v53, s11
	v_mov_b32_e32 v52, v68
	v_mov_b32_e32 v53, v72
	v_mov_b32_e32 v72, v69
	v_pk_add_f32 v[52:53], v[52:53], v[72:73]
	v_mul_f32_e32 v35, v77, v57
	v_pk_add_f32 v[52:53], v[52:53], s[72:73] op_sel_hi:[1,0]
	v_add_u32_e32 v57, s25, v54
	v_mul_f32_e32 v65, 0x4b800000, v52
	v_cmp_gt_f32_e64 s[0:1], s77, v52
	v_cmp_gt_f32_e64 s[38:39], s77, v53
	v_add_u32_e32 v67, s13, v54
	v_cndmask_b32_e64 v52, v52, v65, s[0:1]
	v_mul_f32_e32 v65, 0x4b800000, v53
	v_cndmask_b32_e64 v53, v53, v65, s[38:39]
	v_rsq_f32_e32 v52, v52
	v_rsq_f32_e32 v53, v53
	v_add_u32_e32 v65, s4, v32
	v_add_u32_e32 v32, s18, v32
	v_mul_f32_e32 v33, v90, v56
	v_pk_mul_f32 v[68:69], v[52:53], s[34:35] op_sel_hi:[1,0]
	v_lshl_add_u32 v70, v27, 3, 0
	v_cndmask_b32_e64 v53, v53, v69, s[38:39]
	v_cndmask_b32_e64 v52, v52, v68, s[0:1]
	v_pk_mul_f32 v[14:15], v[14:15], v[52:53]
	v_lshlrev_b32_e32 v27, 2, v27
	v_bfe_u32 v52, v14, 16, 1
	v_add3_u32 v52, v14, v52, s11
	ds_write_b16_d16_hi v51, v52
	ds_write_b16_d16_hi v65, v58
	v_lshl_add_u32 v52, v31, 3, 0
	ds_read_b64 v[68:69], v52 offset:36864
	v_bfe_u32 v51, v15, 16, 1
	v_add3_u32 v51, v15, v51, s11
	ds_write_b16_d16_hi v32, v51
	ds_read_b32 v57, v57
	ds_read_b96 v[52:54], v52 offset:37376
	ds_read_b32 v67, v67
	s_waitcnt lgkmcnt(4)
	v_add_f32_e32 v32, v68, v69
	v_add_f32_e32 v32, 0x358637bd, v32
	v_mul_f32_e32 v51, 0x4b800000, v32
	v_cmp_gt_f32_e64 s[0:1], s77, v32
	s_waitcnt lgkmcnt(2)
	v_pk_mul_f32 v[14:15], v[56:57], v[14:15]
	ds_read_b64 v[70:71], v70 offset:37376
	v_cndmask_b32_e64 v32, v32, v51, s[0:1]
	v_rsq_f32_e32 v51, v32
	s_waitcnt lgkmcnt(1)
	v_pk_mul_f32 v[14:15], v[66:67], v[14:15]
	v_mul_f32_e32 v32, v91, v57
	v_mov_b32_e32 v57, v54
	v_mul_f32_e32 v56, 0x45800000, v51
	v_cndmask_b32_e64 v51, v51, v56, s[0:1]
	v_mul_f32_e32 v51, 0x3db504f3, v51
	v_mul_f32_e32 v51, v78, v51
	v_bfe_u32 v58, v51, 16, 1
	v_add3_u32 v51, v51, v58, s11
	v_lshl_add_u32 v58, v29, 3, 0
	v_add_u32_e32 v65, 0x9000, v58
	ds_read2_b64 v[66:69], v65 offset1:1
	v_mov_b32_e32 v56, v53
	v_lshlrev_b32_e32 v53, 2, v31
	v_mul_lo_u32 v31, v31, s12
	v_add_lshl_u32 v31, v31, v19, 1
	s_waitcnt lgkmcnt(0)
	v_add_f32_e32 v66, v66, v67
	v_add_f32_e32 v66, 0x358637bd, v66
	v_cmp_gt_f32_e64 s[0:1], s77, v66
	v_add_u32_e32 v65, s4, v31
	v_add_u32_e32 v54, s25, v53
	v_rsq_f32_e32 v66, v66
	ds_write_b16_d16_hi v65, v51
	v_add_u32_e32 v51, s13, v53
	v_add_u32_e32 v31, s18, v31
	v_mov_b32_e32 v53, v66
	v_mul_f32_e32 v65, 0x3db504f3, v53
	ds_read_b32 v53, v58 offset:37380
	v_mul_f32_e32 v58, v64, v65
	v_bfe_u32 v64, v58, 16, 1
	v_add3_u32 v58, v58, v64, s11
	ds_read_b64 v[64:65], v54
	ds_read_b64 v[66:67], v51
	s_waitcnt lgkmcnt(2)
	v_pk_add_f32 v[52:53], v[56:57], v[52:53]
	v_mul_lo_u32 v29, v29, s12
	v_pk_add_f32 v[52:53], v[52:53], s[72:73] op_sel_hi:[1,0]
	v_add_lshl_u32 v29, v29, v19, 1
	v_mul_f32_e32 v51, 0x4b800000, v52
	v_cmp_gt_f32_e64 s[0:1], s77, v52
	v_cmp_gt_f32_e64 s[38:39], s77, v53
	v_add_u32_e32 v54, s18, v29
	v_cndmask_b32_e64 v51, v52, v51, s[0:1]
	v_rsq_f32_e32 v52, v51
	v_mul_f32_e32 v51, 0x4b800000, v53
	v_cndmask_b32_e64 v51, v53, v51, s[38:39]
	v_rsq_f32_e32 v53, v51
	s_waitcnt lgkmcnt(1)
	v_mul_f32_e32 v72, v49, v64
	v_add_u32_e32 v51, s4, v29
	v_add_u32_e32 v29, 0x110, v29
	v_pk_mul_f32 v[56:57], v[52:53], s[34:35] op_sel_hi:[1,0]
	s_nop 0
	v_cndmask_b32_e64 v53, v53, v57, s[38:39]
	v_cndmask_b32_e64 v52, v52, v56, s[0:1]
	v_pk_mul_f32 v[8:9], v[8:9], v[52:53]
	s_nop 0
	v_bfe_u32 v52, v8, 16, 1
	v_add3_u32 v52, v8, v52, s11
	ds_write_b16_d16_hi v31, v52
	v_bfe_u32 v31, v9, 16, 1
	v_add3_u32 v31, v9, v31, s11
	ds_write_b16_d16_hi v54, v31
	v_add_f32_e32 v31, v68, v69
	v_add_f32_e32 v31, 0x358637bd, v31
	v_cmp_gt_f32_e64 s[0:1], s77, v31
	v_mul_f32_e32 v54, v48, v65
	v_pk_mul_f32 v[8:9], v[64:65], v[8:9]
	v_rsq_f32_e32 v31, v31
	s_waitcnt lgkmcnt(2)
	v_pk_mul_f32 v[8:9], v[66:67], v[8:9]
	ds_write_b16_d16_hi v51, v58
	v_mul_f32_e32 v31, 0x3db504f3, v31
	v_add_u32_e32 v48, s25, v27
	v_mul_f32_e32 v31, v63, v31
	v_add_u32_e32 v27, s13, v27
	ds_read_b32 v52, v48
	ds_read_b32 v56, v27
	v_bfe_u32 v48, v31, 16, 1
	v_add3_u32 v31, v31, v48, s11
	v_lshl_add_u32 v48, v30, 3, 0
	ds_read2st64_b64 v[64:67], v48 offset0:72 offset1:73
	v_add_u32_e32 v48, s4, v29
	ds_write_b16_d16_hi v48, v31
	s_waitcnt lgkmcnt(3)
	v_mul_f32_e32 v58, v50, v52
	v_add_u32_e32 v29, s18, v29
	s_waitcnt lgkmcnt(1)
; DI bf16_t f2bf(float f) { unsigned u = __float_as_uint(f); u += 0x7fffu + ((u >> 16) & 1u); return (bf16_t)(u >> 16); }
;     ...
;         float rk_[16], rv_[16];
; #pragma unroll
;         for (int e = 0; e < 16; ++e) { const int tt = tt0 + e;
;             const float rq = rsqrtf(ssq[tt * 2] + ssq[tt * 2 + 1] + NEPS) * 0.08838834764831845f, rk = rsqrtf(ssq[(64 + tt) * 2] + ssq[(64 + tt) * 2 + 1] + NEPS);
;             const float bt = betas[tt];
;             qs[tt * 136 + c] = f2bf(y[0][e] * rq);
;             const float kn = y[1][e] * rk; ks[tt * 136 + c] = f2bf(kn);
;             rk_[e] = kn * bt * egs[tt]; rv_[e] = y[2][e] * bt; }
	v_add_f32_e32 v31, v64, v65
	v_add_f32_e32 v31, 0x358637bd, v31
	v_cmp_gt_f32_e64 s[0:1], s77, v31
	s_nop 1
	v_rsq_f32_e32 v31, v31
	v_lshlrev_b32_e32 v48, 2, v30
	v_mul_lo_u32 v30, v30, s12
	v_add_lshl_u32 v30, v30, v19, 1
	v_mov_b32_e32 v27, v31
	v_mul_f32_e32 v27, 0x3db504f3, v27
	v_mul_f32_e32 v27, v62, v27
	v_bfe_u32 v31, v27, 16, 1
	v_add3_u32 v27, v27, v31, s11
	v_add_u32_e32 v62, s4, v30
	v_add_u32_e32 v63, s18, v30
	v_mov_b32_e32 v30, v70
	v_mov_b32_e32 v31, v66
	v_mov_b32_e32 v66, v71
	v_pk_add_f32 v[30:31], v[30:31], v[66:67]
	v_add_u32_e32 v49, s25, v48
	v_pk_add_f32 v[30:31], v[30:31], s[72:73] op_sel_hi:[1,0]
	v_add_u32_e32 v48, s13, v48
	v_mul_f32_e32 v50, 0x4b800000, v30
	v_cmp_gt_f32_e64 s[0:1], s77, v30
	v_cmp_gt_f32_e64 s[38:39], s77, v31
	ds_read_b32 v53, v49
	ds_read_b32 v57, v48
	v_cndmask_b32_e64 v30, v30, v50, s[0:1]
	v_mul_f32_e32 v50, 0x4b800000, v31
	v_cndmask_b32_e64 v31, v31, v50, s[38:39]
	v_rsq_f32_e32 v30, v30
	v_rsq_f32_e32 v31, v31
	s_nop 0
	v_pk_mul_f32 v[48:49], v[30:31], s[34:35] op_sel_hi:[1,0]
	s_nop 0
	v_cndmask_b32_e64 v31, v31, v49, s[38:39]
	v_cndmask_b32_e64 v30, v30, v48, s[0:1]
	v_pk_mul_f32 v[10:11], v[10:11], v[30:31]
	s_nop 0
	v_bfe_u32 v30, v10, 16, 1
	v_add3_u32 v30, v10, v30, s11
	ds_write_b16_d16_hi v29, v30
	v_lshl_add_u32 v29, v28, 3, 0
	ds_read2st64_b64 v[48:51], v29 offset0:72 offset1:73
	ds_write_b16_d16_hi v62, v27
	v_bfe_u32 v27, v11, 16, 1
	v_add3_u32 v27, v11, v27, s11
	ds_write_b16_d16_hi v63, v27
	s_waitcnt lgkmcnt(2)
	v_add_f32_e32 v27, v48, v49
	v_add_f32_e32 v27, 0x358637bd, v27
	v_cmp_gt_f32_e64 s[0:1], s77, v27
	v_pk_mul_f32 v[10:11], v[52:53], v[10:11]
	v_mul_lo_u32 v49, v28, s12
	v_rsq_f32_e32 v27, v27
	v_pk_mul_f32 v[10:11], v[56:57], v[10:11]
	v_mul_f32_e32 v56, v47, v53
	v_lshlrev_b32_e32 v47, 2, v28
	v_mul_f32_e32 v27, 0x3db504f3, v27
	v_add_u32_e32 v29, s25, v47
	v_mul_f32_e32 v27, v61, v27
	ds_read_b32 v48, v29
	v_bfe_u32 v29, v27, 16, 1
	v_lshl_add_u32 v28, v26, 3, 0
	v_add3_u32 v27, v27, v29, s11
	ds_read2st64_b64 v[28:31], v28 offset0:72 offset1:73
	v_add_lshl_u32 v49, v49, v19, 1
	v_add_u32_e32 v52, s4, v49
	ds_write_b16_d16_hi v52, v27
	s_waitcnt lgkmcnt(2)
	v_mul_f32_e32 v61, v46, v48
	s_waitcnt lgkmcnt(1)
	v_add_f32_e32 v27, v28, v29
	v_add_f32_e32 v27, 0x358637bd, v27
	v_cmp_gt_f32_e64 s[0:1], s77, v27
	v_add_u32_e32 v57, s18, v49
	v_cvt_pk_bf16_f32 v10, v10, v11
	v_rsq_f32_e32 v27, v27
	v_add_u32_e32 v28, s13, v47
	ds_read_b32 v52, v28
	v_mul_f32_e32 v27, 0x3db504f3, v27
	v_lshlrev_b32_e32 v28, 2, v26
	v_mul_f32_e32 v27, v60, v27
	v_mul_lo_u32 v26, v26, s12
	v_bfe_u32 v46, v27, 16, 1
	v_add_lshl_u32 v26, v26, v19, 1
	v_add3_u32 v46, v27, v46, s11
	v_add_u32_e32 v47, s4, v26
	v_add_u32_e32 v60, s18, v26
	v_mov_b32_e32 v26, v50
	v_mov_b32_e32 v27, v30
	v_mov_b32_e32 v30, v51
	v_pk_add_f32 v[26:27], v[26:27], v[30:31]
	v_add_u32_e32 v29, s25, v28
	v_pk_add_f32 v[26:27], v[26:27], s[72:73] op_sel_hi:[1,0]
	v_add_u32_e32 v28, s13, v28
	v_mul_f32_e32 v30, 0x4b800000, v26
	v_cmp_gt_f32_e64 s[0:1], s77, v26
	v_cmp_gt_f32_e64 s[38:39], s77, v27
	ds_read_b32 v49, v29
	ds_read_b32 v53, v28
	v_cndmask_b32_e64 v26, v26, v30, s[0:1]
	v_mul_f32_e32 v30, 0x4b800000, v27
	v_cndmask_b32_e64 v27, v27, v30, s[38:39]
	v_rsq_f32_e32 v26, v26
	v_rsq_f32_e32 v27, v27
	s_waitcnt lgkmcnt(1)
	v_mul_f32_e32 v45, v45, v49
	v_pk_mul_f32 v[28:29], v[26:27], s[34:35] op_sel_hi:[1,0]
	s_nop 0
	v_cndmask_b32_e64 v27, v27, v29, s[38:39]
	v_cndmask_b32_e64 v26, v26, v28, s[0:1]
	v_pk_mul_f32 v[6:7], v[6:7], v[26:27]
	s_nop 0
	v_bfe_u32 v26, v6, 16, 1
	v_add3_u32 v26, v6, v26, s11
	ds_write_b16_d16_hi v57, v26
	v_lshl_add_u32 v26, v25, 3, 0
	ds_read2st64_b64 v[26:29], v26 offset0:72 offset1:73
	v_bfe_u32 v30, v7, 16, 1
	v_add3_u32 v30, v7, v30, s11
	v_pk_mul_f32 v[6:7], v[48:49], v[6:7]
	ds_write_b16_d16_hi v60, v30
	s_waitcnt lgkmcnt(1)
	v_add_f32_e32 v26, v26, v27
	v_add_f32_e32 v26, 0x358637bd, v26
	v_cmp_gt_f32_e64 s[0:1], s77, v26
	v_pk_mul_f32 v[30:31], v[52:53], v[6:7]
	ds_write_b16_d16_hi v47, v46
	v_rsq_f32_e32 v26, v26
	v_lshlrev_b32_e32 v7, 2, v25
	v_mul_lo_u32 v25, v25, s12
	v_add_lshl_u32 v25, v25, v19, 1
	v_mov_b32_e32 v6, v26
	v_mul_f32_e32 v6, 0x3db504f3, v6
	v_mul_f32_e32 v6, v59, v6
	v_bfe_u32 v27, v6, 16, 1
	v_add3_u32 v6, v6, v27, s11
	v_lshl_add_u32 v27, v24, 3, 0
	ds_read2st64_b64 v[46:49], v27 offset0:72 offset1:73
	v_add_u32_e32 v27, s4, v25
	ds_write_b16_d16_hi v27, v6
	v_add_u32_e32 v50, s18, v25
	v_add_u32_e32 v26, s25, v7
	s_waitcnt lgkmcnt(1)
	v_add_f32_e32 v6, v46, v47
	v_add_f32_e32 v6, 0x358637bd, v6
	v_cmp_gt_f32_e64 s[0:1], s77, v6
	v_add_u32_e32 v7, s13, v7
	ds_read_b32 v26, v26
	ds_read_b32 v46, v7
	v_rsq_f32_e32 v6, v6
	v_lshlrev_b32_e32 v25, 2, v24
	v_add_u32_e32 v27, s25, v25
	s_waitcnt lgkmcnt(1)
	v_mul_f32_e32 v44, v44, v26
	v_mul_f32_e32 v6, 0x3db504f3, v6
	v_mul_f32_e32 v6, v55, v6
	v_bfe_u32 v7, v6, 16, 1
	v_add3_u32 v51, v6, v7, s11
	v_mul_lo_u32 v6, v24, s12
	v_add_lshl_u32 v6, v6, v19, 1
	v_add_u32_e32 v52, s4, v6
	v_add_u32_e32 v53, s18, v6
	v_mov_b32_e32 v6, v28
	v_mov_b32_e32 v7, v48
	v_mov_b32_e32 v48, v29
	v_pk_add_f32 v[6:7], v[6:7], v[48:49]
	v_cvt_pk_bf16_f32 v11, v30, v31
	v_pk_add_f32 v[6:7], v[6:7], s[72:73] op_sel_hi:[1,0]
	s_nop 0
	v_mul_f32_e32 v24, 0x4b800000, v6
	v_cmp_gt_f32_e64 s[0:1], s77, v6
	v_cmp_gt_f32_e64 s[38:39], s77, v7
	s_nop 0
	v_cndmask_b32_e64 v6, v6, v24, s[0:1]
	v_mul_f32_e32 v24, 0x4b800000, v7
	v_cndmask_b32_e64 v7, v7, v24, s[38:39]
	v_rsq_f32_e32 v6, v6
	v_rsq_f32_e32 v7, v7
	v_add_u32_e32 v24, s13, v25
	ds_read_b32 v27, v27
	ds_read_b32 v47, v24
	v_pk_mul_f32 v[24:25], v[6:7], s[34:35] op_sel_hi:[1,0]
	s_nop 0
	v_cndmask_b32_e64 v7, v7, v25, s[38:39]
	v_cndmask_b32_e64 v6, v6, v24, s[0:1]
	v_pk_mul_f32 v[24:25], v[4:5], v[6:7]
	s_waitcnt lgkmcnt(1)
; DI bf16_t f2bf(float f) { unsigned u = __float_as_uint(f); u += 0x7fffu + ((u >> 16) & 1u); return (bf16_t)(u >> 16); }
; DI unsigned pk2(float lo, float hi) { const f32x2 v = {lo, hi}; return __builtin_bit_cast(unsigned, __builtin_convertvector(v, bf16v2_t)); }
; DI int crow(int i, int h) { return (i & 3) + 8 * (i >> 2) + 4 * h; }
; #define MFMA32(a, b, c) __builtin_amdgcn_mfma_f32_32x32x16_bf16((a), (b), (c), 0, 0, 0)
;     ...
;         for (int e = 0; e < 16; ++e) { const int tt = tt0 + e;
;             const float rq = rsqrtf(ssq[tt * 2] + ssq[tt * 2 + 1] + NEPS) * 0.08838834764831845f, rk = rsqrtf(ssq[(64 + tt) * 2] + ssq[(64 + tt) * 2 + 1] + NEPS);
;             const float bt = betas[tt];
;             qs[tt * 136 + c] = f2bf(y[0][e] * rq);
;             const float kn = y[1][e] * rk; ks[tt * 136 + c] = f2bf(kn);
;             rk_[e] = kn * bt * egs[tt]; rv_[e] = y[2][e] * bt; }
;         u32x4 o0, o1;
; #pragma unroll
;         for (int e = 0; e < 4; ++e) { o0[e] = pk2(rk_[2 * e], rk_[2 * e + 1]); o1[e] = pk2(rk_[8 + 2 * e], rk_[8 + 2 * e + 1]); }
;         *(u32x4*)(RT + (128 + c) * 72 + tt0) = o0; *(u32x4*)(RT + (128 + c) * 72 + tt0 + 8) = o1;
; #pragma unroll
;         for (int e = 0; e < 4; ++e) { o0[e] = pk2(rv_[2 * e], rv_[2 * e + 1]); o1[e] = pk2(rv_[8 + 2 * e], rv_[8 + 2 * e + 1]); }
;         *(u32x4*)(RT + c * 72 + tt0) = o0; *(u32x4*)(RT + c * 72 + tt0 + 8) = o1;
;     ...
;     {
;         const int r = lane & 31, h2 = lane >> 5, w4 = wv & 3, ib = w4 >> 1, jb = w4 & 1;
;         const bf16_t* Am = (wv < 4) ? ks : qs;
;         f32x16 acc; for (int i = 0; i < 16; ++i) acc[i] = 0.f;
; #pragma unroll
;         for (int s = 0; s < 8; ++s) { const bf16x8 av = *(const bf16x8*)(Am + (32 * ib + r) * 136 + 16 * s + 8 * h2), bv = *(const bf16x8*)(ks + (32 * jb + r) * 136 + 16 * s + 8 * h2);
;             acc = MFMA32(av, bv, acc); }
;         const int j = 32 * jb + r; const float gj = gcs[j];
;         bf16_t* aq = a.aqk + (size_t)item * 4096;
; #pragma unroll
;         for (int i2 = 0; i2 < 16; ++i2) { const int i = 32 * ib + crow(i2, h2); const float gi = gcs[i];
;             if (wv < 4) { Lm[i * 68 + j] = (j < i) ? betas[i] * acc[i2] * __expf(gi - gj) : 0.f; }
;             else { aq[i * 64 + j] = f2bf((j <= i) ? acc[i2] * __expf(gi - gj) : 0.f); } }
	v_mul_f32_e32 v40, v40, v27
	v_bfe_u32 v4, v24, 16, 1
	v_add3_u32 v4, v24, v4, s11
	ds_write_b16_d16_hi v50, v4
	v_lshl_add_u32 v4, v22, 3, 0
	ds_read2st64_b64 v[4:7], v4 offset0:72 offset1:73
	v_bfe_u32 v28, v25, 16, 1
	v_add3_u32 v28, v25, v28, s11
	ds_write_b16_d16_hi v53, v28
	ds_write_b16_d16_hi v52, v51
	s_waitcnt lgkmcnt(2)
	v_add_f32_e32 v4, v4, v5
	v_add_f32_e32 v4, 0x358637bd, v4
	v_mul_f32_e32 v5, 0x4b800000, v4
	v_cmp_gt_f32_e64 s[0:1], s77, v4
	s_nop 1
	v_cndmask_b32_e64 v4, v4, v5, s[0:1]
	v_rsq_f32_e32 v48, v4
	v_pk_mul_f32 v[4:5], v[26:27], v[24:25]
	s_nop 0
	v_pk_mul_f32 v[28:29], v[46:47], v[4:5]
	v_mul_f32_e32 v4, 0x45800000, v48
	v_cndmask_b32_e64 v4, v48, v4, s[0:1]
	v_mul_f32_e32 v5, 0x3db504f3, v4
	v_mul_f32_e32 v5, v37, v5
	v_bfe_u32 v24, v5, 16, 1
	v_add3_u32 v5, v5, v24, s11
	v_lshl_add_u32 v24, v21, 3, 0
	ds_read2st64_b64 v[24:27], v24 offset0:72 offset1:73
	v_lshlrev_b32_e32 v46, 2, v22
	v_mul_lo_u32 v22, v22, s12
	v_add_lshl_u32 v22, v22, v19, 1
	v_add_u32_e32 v37, s4, v22
	ds_write_b16_d16_hi v37, v5
	s_waitcnt lgkmcnt(1)
	v_add_f32_e32 v5, v24, v25
	v_add_f32_e32 v5, 0x358637bd, v5
	v_cmp_gt_f32_e64 s[0:1], s77, v5
	v_mov_b32_e32 v37, v26
	v_mov_b32_e32 v26, v7
	v_rsq_f32_e32 v5, v5
	v_add_u32_e32 v4, s25, v46
	ds_read_b32 v4, v4
	v_add_u32_e32 v24, s13, v46
	v_mul_f32_e32 v5, 0x3db504f3, v5
	v_mul_f32_e32 v5, v36, v5
	v_bfe_u32 v36, v5, 16, 1
	v_add3_u32 v47, v5, v36, s11
	v_mov_b32_e32 v36, v6
	v_mul_lo_u32 v5, v21, s12
	v_pk_add_f32 v[6:7], v[36:37], v[26:27]
	v_add_lshl_u32 v5, v5, v19, 1
	v_pk_add_f32 v[6:7], v[6:7], s[72:73] op_sel_hi:[1,0]
	v_lshlrev_b32_e32 v25, 2, v21
	v_add_u32_e32 v21, s4, v5
	v_add_u32_e32 v48, s18, v5
	v_mul_f32_e32 v5, 0x4b800000, v6
	v_cmp_gt_f32_e64 s[0:1], s77, v6
	v_cmp_gt_f32_e64 s[38:39], s77, v7
	v_add_u32_e32 v46, s25, v25
	v_cndmask_b32_e64 v5, v6, v5, s[0:1]
	v_rsq_f32_e32 v6, v5
	v_mul_f32_e32 v5, 0x4b800000, v7
	v_cndmask_b32_e64 v5, v7, v5, s[38:39]
	v_rsq_f32_e32 v7, v5
	v_add_u32_e32 v25, s13, v25
	ds_read_b32 v24, v24
	ds_read_b32 v5, v46
	ds_read_b32 v25, v25
	v_pk_mul_f32 v[26:27], v[6:7], s[34:35] op_sel_hi:[1,0]
	v_add_u32_e32 v22, s18, v22
	v_cndmask_b32_e64 v7, v7, v27, s[38:39]
	v_cndmask_b32_e64 v6, v6, v26, s[0:1]
	v_pk_mul_f32 v[2:3], v[2:3], v[6:7]
	s_waitcnt lgkmcnt(3)
	v_mul_f32_e32 v41, v41, v4
	v_bfe_u32 v6, v2, 16, 1
	v_add3_u32 v6, v2, v6, s11
	ds_write_b16_d16_hi v22, v6
	ds_write_b16_d16_hi v21, v47
	v_bfe_u32 v6, v3, 16, 1
	v_add3_u32 v6, v3, v6, s11
	s_waitcnt lgkmcnt(3)
	v_pk_mul_f32 v[2:3], v[4:5], v[2:3]
	ds_write_b16_d16_hi v48, v6
	s_waitcnt lgkmcnt(3)
	v_pk_mul_f32 v[6:7], v[24:25], v[2:3]
	v_cvt_pk_bf16_f32 v2, v12, v13
	v_cvt_pk_bf16_f32 v13, v6, v7
	v_mul_u32_u24_e32 v6, 0x90, v19
	v_lshlrev_b32_e32 v7, 1, v20
	v_mul_f32_e32 v0, v0, v5
	v_cvt_pk_bf16_f32 v3, v16, v17
	v_cvt_pk_bf16_f32 v4, v14, v15
	v_cvt_pk_bf16_f32 v5, v8, v9
	v_add3_u32 v14, 0, v6, v7
	v_cvt_pk_bf16_f32 v12, v28, v29
	ds_write_b128 v14, v[2:5] offset:18432
	ds_write_b128 v14, v[10:13] offset:18448
	v_cvt_pk_bf16_f32 v2, v42, v34
	v_cvt_pk_bf16_f32 v3, v43, v35
	v_cvt_pk_bf16_f32 v4, v33, v32
	v_cvt_pk_bf16_f32 v5, v72, v54
	v_cvt_pk_bf16_f32 v6, v58, v56
	v_cvt_pk_bf16_f32 v7, v61, v45
	v_cvt_pk_bf16_f32 v8, v44, v40
	v_cvt_pk_bf16_f32 v9, v41, v0
	ds_write_b128 v14, v[2:5]
	ds_write_b128 v14, v[6:9] offset:16
	v_mov_b32_e32 v0, s4
	v_mov_b32_e32 v2, s18
	v_cmp_gt_i32_e64 s[38:39], 4, v23
	v_and_b32_e32 v19, 31, v38
	v_lshrrev_b32_e32 v34, 5, v18
	v_cndmask_b32_e64 v0, v0, v2, s[38:39]
	v_lshlrev_b32_e32 v2, 4, v23
	v_and_b32_e32 v21, 32, v2
	v_or_b32_e32 v2, v21, v19
	v_mul_u32_u24_e32 v2, 0x110, v2
	v_lshlrev_b32_e32 v6, 4, v34
	v_add3_u32 v20, v0, v2, v6
	s_waitcnt lgkmcnt(0)
	s_barrier
	ds_read_b128 v[2:5], v20
	v_lshl_or_b32 v0, v85, 5, v19
	v_mul_u32_u24_e32 v7, 0x110, v0
	v_add3_u32 v22, s18, v7, v6
	ds_read_b128 v[6:9], v22
	ds_read_b128 v[24:27], v20 offset:32
	ds_read_b128 v[28:31], v22 offset:32
	s_waitcnt lgkmcnt(2)
	v_mfma_f32_32x32x16_bf16 v[2:17], v[2:5], v[6:9], 0
	s_add_i32 s13, 0, 0x25480
	s_ashr_i32 s25, s24, 31
	s_lshl_b64 s[42:43], s[24:25], 13
	v_readlane_b32 s12, v251, 43
	s_add_u32 s44, s12, s42
	v_readlane_b32 s12, v251, 44
	v_cmp_lt_i32_e64 s[0:1], 3, v23
	s_waitcnt lgkmcnt(0)
	v_mfma_f32_32x32x16_bf16 v[2:17], v[24:27], v[28:31], v[2:17]
	ds_read_b128 v[24:27], v20 offset:64
	ds_read_b128 v[28:31], v22 offset:64
	ds_read_b128 v[40:43], v20 offset:96
	ds_read_b128 v[44:47], v22 offset:96
	s_addc_u32 s45, s12, s43
	s_waitcnt lgkmcnt(2)
	v_mfma_f32_32x32x16_bf16 v[2:17], v[24:27], v[28:31], v[2:17]
	s_waitcnt lgkmcnt(0)
	v_mfma_f32_32x32x16_bf16 v[2:17], v[40:43], v[44:47], v[2:17]
	ds_read_b128 v[24:27], v20 offset:128
	ds_read_b128 v[28:31], v22 offset:128
	ds_read_b128 v[40:43], v20 offset:160
	ds_read_b128 v[44:47], v22 offset:160
	s_waitcnt lgkmcnt(2)
	v_mfma_f32_32x32x16_bf16 v[2:17], v[24:27], v[28:31], v[2:17]
	s_waitcnt lgkmcnt(0)
	v_mfma_f32_32x32x16_bf16 v[2:17], v[40:43], v[44:47], v[2:17]
	ds_read_b128 v[24:27], v20 offset:192
	ds_read_b128 v[28:31], v22 offset:192
	ds_read_b128 v[40:43], v20 offset:224
	ds_read_b128 v[44:47], v22 offset:224
	v_lshlrev_b32_e32 v20, 2, v0
	v_add_u32_e32 v22, s13, v20
	s_waitcnt lgkmcnt(2)
	v_mfma_f32_32x32x16_bf16 v[2:17], v[24:27], v[28:31], v[2:17]
	v_lshl_or_b32 v26, v34, 2, v21
	v_lshl_add_u32 v21, v26, 2, s13
	ds_read_b32 v22, v22
	ds_read_b32 v21, v21
	v_lshlrev_b32_e32 v25, 1, v0
	s_waitcnt lgkmcnt(2)
	v_mfma_f32_32x32x16_bf16 v[2:17], v[40:43], v[44:47], v[2:17]
	s_and_saveexec_b64 s[34:35], s[0:1]
	s_xor_b64 s[46:47], exec, s[34:35]
	s_cbranch_execz .LBB0_410
	s_waitcnt lgkmcnt(0)
	v_sub_f32_e32 v21, v21, v22
	v_mul_f32_e32 v21, 0x3fb8aa3b, v21
	v_exp_f32_e32 v21, v21
	v_cmp_le_u32_e64 s[40:41], v0, v26
	s_nop 3
	v_mul_f32_e32 v21, v2, v21
	v_cndmask_b32_e64 v21, 0, v21, s[40:41]
	v_bfe_u32 v24, v21, 16, 1
	v_add3_u32 v21, v21, v24, s11
	v_lshl_or_b32 v24, v26, 7, v25
	global_store_short_d16_hi v24, v21, s[44:45]
